# chunk_local forward substitution with packed f32 FMAs over column pairs (two f32 partial sums per row; addition order inside a row changes, products and width unchanged)
# speedup vs baseline: 1.0013x; 1.0013x over previous
.LBB0_643:
	v_add_u32_e32 v72, s3, v221
	ds_read_b128 v[66:69], v72
	v_add_co_u32_e32 v70, vcc, 0xffff5000, v64
	s_addk_i32 s3, 0x800
	s_nop 0
	v_addc_co_u32_e32 v71, vcc, -1, v65, vcc
	s_waitcnt lgkmcnt(0)
	global_store_dwordx4 v[70:71], v[66:69], off
	ds_read_b128 v[66:69], v72 offset:1024
	s_cmpk_lg_i32 s3, 0x2000
	s_waitcnt lgkmcnt(0)
	global_store_dwordx4 v[64:65], v[66:69], off
	v_lshl_add_u64 v[64:65], v[64:65], 0, s[72:73]
	s_cbranch_scc1 .LBB0_643
	v_mfma_f32_16x16x32_bf16 v[72:75], v[60:63], v[60:63], 0
	ds_read_b128 v[64:67], v148 offset:17408
	ds_read_b128 v[68:71], v148 offset:17664
	s_mov_b32 s3, 0
	s_waitcnt lgkmcnt(1)
	v_sub_f32_e32 v64, v64, v146
	v_mfma_f32_16x16x32_bf16 v[72:75], v[56:59], v[56:59], v[72:75]
	v_mul_f32_e32 v64, 0x3fb8aa3b, v64
	v_exp_f32_e32 v64, v64
	v_sub_f32_e32 v65, v65, v146
	v_mfma_f32_16x16x32_bf16 v[72:75], v[52:55], v[52:55], v[72:75]
	v_mul_f32_e32 v65, 0x3fb8aa3b, v65
	v_sub_f32_e32 v66, v66, v146
	v_exp_f32_e32 v65, v65
	v_mfma_f32_16x16x32_bf16 v[72:75], v[48:51], v[48:51], v[72:75]
	v_mul_f32_e32 v66, 0x3fb8aa3b, v66
	v_exp_f32_e32 v66, v66
	s_waitcnt lgkmcnt(0)
	s_nop 4
	v_mul_f32_e32 v68, v68, v72
	v_mul_f32_e32 v64, v64, v68
	v_cndmask_b32_e64 v64, 0, v64, s[30:31]
	ds_write_b32 v241, v64
	v_mul_f32_e32 v64, v69, v73
	v_mul_f32_e32 v64, v65, v64
	v_mul_f32_e32 v65, v70, v74
	v_mul_f32_e32 v65, v66, v65
	v_cndmask_b32_e64 v64, v64, 0, s[4:5]
	v_cndmask_b32_e64 v65, 0, v65, s[34:35]
	ds_write2_b32 v242, v64, v65 offset1:68
	v_sub_f32_e32 v65, v67, v146
	v_mul_f32_e32 v65, 0x3fb8aa3b, v65
	v_mul_f32_e32 v64, v71, v75
	v_exp_f32_e32 v65, v65
	v_mfma_f32_16x16x32_bf16 v[72:75], v[44:47], v[60:63], 0
	v_mul_f32_e32 v64, v65, v64
	v_mfma_f32_16x16x32_bf16 v[72:75], v[40:43], v[56:59], v[72:75]
	v_cndmask_b32_e64 v64, 0, v64, s[36:37]
	ds_write_b32 v242, v64 offset:544
	ds_read_b128 v[64:67], v148 offset:17472
	ds_read_b128 v[68:71], v148 offset:17728
	v_mfma_f32_16x16x32_bf16 v[72:75], v[32:35], v[52:55], v[72:75]
	s_waitcnt lgkmcnt(1)
	v_sub_f32_e32 v76, v64, v146
	v_mfma_f32_16x16x32_bf16 v[72:75], v[36:39], v[48:51], v[72:75]
	v_mul_f32_e32 v76, 0x3fb8aa3b, v76
	v_exp_f32_e32 v76, v76
	v_sub_f32_e32 v64, v64, v147
	v_mul_f32_e32 v64, 0x3fb8aa3b, v64
	v_exp_f32_e32 v64, v64
	s_waitcnt lgkmcnt(0)
	s_nop 1
	v_mul_f32_e32 v72, v68, v72
	v_mul_f32_e32 v76, v76, v72
	v_mul_f32_e32 v72, v69, v73
	v_sub_f32_e32 v73, v65, v146
	v_mul_f32_e32 v73, 0x3fb8aa3b, v73
	v_exp_f32_e32 v73, v73
	v_sub_f32_e32 v65, v65, v147
	v_mul_f32_e32 v65, 0x3fb8aa3b, v65
	v_exp_f32_e32 v65, v65
	v_mul_f32_e32 v77, v73, v72
	v_sub_f32_e32 v73, v66, v146
	v_mul_f32_e32 v73, 0x3fb8aa3b, v73
	v_exp_f32_e32 v73, v73
	v_mul_f32_e32 v72, v70, v74
	v_sub_f32_e32 v66, v66, v147
	v_mul_f32_e32 v66, 0x3fb8aa3b, v66
	v_mul_f32_e32 v78, v73, v72
	v_sub_f32_e32 v73, v67, v146
	v_mul_f32_e32 v73, 0x3fb8aa3b, v73
	v_exp_f32_e32 v73, v73
	v_mul_f32_e32 v72, v71, v75
	v_exp_f32_e32 v66, v66
	v_mul_f32_e32 v79, v73, v72
	v_mfma_f32_16x16x32_bf16 v[72:75], v[44:47], v[44:47], 0
	v_mfma_f32_16x16x32_bf16 v[72:75], v[40:43], v[40:43], v[72:75]
	v_mfma_f32_16x16x32_bf16 v[72:75], v[32:35], v[32:35], v[72:75]
	v_mfma_f32_16x16x32_bf16 v[72:75], v[36:39], v[36:39], v[72:75]
	s_nop 7
	v_mul_f32_e32 v68, v68, v72
	v_mul_f32_e32 v64, v64, v68
	v_cndmask_b32_e64 v64, 0, v64, s[30:31]
	v_add_u32_e32 v68, 0xe00, v242
	ds_write2_b32 v68, v76, v64 offset0:124 offset1:140
	v_mul_f32_e32 v64, v69, v73
	v_mul_f32_e32 v64, v65, v64
	v_cndmask_b32_e64 v64, 0, v64, s[38:39]
	v_add_u32_e32 v65, 0x1000, v242
	ds_write2_b32 v65, v77, v64 offset0:64 offset1:80
	v_mul_f32_e32 v64, v70, v74
	v_mul_f32_e32 v64, v66, v64
	v_sub_f32_e32 v66, v67, v147
	v_cndmask_b32_e64 v64, 0, v64, s[40:41]
	v_mul_f32_e32 v66, 0x3fb8aa3b, v66
	ds_write2_b32 v65, v78, v64 offset0:132 offset1:148
	v_mul_f32_e32 v64, v71, v75
	v_exp_f32_e32 v66, v66
	v_mfma_f32_16x16x32_bf16 v[72:75], v[28:31], v[60:63], 0
	v_mul_f32_e32 v64, v66, v64
	v_mfma_f32_16x16x32_bf16 v[72:75], v[24:27], v[56:59], v[72:75]
	v_cndmask_b32_e64 v64, 0, v64, s[42:43]
	ds_write2_b32 v65, v79, v64 offset0:200 offset1:216
	ds_read_b128 v[64:67], v148 offset:17536
	ds_read_b128 v[68:71], v148 offset:17792
	v_mfma_f32_16x16x32_bf16 v[72:75], v[20:23], v[52:55], v[72:75]
	s_waitcnt lgkmcnt(1)
	v_sub_f32_e32 v76, v64, v146
	v_mfma_f32_16x16x32_bf16 v[72:75], v[16:19], v[48:51], v[72:75]
	v_mul_f32_e32 v76, 0x3fb8aa3b, v76
	v_exp_f32_e32 v76, v76
	v_sub_f32_e32 v80, v64, v147
	v_mul_f32_e32 v80, 0x3fb8aa3b, v80
	v_exp_f32_e32 v80, v80
	s_waitcnt lgkmcnt(0)
	s_nop 1
	v_mul_f32_e32 v72, v68, v72
	v_mul_f32_e32 v76, v76, v72
	v_mul_f32_e32 v72, v69, v73
	v_sub_f32_e32 v73, v65, v146
	v_mul_f32_e32 v73, 0x3fb8aa3b, v73
	v_exp_f32_e32 v73, v73
	v_sub_f32_e32 v64, v64, v144
	v_mul_f32_e32 v64, 0x3fb8aa3b, v64
	v_exp_f32_e32 v64, v64
	v_mul_f32_e32 v77, v73, v72
	v_sub_f32_e32 v73, v66, v146
	v_mul_f32_e32 v73, 0x3fb8aa3b, v73
	v_exp_f32_e32 v73, v73
	v_mul_f32_e32 v72, v70, v74
	v_mfma_f32_16x16x32_bf16 v[60:63], v[12:15], v[60:63], 0
	v_mul_f32_e32 v78, v73, v72
	v_sub_f32_e32 v73, v67, v146
	v_mul_f32_e32 v73, 0x3fb8aa3b, v73
	v_exp_f32_e32 v73, v73
	v_mul_f32_e32 v72, v71, v75
	v_mfma_f32_16x16x32_bf16 v[56:59], v[8:11], v[56:59], v[60:63]
	v_mul_f32_e32 v79, v73, v72
	v_mfma_f32_16x16x32_bf16 v[72:75], v[28:31], v[44:47], 0
	v_mfma_f32_16x16x32_bf16 v[72:75], v[24:27], v[40:43], v[72:75]
	v_mfma_f32_16x16x32_bf16 v[72:75], v[20:23], v[32:35], v[72:75]
	v_mfma_f32_16x16x32_bf16 v[72:75], v[16:19], v[36:39], v[72:75]
	v_mfma_f32_16x16x32_bf16 v[44:47], v[12:15], v[44:47], 0
	v_mfma_f32_16x16x32_bf16 v[40:43], v[8:11], v[40:43], v[44:47]
	s_nop 5
	v_mul_f32_e32 v72, v68, v72
	v_mul_f32_e32 v72, v80, v72
	v_add_u32_e32 v80, 0x2000, v242
	ds_write2_b32 v80, v76, v72 offset0:60 offset1:76
	v_mul_f32_e32 v72, v69, v73
	v_sub_f32_e32 v73, v65, v147
	v_mul_f32_e32 v73, 0x3fb8aa3b, v73
	v_exp_f32_e32 v73, v73
	v_sub_f32_e32 v65, v65, v144
	v_mul_f32_e32 v65, 0x3fb8aa3b, v65
	v_exp_f32_e32 v65, v65
	v_mul_f32_e32 v76, v73, v72
	v_sub_f32_e32 v73, v66, v147
	v_mul_f32_e32 v73, 0x3fb8aa3b, v73
	v_exp_f32_e32 v73, v73
	v_mul_f32_e32 v72, v70, v74
	v_mfma_f32_16x16x32_bf16 v[52:55], v[0:3], v[52:55], v[56:59]
	v_mul_f32_e32 v72, v73, v72
	v_sub_f32_e32 v73, v67, v147
	v_mul_f32_e32 v73, 0x3fb8aa3b, v73
	v_exp_f32_e32 v73, v73
	ds_write2_b32 v80, v78, v72 offset0:196 offset1:212
	v_mul_f32_e32 v72, v71, v75
	v_mfma_f32_16x16x32_bf16 v[32:35], v[0:3], v[32:35], v[40:43]
	v_mul_f32_e32 v78, v73, v72
	v_mfma_f32_16x16x32_bf16 v[72:75], v[28:31], v[28:31], 0
	v_mfma_f32_16x16x32_bf16 v[72:75], v[24:27], v[24:27], v[72:75]
	v_mfma_f32_16x16x32_bf16 v[72:75], v[20:23], v[20:23], v[72:75]
	v_mfma_f32_16x16x32_bf16 v[72:75], v[16:19], v[16:19], v[72:75]
	v_mfma_f32_16x16x32_bf16 v[28:31], v[12:15], v[28:31], 0
	v_mfma_f32_16x16x32_bf16 v[12:15], v[12:15], v[12:15], 0
	s_nop 5
	v_mul_f32_e32 v68, v68, v72
	v_mul_f32_e32 v64, v64, v68
	v_cndmask_b32_e64 v64, 0, v64, s[30:31]
	ds_write2_b32 v80, v64, v77 offset0:92 offset1:128
	v_mul_f32_e32 v64, v69, v73
	v_mul_f32_e32 v64, v65, v64
	v_sub_f32_e32 v65, v66, v144
	v_mul_f32_e32 v65, 0x3fb8aa3b, v65
	v_exp_f32_e32 v65, v65
	v_cndmask_b32_e64 v64, 0, v64, s[44:45]
	ds_write2_b32 v80, v76, v64 offset0:144 offset1:160
	v_mul_f32_e32 v64, v70, v74
	v_mul_f32_e32 v64, v65, v64
	v_cndmask_b32_e64 v64, 0, v64, s[46:47]
	v_add_u32_e32 v65, 0x2200, v242
	ds_write2_b32 v65, v64, v79 offset0:100 offset1:136
	v_sub_f32_e32 v65, v67, v144
	v_mul_f32_e32 v65, 0x3fb8aa3b, v65
	v_exp_f32_e32 v65, v65
	v_mul_f32_e32 v64, v71, v75
	v_mfma_f32_16x16x32_bf16 v[24:27], v[8:11], v[24:27], v[28:31]
	v_mul_f32_e32 v64, v65, v64
	v_cndmask_b32_e64 v64, 0, v64, s[48:49]
	v_mfma_f32_16x16x32_bf16 v[8:11], v[8:11], v[8:11], v[12:15]
	v_add_u32_e32 v65, 0x2400, v242
	ds_write2_b32 v65, v78, v64 offset0:24 offset1:40
	ds_read_b128 v[64:67], v148 offset:17600
	ds_read_b128 v[68:71], v148 offset:17856
	v_mfma_f32_16x16x32_bf16 v[20:23], v[0:3], v[20:23], v[24:27]
	v_mfma_f32_16x16x32_bf16 v[0:3], v[0:3], v[0:3], v[8:11]
	v_mfma_f32_16x16x32_bf16 v[48:51], v[4:7], v[48:51], v[52:55]
	v_mfma_f32_16x16x32_bf16 v[32:35], v[4:7], v[36:39], v[32:35]
	s_waitcnt lgkmcnt(1)
	v_sub_f32_e32 v36, v64, v147
	v_mul_f32_e32 v36, 0x3fb8aa3b, v36
	v_sub_f32_e32 v52, v64, v146
	v_mfma_f32_16x16x32_bf16 v[16:19], v[4:7], v[16:19], v[20:23]
	v_exp_f32_e32 v36, v36
	v_mul_f32_e32 v52, 0x3fb8aa3b, v52
	v_exp_f32_e32 v52, v52
	v_mfma_f32_16x16x32_bf16 v[0:3], v[4:7], v[4:7], v[0:3]
	v_sub_f32_e32 v4, v64, v145
	v_sub_f32_e32 v20, v64, v144
	v_mul_f32_e32 v4, 0x3fb8aa3b, v4
	v_mul_f32_e32 v20, 0x3fb8aa3b, v20
	v_exp_f32_e32 v4, v4
	v_exp_f32_e32 v20, v20
	s_waitcnt lgkmcnt(0)
	s_nop 0
	v_mul_f32_e32 v0, v68, v0
	v_mul_f32_e32 v32, v68, v32
	v_mul_f32_e32 v16, v68, v16
	v_mul_f32_e32 v0, v4, v0
	v_mul_f32_e32 v32, v36, v32
	v_add_u32_e32 v36, 0x3000, v242
	v_mul_f32_e32 v16, v20, v16
	v_cndmask_b32_e64 v0, 0, v0, s[30:31]
	v_mul_f32_e32 v48, v68, v48
	ds_write2_b32 v36, v16, v0 offset0:156 offset1:172
	v_mul_f32_e32 v0, v69, v1
	v_sub_f32_e32 v1, v65, v145
	v_mul_f32_e32 v48, v52, v48
	v_sub_f32_e32 v52, v65, v146
	v_sub_f32_e32 v20, v65, v144
	v_mul_f32_e32 v1, 0x3fb8aa3b, v1
	v_mul_f32_e32 v52, 0x3fb8aa3b, v52
	v_mul_f32_e32 v20, 0x3fb8aa3b, v20
	v_exp_f32_e32 v1, v1
	v_exp_f32_e32 v52, v52
	v_exp_f32_e32 v20, v20
	ds_write2_b32 v36, v48, v32 offset0:124 offset1:140
	v_mul_f32_e32 v32, v69, v33
	v_sub_f32_e32 v33, v65, v147
	v_mul_f32_e32 v33, 0x3fb8aa3b, v33
	v_mul_f32_e32 v49, v69, v49
	v_exp_f32_e32 v33, v33
	v_mul_f32_e32 v17, v69, v17
	v_mul_f32_e32 v0, v1, v0
	v_sub_f32_e32 v1, v66, v145
	v_mul_f32_e32 v49, v52, v49
	v_sub_f32_e32 v52, v66, v146
	v_mul_f32_e32 v17, v20, v17
	v_sub_f32_e32 v20, v66, v144
	v_mul_f32_e32 v1, 0x3fb8aa3b, v1
	v_mul_f32_e32 v52, 0x3fb8aa3b, v52
	v_mul_f32_e32 v20, 0x3fb8aa3b, v20
	v_exp_f32_e32 v1, v1
	v_exp_f32_e32 v52, v52
	v_exp_f32_e32 v20, v20
	v_mul_f32_e32 v32, v33, v32
	v_sub_f32_e32 v33, v66, v147
	v_cndmask_b32_e64 v0, 0, v0, s[50:51]
	v_mul_f32_e32 v33, 0x3fb8aa3b, v33
	ds_write2_b32 v36, v17, v0 offset0:224 offset1:240
	v_mul_f32_e32 v0, v70, v2
	v_mul_f32_e32 v50, v70, v50
	v_exp_f32_e32 v33, v33
	v_mul_f32_e32 v18, v70, v18
	v_mul_f32_e32 v0, v1, v0
	v_sub_f32_e32 v1, v67, v145
	v_mul_f32_e32 v50, v52, v50
	v_sub_f32_e32 v52, v67, v146
	ds_write2_b32 v36, v49, v32 offset0:192 offset1:208
	v_mul_f32_e32 v32, v70, v34
	v_sub_f32_e32 v34, v67, v147
	v_mul_f32_e32 v18, v20, v18
	v_sub_f32_e32 v20, v67, v144
	v_mul_f32_e32 v1, 0x3fb8aa3b, v1
	v_mul_f32_e32 v52, 0x3fb8aa3b, v52
	v_mul_f32_e32 v34, 0x3fb8aa3b, v34
	v_mul_f32_e32 v20, 0x3fb8aa3b, v20
	v_exp_f32_e32 v1, v1
	v_exp_f32_e32 v52, v52
	v_exp_f32_e32 v34, v34
	v_exp_f32_e32 v20, v20
	v_mul_f32_e32 v32, v33, v32
	v_add_u32_e32 v33, 0x3400, v242
	v_cndmask_b32_e64 v0, 0, v0, s[52:53]
	ds_write2_b32 v33, v18, v0 offset0:36 offset1:52
	v_mul_f32_e32 v0, v71, v3
	v_mul_f32_e32 v51, v71, v51
	ds_write2_b32 v33, v50, v32 offset0:4 offset1:20
	v_mul_f32_e32 v32, v71, v35
	v_mul_f32_e32 v19, v71, v19
	v_mul_f32_e32 v0, v1, v0
	v_mul_f32_e32 v51, v52, v51
	v_mul_f32_e32 v32, v34, v32
	v_mul_f32_e32 v19, v20, v19
	v_cndmask_b32_e64 v0, 0, v0, s[54:55]
	ds_write2_b32 v33, v51, v32 offset0:72 offset1:88
	ds_write2_b32 v33, v19, v0 offset0:104 offset1:120
	v_mov_b32_e32 v64, s63
	v_mov_b32_e32 v0, v153
	ds_read_b128 v[68:71], v64 offset:272
	ds_read_b128 v[72:75], v64 offset:544
	ds_read_b128 v[76:79], v64 offset:816
	ds_read_b128 v[80:83], v64 offset:1088
	ds_read_b128 v[84:87], v64 offset:1360
	ds_read_b128 v[88:91], v64 offset:1376
	ds_read_b128 v[92:95], v64 offset:1632
	ds_read_b128 v[96:99], v64 offset:1904
	ds_read_b128 v[100:103], v64 offset:1648
	ds_read_b128 v[104:107], v64 offset:1920
	s_waitcnt lgkmcnt(9)
	v_fma_f32 v1, -v68, v0, v154
	ds_read_b128 v[68:71], v64 offset:2176
	s_waitcnt lgkmcnt(9)
	v_pk_mul_f32 v[108:109], v[72:73], v[0:1] neg_lo:[1,0] neg_hi:[1,0]
	v_add_f32_e32 v108, v108, v109
	v_add_f32_e32 v2, v155, v108
	ds_read_b128 v[72:75], v64 offset:2448
	s_waitcnt lgkmcnt(9)
	v_pk_mul_f32 v[110:111], v[76:77], v[0:1] neg_lo:[1,0] neg_hi:[1,0]
	v_fma_f32 v110, -v78, v2, v110
	v_add_f32_e32 v110, v110, v111
	v_add_f32_e32 v3, v156, v110
	ds_read_b128 v[76:79], v64 offset:2192
	s_waitcnt lgkmcnt(9)
	v_pk_mul_f32 v[112:113], v[80:81], v[0:1] neg_lo:[1,0] neg_hi:[1,0]
	v_pk_fma_f32 v[112:113], v[82:83], v[2:3], v[112:113] neg_lo:[1,0,0] neg_hi:[1,0,0]
	v_add_f32_e32 v112, v112, v113
	v_add_f32_e32 v4, v157, v112
	ds_read_b128 v[80:83], v64 offset:2464
	s_waitcnt lgkmcnt(9)
	v_pk_mul_f32 v[114:115], v[84:85], v[0:1] neg_lo:[1,0] neg_hi:[1,0]
	v_pk_fma_f32 v[114:115], v[86:87], v[2:3], v[114:115] neg_lo:[1,0,0] neg_hi:[1,0,0]
	ds_read_b128 v[84:87], v64 offset:2480
	s_waitcnt lgkmcnt(9)
	v_fma_f32 v114, -v88, v4, v114
	v_add_f32_e32 v114, v114, v115
	v_add_f32_e32 v5, v158, v114
	ds_read_b128 v[88:91], v64 offset:2720
	s_waitcnt lgkmcnt(9)
	v_pk_mul_f32 v[108:109], v[92:93], v[0:1] neg_lo:[1,0] neg_hi:[1,0]
	v_pk_fma_f32 v[108:109], v[94:95], v[2:3], v[108:109] neg_lo:[1,0,0] neg_hi:[1,0,0]
	ds_read_b128 v[92:95], v64 offset:2992
	s_waitcnt lgkmcnt(9)
	v_pk_mul_f32 v[110:111], v[96:97], v[0:1] neg_lo:[1,0] neg_hi:[1,0]
	v_pk_fma_f32 v[110:111], v[98:99], v[2:3], v[110:111] neg_lo:[1,0,0] neg_hi:[1,0,0]
	ds_read_b128 v[96:99], v64 offset:2736
	s_waitcnt lgkmcnt(9)
	v_pk_fma_f32 v[108:109], v[100:101], v[4:5], v[108:109] neg_lo:[1,0,0] neg_hi:[1,0,0]
	v_add_f32_e32 v108, v108, v109
	v_add_f32_e32 v6, v159, v108
	ds_read_b128 v[100:103], v64 offset:3008
	s_waitcnt lgkmcnt(9)
	v_pk_fma_f32 v[110:111], v[104:105], v[4:5], v[110:111] neg_lo:[1,0,0] neg_hi:[1,0,0]
	v_fma_f32 v110, -v106, v6, v110
	v_add_f32_e32 v110, v110, v111
	v_add_f32_e32 v7, v160, v110
	ds_read_b128 v[104:107], v64 offset:2752
	s_waitcnt lgkmcnt(9)
	v_pk_mul_f32 v[112:113], v[68:69], v[0:1] neg_lo:[1,0] neg_hi:[1,0]
	v_pk_fma_f32 v[112:113], v[70:71], v[2:3], v[112:113] neg_lo:[1,0,0] neg_hi:[1,0,0]
	ds_read_b128 v[68:71], v64 offset:3024
	s_waitcnt lgkmcnt(9)
	v_pk_mul_f32 v[114:115], v[72:73], v[0:1] neg_lo:[1,0] neg_hi:[1,0]
	v_pk_fma_f32 v[114:115], v[74:75], v[2:3], v[114:115] neg_lo:[1,0,0] neg_hi:[1,0,0]
	ds_read_b128 v[72:75], v64 offset:3264
	s_waitcnt lgkmcnt(9)
	v_pk_fma_f32 v[112:113], v[76:77], v[4:5], v[112:113] neg_lo:[1,0,0] neg_hi:[1,0,0]
	v_pk_fma_f32 v[112:113], v[78:79], v[6:7], v[112:113] neg_lo:[1,0,0] neg_hi:[1,0,0]
	v_add_f32_e32 v112, v112, v113
	v_add_f32_e32 v8, v161, v112
	ds_read_b128 v[76:79], v64 offset:3536
	s_waitcnt lgkmcnt(9)
	v_pk_fma_f32 v[114:115], v[80:81], v[4:5], v[114:115] neg_lo:[1,0,0] neg_hi:[1,0,0]
	v_pk_fma_f32 v[114:115], v[82:83], v[6:7], v[114:115] neg_lo:[1,0,0] neg_hi:[1,0,0]
	ds_read_b128 v[80:83], v64 offset:3280
	s_waitcnt lgkmcnt(9)
	v_fma_f32 v114, -v84, v8, v114
	v_add_f32_e32 v114, v114, v115
	v_add_f32_e32 v9, v162, v114
	ds_read_b128 v[84:87], v64 offset:3552
	s_waitcnt lgkmcnt(9)
	v_pk_mul_f32 v[108:109], v[88:89], v[0:1] neg_lo:[1,0] neg_hi:[1,0]
	v_pk_fma_f32 v[108:109], v[90:91], v[2:3], v[108:109] neg_lo:[1,0,0] neg_hi:[1,0,0]
	ds_read_b128 v[88:91], v64 offset:3296
	s_waitcnt lgkmcnt(9)
	v_pk_mul_f32 v[110:111], v[92:93], v[0:1] neg_lo:[1,0] neg_hi:[1,0]
	v_pk_fma_f32 v[110:111], v[94:95], v[2:3], v[110:111] neg_lo:[1,0,0] neg_hi:[1,0,0]
	ds_read_b128 v[92:95], v64 offset:3568
	s_waitcnt lgkmcnt(9)
	v_pk_fma_f32 v[108:109], v[96:97], v[4:5], v[108:109] neg_lo:[1,0,0] neg_hi:[1,0,0]
	v_pk_fma_f32 v[108:109], v[98:99], v[6:7], v[108:109] neg_lo:[1,0,0] neg_hi:[1,0,0]
	ds_read_b128 v[96:99], v64 offset:3584
	s_waitcnt lgkmcnt(9)
	v_pk_fma_f32 v[110:111], v[100:101], v[4:5], v[110:111] neg_lo:[1,0,0] neg_hi:[1,0,0]
	v_pk_fma_f32 v[110:111], v[102:103], v[6:7], v[110:111] neg_lo:[1,0,0] neg_hi:[1,0,0]
	ds_read_b128 v[100:103], v64 offset:3808
	s_waitcnt lgkmcnt(9)
	v_pk_fma_f32 v[108:109], v[104:105], v[8:9], v[108:109] neg_lo:[1,0,0] neg_hi:[1,0,0]
	v_add_f32_e32 v108, v108, v109
	v_add_f32_e32 v10, v163, v108
	ds_read_b128 v[104:107], v64 offset:4080
	s_waitcnt lgkmcnt(9)
	v_pk_fma_f32 v[110:111], v[68:69], v[8:9], v[110:111] neg_lo:[1,0,0] neg_hi:[1,0,0]
	v_fma_f32 v110, -v70, v10, v110
	v_add_f32_e32 v110, v110, v111
	v_add_f32_e32 v11, v164, v110
	ds_read_b128 v[68:71], v64 offset:3824
	s_waitcnt lgkmcnt(9)
	v_pk_mul_f32 v[112:113], v[72:73], v[0:1] neg_lo:[1,0] neg_hi:[1,0]
	v_pk_fma_f32 v[112:113], v[74:75], v[2:3], v[112:113] neg_lo:[1,0,0] neg_hi:[1,0,0]
	ds_read_b128 v[72:75], v64 offset:4096
	s_waitcnt lgkmcnt(9)
	v_pk_mul_f32 v[114:115], v[76:77], v[0:1] neg_lo:[1,0] neg_hi:[1,0]
	v_pk_fma_f32 v[114:115], v[78:79], v[2:3], v[114:115] neg_lo:[1,0,0] neg_hi:[1,0,0]
	ds_read_b128 v[76:79], v64 offset:3840
	s_waitcnt lgkmcnt(9)
	v_pk_fma_f32 v[112:113], v[80:81], v[4:5], v[112:113] neg_lo:[1,0,0] neg_hi:[1,0,0]
	v_pk_fma_f32 v[112:113], v[82:83], v[6:7], v[112:113] neg_lo:[1,0,0] neg_hi:[1,0,0]
	ds_read_b128 v[80:83], v64 offset:4112
	s_waitcnt lgkmcnt(9)
	v_pk_fma_f32 v[114:115], v[84:85], v[4:5], v[114:115] neg_lo:[1,0,0] neg_hi:[1,0,0]
	v_pk_fma_f32 v[114:115], v[86:87], v[6:7], v[114:115] neg_lo:[1,0,0] neg_hi:[1,0,0]
	ds_read_b128 v[84:87], v64 offset:3856
	s_waitcnt lgkmcnt(9)
	v_pk_fma_f32 v[112:113], v[88:89], v[8:9], v[112:113] neg_lo:[1,0,0] neg_hi:[1,0,0]
	v_pk_fma_f32 v[112:113], v[90:91], v[10:11], v[112:113] neg_lo:[1,0,0] neg_hi:[1,0,0]
	v_add_f32_e32 v112, v112, v113
	v_add_f32_e32 v12, v165, v112
	ds_read_b128 v[88:91], v64 offset:4128
	s_waitcnt lgkmcnt(9)
	v_pk_fma_f32 v[114:115], v[92:93], v[8:9], v[114:115] neg_lo:[1,0,0] neg_hi:[1,0,0]
	v_pk_fma_f32 v[114:115], v[94:95], v[10:11], v[114:115] neg_lo:[1,0,0] neg_hi:[1,0,0]
	ds_read_b128 v[92:95], v64 offset:4352
	s_waitcnt lgkmcnt(9)
	v_fma_f32 v114, -v96, v12, v114
	v_add_f32_e32 v114, v114, v115
	v_add_f32_e32 v13, v166, v114
	ds_read_b128 v[96:99], v64 offset:4624
	s_waitcnt lgkmcnt(9)
	v_pk_mul_f32 v[108:109], v[100:101], v[0:1] neg_lo:[1,0] neg_hi:[1,0]
	v_pk_fma_f32 v[108:109], v[102:103], v[2:3], v[108:109] neg_lo:[1,0,0] neg_hi:[1,0,0]
	ds_read_b128 v[100:103], v64 offset:4368
	s_waitcnt lgkmcnt(9)
	v_pk_mul_f32 v[110:111], v[104:105], v[0:1] neg_lo:[1,0] neg_hi:[1,0]
	v_pk_fma_f32 v[110:111], v[106:107], v[2:3], v[110:111] neg_lo:[1,0,0] neg_hi:[1,0,0]
	ds_read_b128 v[104:107], v64 offset:4640
	s_waitcnt lgkmcnt(9)
	v_pk_fma_f32 v[108:109], v[68:69], v[4:5], v[108:109] neg_lo:[1,0,0] neg_hi:[1,0,0]
	v_pk_fma_f32 v[108:109], v[70:71], v[6:7], v[108:109] neg_lo:[1,0,0] neg_hi:[1,0,0]
	ds_read_b128 v[68:71], v64 offset:4384
	s_waitcnt lgkmcnt(9)
	v_pk_fma_f32 v[110:111], v[72:73], v[4:5], v[110:111] neg_lo:[1,0,0] neg_hi:[1,0,0]
	v_pk_fma_f32 v[110:111], v[74:75], v[6:7], v[110:111] neg_lo:[1,0,0] neg_hi:[1,0,0]
	ds_read_b128 v[72:75], v64 offset:4656
	s_waitcnt lgkmcnt(9)
	v_pk_fma_f32 v[108:109], v[76:77], v[8:9], v[108:109] neg_lo:[1,0,0] neg_hi:[1,0,0]
	v_pk_fma_f32 v[108:109], v[78:79], v[10:11], v[108:109] neg_lo:[1,0,0] neg_hi:[1,0,0]
	ds_read_b128 v[76:79], v64 offset:4400
	s_waitcnt lgkmcnt(9)
	v_pk_fma_f32 v[110:111], v[80:81], v[8:9], v[110:111] neg_lo:[1,0,0] neg_hi:[1,0,0]
	v_pk_fma_f32 v[110:111], v[82:83], v[10:11], v[110:111] neg_lo:[1,0,0] neg_hi:[1,0,0]
	ds_read_b128 v[80:83], v64 offset:4672
	s_waitcnt lgkmcnt(9)
	v_pk_fma_f32 v[108:109], v[84:85], v[12:13], v[108:109] neg_lo:[1,0,0] neg_hi:[1,0,0]
	v_add_f32_e32 v108, v108, v109
	v_add_f32_e32 v14, v167, v108
	ds_read_b128 v[84:87], v64 offset:4688
	s_waitcnt lgkmcnt(9)
	v_pk_fma_f32 v[110:111], v[88:89], v[12:13], v[110:111] neg_lo:[1,0,0] neg_hi:[1,0,0]
	v_fma_f32 v110, -v90, v14, v110
	v_add_f32_e32 v110, v110, v111
	v_add_f32_e32 v15, v168, v110
	ds_read_b128 v[88:91], v64 offset:4896
	s_waitcnt lgkmcnt(9)
	v_pk_mul_f32 v[112:113], v[92:93], v[0:1] neg_lo:[1,0] neg_hi:[1,0]
	v_pk_fma_f32 v[112:113], v[94:95], v[2:3], v[112:113] neg_lo:[1,0,0] neg_hi:[1,0,0]
	ds_read_b128 v[92:95], v64 offset:5168
	s_waitcnt lgkmcnt(9)
	v_pk_mul_f32 v[114:115], v[96:97], v[0:1] neg_lo:[1,0] neg_hi:[1,0]
	v_pk_fma_f32 v[114:115], v[98:99], v[2:3], v[114:115] neg_lo:[1,0,0] neg_hi:[1,0,0]
	ds_read_b128 v[96:99], v64 offset:4912
	s_waitcnt lgkmcnt(9)
	v_pk_fma_f32 v[112:113], v[100:101], v[4:5], v[112:113] neg_lo:[1,0,0] neg_hi:[1,0,0]
	v_pk_fma_f32 v[112:113], v[102:103], v[6:7], v[112:113] neg_lo:[1,0,0] neg_hi:[1,0,0]
	ds_read_b128 v[100:103], v64 offset:5184
	s_waitcnt lgkmcnt(9)
	v_pk_fma_f32 v[114:115], v[104:105], v[4:5], v[114:115] neg_lo:[1,0,0] neg_hi:[1,0,0]
	v_pk_fma_f32 v[114:115], v[106:107], v[6:7], v[114:115] neg_lo:[1,0,0] neg_hi:[1,0,0]
	ds_read_b128 v[104:107], v64 offset:4928
	s_waitcnt lgkmcnt(9)
	v_pk_fma_f32 v[112:113], v[68:69], v[8:9], v[112:113] neg_lo:[1,0,0] neg_hi:[1,0,0]
	v_pk_fma_f32 v[112:113], v[70:71], v[10:11], v[112:113] neg_lo:[1,0,0] neg_hi:[1,0,0]
	ds_read_b128 v[68:71], v64 offset:5200
	s_waitcnt lgkmcnt(9)
	v_pk_fma_f32 v[114:115], v[72:73], v[8:9], v[114:115] neg_lo:[1,0,0] neg_hi:[1,0,0]
	v_pk_fma_f32 v[114:115], v[74:75], v[10:11], v[114:115] neg_lo:[1,0,0] neg_hi:[1,0,0]
	ds_read_b128 v[72:75], v64 offset:4944
	s_waitcnt lgkmcnt(9)
	v_pk_fma_f32 v[112:113], v[76:77], v[12:13], v[112:113] neg_lo:[1,0,0] neg_hi:[1,0,0]
	v_pk_fma_f32 v[112:113], v[78:79], v[14:15], v[112:113] neg_lo:[1,0,0] neg_hi:[1,0,0]
	v_add_f32_e32 v112, v112, v113
	v_add_f32_e32 v16, v169, v112
	ds_read_b128 v[76:79], v64 offset:5216
	s_waitcnt lgkmcnt(9)
	v_pk_fma_f32 v[114:115], v[80:81], v[12:13], v[114:115] neg_lo:[1,0,0] neg_hi:[1,0,0]
	v_pk_fma_f32 v[114:115], v[82:83], v[14:15], v[114:115] neg_lo:[1,0,0] neg_hi:[1,0,0]
	ds_read_b128 v[80:83], v64 offset:4960
	s_waitcnt lgkmcnt(9)
	v_fma_f32 v114, -v84, v16, v114
	v_add_f32_e32 v114, v114, v115
	v_add_f32_e32 v17, v170, v114
	ds_read_b128 v[84:87], v64 offset:5232
	s_waitcnt lgkmcnt(9)
	v_pk_mul_f32 v[108:109], v[88:89], v[0:1] neg_lo:[1,0] neg_hi:[1,0]
	v_pk_fma_f32 v[108:109], v[90:91], v[2:3], v[108:109] neg_lo:[1,0,0] neg_hi:[1,0,0]
	ds_read_b128 v[88:91], v64 offset:5440
	s_waitcnt lgkmcnt(9)
	v_pk_mul_f32 v[110:111], v[92:93], v[0:1] neg_lo:[1,0] neg_hi:[1,0]
	v_pk_fma_f32 v[110:111], v[94:95], v[2:3], v[110:111] neg_lo:[1,0,0] neg_hi:[1,0,0]
	ds_read_b128 v[92:95], v64 offset:5712
	s_waitcnt lgkmcnt(9)
	v_pk_fma_f32 v[108:109], v[96:97], v[4:5], v[108:109] neg_lo:[1,0,0] neg_hi:[1,0,0]
	v_pk_fma_f32 v[108:109], v[98:99], v[6:7], v[108:109] neg_lo:[1,0,0] neg_hi:[1,0,0]
	ds_read_b128 v[96:99], v64 offset:5456
	s_waitcnt lgkmcnt(9)
	v_pk_fma_f32 v[110:111], v[100:101], v[4:5], v[110:111] neg_lo:[1,0,0] neg_hi:[1,0,0]
	v_pk_fma_f32 v[110:111], v[102:103], v[6:7], v[110:111] neg_lo:[1,0,0] neg_hi:[1,0,0]
	ds_read_b128 v[100:103], v64 offset:5728
	s_waitcnt lgkmcnt(9)
	v_pk_fma_f32 v[108:109], v[104:105], v[8:9], v[108:109] neg_lo:[1,0,0] neg_hi:[1,0,0]
	v_pk_fma_f32 v[108:109], v[106:107], v[10:11], v[108:109] neg_lo:[1,0,0] neg_hi:[1,0,0]
	ds_read_b128 v[104:107], v64 offset:5472
	s_waitcnt lgkmcnt(9)
	v_pk_fma_f32 v[110:111], v[68:69], v[8:9], v[110:111] neg_lo:[1,0,0] neg_hi:[1,0,0]
	v_pk_fma_f32 v[110:111], v[70:71], v[10:11], v[110:111] neg_lo:[1,0,0] neg_hi:[1,0,0]
	ds_read_b128 v[68:71], v64 offset:5744
	s_waitcnt lgkmcnt(9)
	v_pk_fma_f32 v[108:109], v[72:73], v[12:13], v[108:109] neg_lo:[1,0,0] neg_hi:[1,0,0]
	v_pk_fma_f32 v[108:109], v[74:75], v[14:15], v[108:109] neg_lo:[1,0,0] neg_hi:[1,0,0]
	ds_read_b128 v[72:75], v64 offset:5488
	s_waitcnt lgkmcnt(9)
	v_pk_fma_f32 v[110:111], v[76:77], v[12:13], v[110:111] neg_lo:[1,0,0] neg_hi:[1,0,0]
	v_pk_fma_f32 v[110:111], v[78:79], v[14:15], v[110:111] neg_lo:[1,0,0] neg_hi:[1,0,0]
	ds_read_b128 v[76:79], v64 offset:5760
	s_waitcnt lgkmcnt(9)
	v_pk_fma_f32 v[108:109], v[80:81], v[16:17], v[108:109] neg_lo:[1,0,0] neg_hi:[1,0,0]
	v_add_f32_e32 v108, v108, v109
	v_add_f32_e32 v18, v171, v108
	ds_read_b128 v[80:83], v64 offset:5504
	s_waitcnt lgkmcnt(9)
	v_pk_fma_f32 v[110:111], v[84:85], v[16:17], v[110:111] neg_lo:[1,0,0] neg_hi:[1,0,0]
	v_fma_f32 v110, -v86, v18, v110
	v_add_f32_e32 v110, v110, v111
	v_add_f32_e32 v19, v172, v110
	ds_read_b128 v[84:87], v64 offset:5776
	s_waitcnt lgkmcnt(9)
	v_pk_mul_f32 v[112:113], v[88:89], v[0:1] neg_lo:[1,0] neg_hi:[1,0]
	v_pk_fma_f32 v[112:113], v[90:91], v[2:3], v[112:113] neg_lo:[1,0,0] neg_hi:[1,0,0]
	ds_read_b128 v[88:91], v64 offset:5792
	s_waitcnt lgkmcnt(9)
	v_pk_mul_f32 v[114:115], v[92:93], v[0:1] neg_lo:[1,0] neg_hi:[1,0]
	v_pk_fma_f32 v[114:115], v[94:95], v[2:3], v[114:115] neg_lo:[1,0,0] neg_hi:[1,0,0]
	ds_read_b128 v[92:95], v64 offset:5984
	s_waitcnt lgkmcnt(9)
	v_pk_fma_f32 v[112:113], v[96:97], v[4:5], v[112:113] neg_lo:[1,0,0] neg_hi:[1,0,0]
	v_pk_fma_f32 v[112:113], v[98:99], v[6:7], v[112:113] neg_lo:[1,0,0] neg_hi:[1,0,0]
	ds_read_b128 v[96:99], v64 offset:6256
	s_waitcnt lgkmcnt(9)
	v_pk_fma_f32 v[114:115], v[100:101], v[4:5], v[114:115] neg_lo:[1,0,0] neg_hi:[1,0,0]
	v_pk_fma_f32 v[114:115], v[102:103], v[6:7], v[114:115] neg_lo:[1,0,0] neg_hi:[1,0,0]
	ds_read_b128 v[100:103], v64 offset:6000
	s_waitcnt lgkmcnt(9)
	v_pk_fma_f32 v[112:113], v[104:105], v[8:9], v[112:113] neg_lo:[1,0,0] neg_hi:[1,0,0]
	v_pk_fma_f32 v[112:113], v[106:107], v[10:11], v[112:113] neg_lo:[1,0,0] neg_hi:[1,0,0]
	ds_read_b128 v[104:107], v64 offset:6272
	s_waitcnt lgkmcnt(9)
	v_pk_fma_f32 v[114:115], v[68:69], v[8:9], v[114:115] neg_lo:[1,0,0] neg_hi:[1,0,0]
	v_pk_fma_f32 v[114:115], v[70:71], v[10:11], v[114:115] neg_lo:[1,0,0] neg_hi:[1,0,0]
	ds_read_b128 v[68:71], v64 offset:6016
	s_waitcnt lgkmcnt(9)
	v_pk_fma_f32 v[112:113], v[72:73], v[12:13], v[112:113] neg_lo:[1,0,0] neg_hi:[1,0,0]
	v_pk_fma_f32 v[112:113], v[74:75], v[14:15], v[112:113] neg_lo:[1,0,0] neg_hi:[1,0,0]
	ds_read_b128 v[72:75], v64 offset:6288
	s_waitcnt lgkmcnt(9)
	v_pk_fma_f32 v[114:115], v[76:77], v[12:13], v[114:115] neg_lo:[1,0,0] neg_hi:[1,0,0]
	v_pk_fma_f32 v[114:115], v[78:79], v[14:15], v[114:115] neg_lo:[1,0,0] neg_hi:[1,0,0]
	ds_read_b128 v[76:79], v64 offset:6032
	s_waitcnt lgkmcnt(9)
	v_pk_fma_f32 v[112:113], v[80:81], v[16:17], v[112:113] neg_lo:[1,0,0] neg_hi:[1,0,0]
	v_pk_fma_f32 v[112:113], v[82:83], v[18:19], v[112:113] neg_lo:[1,0,0] neg_hi:[1,0,0]
	v_add_f32_e32 v112, v112, v113
	v_add_f32_e32 v20, v173, v112
	ds_read_b128 v[80:83], v64 offset:6304
	s_waitcnt lgkmcnt(9)
	v_pk_fma_f32 v[114:115], v[84:85], v[16:17], v[114:115] neg_lo:[1,0,0] neg_hi:[1,0,0]
	v_pk_fma_f32 v[114:115], v[86:87], v[18:19], v[114:115] neg_lo:[1,0,0] neg_hi:[1,0,0]
	ds_read_b128 v[84:87], v64 offset:6048
	s_waitcnt lgkmcnt(9)
	v_fma_f32 v114, -v88, v20, v114
	v_add_f32_e32 v114, v114, v115
	v_add_f32_e32 v21, v174, v114
	ds_read_b128 v[88:91], v64 offset:6320
	s_waitcnt lgkmcnt(9)
	v_pk_mul_f32 v[108:109], v[92:93], v[0:1] neg_lo:[1,0] neg_hi:[1,0]
	v_pk_fma_f32 v[108:109], v[94:95], v[2:3], v[108:109] neg_lo:[1,0,0] neg_hi:[1,0,0]
	ds_read_b128 v[92:95], v64 offset:6064
	s_waitcnt lgkmcnt(9)
	v_pk_mul_f32 v[110:111], v[96:97], v[0:1] neg_lo:[1,0] neg_hi:[1,0]
	v_pk_fma_f32 v[110:111], v[98:99], v[2:3], v[110:111] neg_lo:[1,0,0] neg_hi:[1,0,0]
	ds_read_b128 v[96:99], v64 offset:6336
	s_waitcnt lgkmcnt(9)
	v_pk_fma_f32 v[108:109], v[100:101], v[4:5], v[108:109] neg_lo:[1,0,0] neg_hi:[1,0,0]
	v_pk_fma_f32 v[108:109], v[102:103], v[6:7], v[108:109] neg_lo:[1,0,0] neg_hi:[1,0,0]
	ds_read_b128 v[100:103], v64 offset:6528
	s_waitcnt lgkmcnt(9)
	v_pk_fma_f32 v[110:111], v[104:105], v[4:5], v[110:111] neg_lo:[1,0,0] neg_hi:[1,0,0]
	v_pk_fma_f32 v[110:111], v[106:107], v[6:7], v[110:111] neg_lo:[1,0,0] neg_hi:[1,0,0]
	ds_read_b128 v[104:107], v64 offset:6800
	s_waitcnt lgkmcnt(9)
	v_pk_fma_f32 v[108:109], v[68:69], v[8:9], v[108:109] neg_lo:[1,0,0] neg_hi:[1,0,0]
	v_pk_fma_f32 v[108:109], v[70:71], v[10:11], v[108:109] neg_lo:[1,0,0] neg_hi:[1,0,0]
	ds_read_b128 v[68:71], v64 offset:6544
	s_waitcnt lgkmcnt(9)
	v_pk_fma_f32 v[110:111], v[72:73], v[8:9], v[110:111] neg_lo:[1,0,0] neg_hi:[1,0,0]
	v_pk_fma_f32 v[110:111], v[74:75], v[10:11], v[110:111] neg_lo:[1,0,0] neg_hi:[1,0,0]
	ds_read_b128 v[72:75], v64 offset:6816
	s_waitcnt lgkmcnt(9)
	v_pk_fma_f32 v[108:109], v[76:77], v[12:13], v[108:109] neg_lo:[1,0,0] neg_hi:[1,0,0]
	v_pk_fma_f32 v[108:109], v[78:79], v[14:15], v[108:109] neg_lo:[1,0,0] neg_hi:[1,0,0]
	ds_read_b128 v[76:79], v64 offset:6560
	s_waitcnt lgkmcnt(9)
	v_pk_fma_f32 v[110:111], v[80:81], v[12:13], v[110:111] neg_lo:[1,0,0] neg_hi:[1,0,0]
	v_pk_fma_f32 v[110:111], v[82:83], v[14:15], v[110:111] neg_lo:[1,0,0] neg_hi:[1,0,0]
	ds_read_b128 v[80:83], v64 offset:6832
	s_waitcnt lgkmcnt(9)
	v_pk_fma_f32 v[108:109], v[84:85], v[16:17], v[108:109] neg_lo:[1,0,0] neg_hi:[1,0,0]
	v_pk_fma_f32 v[108:109], v[86:87], v[18:19], v[108:109] neg_lo:[1,0,0] neg_hi:[1,0,0]
	ds_read_b128 v[84:87], v64 offset:6576
	s_waitcnt lgkmcnt(9)
	v_pk_fma_f32 v[110:111], v[88:89], v[16:17], v[110:111] neg_lo:[1,0,0] neg_hi:[1,0,0]
	v_pk_fma_f32 v[110:111], v[90:91], v[18:19], v[110:111] neg_lo:[1,0,0] neg_hi:[1,0,0]
	ds_read_b128 v[88:91], v64 offset:6848
	s_waitcnt lgkmcnt(9)
	v_pk_fma_f32 v[108:109], v[92:93], v[20:21], v[108:109] neg_lo:[1,0,0] neg_hi:[1,0,0]
	v_add_f32_e32 v108, v108, v109
	v_add_f32_e32 v22, v175, v108
	ds_read_b128 v[92:95], v64 offset:6592
	s_waitcnt lgkmcnt(9)
	v_pk_fma_f32 v[110:111], v[96:97], v[20:21], v[110:111] neg_lo:[1,0,0] neg_hi:[1,0,0]
	v_fma_f32 v110, -v98, v22, v110
	v_add_f32_e32 v110, v110, v111
	v_add_f32_e32 v23, v176, v110
	ds_read_b128 v[96:99], v64 offset:6864
	s_waitcnt lgkmcnt(9)
	v_pk_mul_f32 v[112:113], v[100:101], v[0:1] neg_lo:[1,0] neg_hi:[1,0]
	v_pk_fma_f32 v[112:113], v[102:103], v[2:3], v[112:113] neg_lo:[1,0,0] neg_hi:[1,0,0]
	ds_read_b128 v[100:103], v64 offset:6608
	s_waitcnt lgkmcnt(9)
	v_pk_mul_f32 v[114:115], v[104:105], v[0:1] neg_lo:[1,0] neg_hi:[1,0]
	v_pk_fma_f32 v[114:115], v[106:107], v[2:3], v[114:115] neg_lo:[1,0,0] neg_hi:[1,0,0]
	ds_read_b128 v[104:107], v64 offset:6880
	s_waitcnt lgkmcnt(9)
	v_pk_fma_f32 v[112:113], v[68:69], v[4:5], v[112:113] neg_lo:[1,0,0] neg_hi:[1,0,0]
	v_pk_fma_f32 v[112:113], v[70:71], v[6:7], v[112:113] neg_lo:[1,0,0] neg_hi:[1,0,0]
	ds_read_b128 v[68:71], v64 offset:6896
	s_waitcnt lgkmcnt(9)
	v_pk_fma_f32 v[114:115], v[72:73], v[4:5], v[114:115] neg_lo:[1,0,0] neg_hi:[1,0,0]
	v_pk_fma_f32 v[114:115], v[74:75], v[6:7], v[114:115] neg_lo:[1,0,0] neg_hi:[1,0,0]
	ds_read_b128 v[72:75], v64 offset:7072
	s_waitcnt lgkmcnt(9)
	v_pk_fma_f32 v[112:113], v[76:77], v[8:9], v[112:113] neg_lo:[1,0,0] neg_hi:[1,0,0]
	v_pk_fma_f32 v[112:113], v[78:79], v[10:11], v[112:113] neg_lo:[1,0,0] neg_hi:[1,0,0]
	ds_read_b128 v[76:79], v64 offset:7344
	s_waitcnt lgkmcnt(9)
	v_pk_fma_f32 v[114:115], v[80:81], v[8:9], v[114:115] neg_lo:[1,0,0] neg_hi:[1,0,0]
	v_pk_fma_f32 v[114:115], v[82:83], v[10:11], v[114:115] neg_lo:[1,0,0] neg_hi:[1,0,0]
	ds_read_b128 v[80:83], v64 offset:7088
	s_waitcnt lgkmcnt(9)
	v_pk_fma_f32 v[112:113], v[84:85], v[12:13], v[112:113] neg_lo:[1,0,0] neg_hi:[1,0,0]
	v_pk_fma_f32 v[112:113], v[86:87], v[14:15], v[112:113] neg_lo:[1,0,0] neg_hi:[1,0,0]
	ds_read_b128 v[84:87], v64 offset:7360
	s_waitcnt lgkmcnt(9)
	v_pk_fma_f32 v[114:115], v[88:89], v[12:13], v[114:115] neg_lo:[1,0,0] neg_hi:[1,0,0]
	v_pk_fma_f32 v[114:115], v[90:91], v[14:15], v[114:115] neg_lo:[1,0,0] neg_hi:[1,0,0]
	ds_read_b128 v[88:91], v64 offset:7104
	s_waitcnt lgkmcnt(9)
	v_pk_fma_f32 v[112:113], v[92:93], v[16:17], v[112:113] neg_lo:[1,0,0] neg_hi:[1,0,0]
	v_pk_fma_f32 v[112:113], v[94:95], v[18:19], v[112:113] neg_lo:[1,0,0] neg_hi:[1,0,0]
	ds_read_b128 v[92:95], v64 offset:7376
	s_waitcnt lgkmcnt(9)
	v_pk_fma_f32 v[114:115], v[96:97], v[16:17], v[114:115] neg_lo:[1,0,0] neg_hi:[1,0,0]
	v_pk_fma_f32 v[114:115], v[98:99], v[18:19], v[114:115] neg_lo:[1,0,0] neg_hi:[1,0,0]
	ds_read_b128 v[96:99], v64 offset:7120
	s_waitcnt lgkmcnt(9)
	v_pk_fma_f32 v[112:113], v[100:101], v[20:21], v[112:113] neg_lo:[1,0,0] neg_hi:[1,0,0]
	v_pk_fma_f32 v[112:113], v[102:103], v[22:23], v[112:113] neg_lo:[1,0,0] neg_hi:[1,0,0]
	v_add_f32_e32 v112, v112, v113
	v_add_f32_e32 v24, v177, v112
	ds_read_b128 v[100:103], v64 offset:7392
	s_waitcnt lgkmcnt(9)
	v_pk_fma_f32 v[114:115], v[104:105], v[20:21], v[114:115] neg_lo:[1,0,0] neg_hi:[1,0,0]
	v_pk_fma_f32 v[114:115], v[106:107], v[22:23], v[114:115] neg_lo:[1,0,0] neg_hi:[1,0,0]
	ds_read_b128 v[104:107], v64 offset:7136
	s_waitcnt lgkmcnt(9)
	v_fma_f32 v114, -v68, v24, v114
	v_add_f32_e32 v114, v114, v115
	v_add_f32_e32 v25, v178, v114
	ds_read_b128 v[68:71], v64 offset:7408
	s_waitcnt lgkmcnt(9)
	v_pk_mul_f32 v[108:109], v[72:73], v[0:1] neg_lo:[1,0] neg_hi:[1,0]
	v_pk_fma_f32 v[108:109], v[74:75], v[2:3], v[108:109] neg_lo:[1,0,0] neg_hi:[1,0,0]
	ds_read_b128 v[72:75], v64 offset:7152
	s_waitcnt lgkmcnt(9)
	v_pk_mul_f32 v[110:111], v[76:77], v[0:1] neg_lo:[1,0] neg_hi:[1,0]
	v_pk_fma_f32 v[110:111], v[78:79], v[2:3], v[110:111] neg_lo:[1,0,0] neg_hi:[1,0,0]
	ds_read_b128 v[76:79], v64 offset:7424
	s_waitcnt lgkmcnt(9)
	v_pk_fma_f32 v[108:109], v[80:81], v[4:5], v[108:109] neg_lo:[1,0,0] neg_hi:[1,0,0]
	v_pk_fma_f32 v[108:109], v[82:83], v[6:7], v[108:109] neg_lo:[1,0,0] neg_hi:[1,0,0]
	ds_read_b128 v[80:83], v64 offset:7168
	s_waitcnt lgkmcnt(9)
	v_pk_fma_f32 v[110:111], v[84:85], v[4:5], v[110:111] neg_lo:[1,0,0] neg_hi:[1,0,0]
	v_pk_fma_f32 v[110:111], v[86:87], v[6:7], v[110:111] neg_lo:[1,0,0] neg_hi:[1,0,0]
	ds_read_b128 v[84:87], v64 offset:7440
	s_waitcnt lgkmcnt(9)
	v_pk_fma_f32 v[108:109], v[88:89], v[8:9], v[108:109] neg_lo:[1,0,0] neg_hi:[1,0,0]
	v_pk_fma_f32 v[108:109], v[90:91], v[10:11], v[108:109] neg_lo:[1,0,0] neg_hi:[1,0,0]
	ds_read_b128 v[88:91], v64 offset:7616
	s_waitcnt lgkmcnt(9)
	v_pk_fma_f32 v[110:111], v[92:93], v[8:9], v[110:111] neg_lo:[1,0,0] neg_hi:[1,0,0]
	v_pk_fma_f32 v[110:111], v[94:95], v[10:11], v[110:111] neg_lo:[1,0,0] neg_hi:[1,0,0]
	ds_read_b128 v[92:95], v64 offset:7888
	s_waitcnt lgkmcnt(9)
	v_pk_fma_f32 v[108:109], v[96:97], v[12:13], v[108:109] neg_lo:[1,0,0] neg_hi:[1,0,0]
	v_pk_fma_f32 v[108:109], v[98:99], v[14:15], v[108:109] neg_lo:[1,0,0] neg_hi:[1,0,0]
	ds_read_b128 v[96:99], v64 offset:7632
	s_waitcnt lgkmcnt(9)
	v_pk_fma_f32 v[110:111], v[100:101], v[12:13], v[110:111] neg_lo:[1,0,0] neg_hi:[1,0,0]
	v_pk_fma_f32 v[110:111], v[102:103], v[14:15], v[110:111] neg_lo:[1,0,0] neg_hi:[1,0,0]
	ds_read_b128 v[100:103], v64 offset:7904
	s_waitcnt lgkmcnt(9)
	v_pk_fma_f32 v[108:109], v[104:105], v[16:17], v[108:109] neg_lo:[1,0,0] neg_hi:[1,0,0]
	v_pk_fma_f32 v[108:109], v[106:107], v[18:19], v[108:109] neg_lo:[1,0,0] neg_hi:[1,0,0]
	ds_read_b128 v[104:107], v64 offset:7648
	s_waitcnt lgkmcnt(9)
	v_pk_fma_f32 v[110:111], v[68:69], v[16:17], v[110:111] neg_lo:[1,0,0] neg_hi:[1,0,0]
	v_pk_fma_f32 v[110:111], v[70:71], v[18:19], v[110:111] neg_lo:[1,0,0] neg_hi:[1,0,0]
	ds_read_b128 v[68:71], v64 offset:7920
	s_waitcnt lgkmcnt(9)
	v_pk_fma_f32 v[108:109], v[72:73], v[20:21], v[108:109] neg_lo:[1,0,0] neg_hi:[1,0,0]
	v_pk_fma_f32 v[108:109], v[74:75], v[22:23], v[108:109] neg_lo:[1,0,0] neg_hi:[1,0,0]
	ds_read_b128 v[72:75], v64 offset:7664
	s_waitcnt lgkmcnt(9)
	v_pk_fma_f32 v[110:111], v[76:77], v[20:21], v[110:111] neg_lo:[1,0,0] neg_hi:[1,0,0]
	v_pk_fma_f32 v[110:111], v[78:79], v[22:23], v[110:111] neg_lo:[1,0,0] neg_hi:[1,0,0]
	ds_read_b128 v[76:79], v64 offset:7936
	s_waitcnt lgkmcnt(9)
	v_pk_fma_f32 v[108:109], v[80:81], v[24:25], v[108:109] neg_lo:[1,0,0] neg_hi:[1,0,0]
	v_add_f32_e32 v108, v108, v109
	v_add_f32_e32 v26, v179, v108
	ds_read_b128 v[80:83], v64 offset:7680
	s_waitcnt lgkmcnt(9)
	v_pk_fma_f32 v[110:111], v[84:85], v[24:25], v[110:111] neg_lo:[1,0,0] neg_hi:[1,0,0]
	v_fma_f32 v110, -v86, v26, v110
	v_add_f32_e32 v110, v110, v111
	v_add_f32_e32 v27, v180, v110
	ds_read_b128 v[84:87], v64 offset:7952
	s_waitcnt lgkmcnt(9)
	v_pk_mul_f32 v[112:113], v[88:89], v[0:1] neg_lo:[1,0] neg_hi:[1,0]
	v_pk_fma_f32 v[112:113], v[90:91], v[2:3], v[112:113] neg_lo:[1,0,0] neg_hi:[1,0,0]
	ds_read_b128 v[88:91], v64 offset:7696
	s_waitcnt lgkmcnt(9)
	v_pk_mul_f32 v[114:115], v[92:93], v[0:1] neg_lo:[1,0] neg_hi:[1,0]
	v_pk_fma_f32 v[114:115], v[94:95], v[2:3], v[114:115] neg_lo:[1,0,0] neg_hi:[1,0,0]
	ds_read_b128 v[92:95], v64 offset:7968
	s_waitcnt lgkmcnt(9)
	v_pk_fma_f32 v[112:113], v[96:97], v[4:5], v[112:113] neg_lo:[1,0,0] neg_hi:[1,0,0]
	v_pk_fma_f32 v[112:113], v[98:99], v[6:7], v[112:113] neg_lo:[1,0,0] neg_hi:[1,0,0]
	ds_read_b128 v[96:99], v64 offset:7712
	s_waitcnt lgkmcnt(9)
	v_pk_fma_f32 v[114:115], v[100:101], v[4:5], v[114:115] neg_lo:[1,0,0] neg_hi:[1,0,0]
	v_pk_fma_f32 v[114:115], v[102:103], v[6:7], v[114:115] neg_lo:[1,0,0] neg_hi:[1,0,0]
	ds_read_b128 v[100:103], v64 offset:7984
	s_waitcnt lgkmcnt(9)
	v_pk_fma_f32 v[112:113], v[104:105], v[8:9], v[112:113] neg_lo:[1,0,0] neg_hi:[1,0,0]
	v_pk_fma_f32 v[112:113], v[106:107], v[10:11], v[112:113] neg_lo:[1,0,0] neg_hi:[1,0,0]
	ds_read_b128 v[104:107], v64 offset:8000
	s_waitcnt lgkmcnt(9)
	v_pk_fma_f32 v[114:115], v[68:69], v[8:9], v[114:115] neg_lo:[1,0,0] neg_hi:[1,0,0]
	v_pk_fma_f32 v[114:115], v[70:71], v[10:11], v[114:115] neg_lo:[1,0,0] neg_hi:[1,0,0]
	ds_read_b128 v[68:71], v64 offset:8160
	s_waitcnt lgkmcnt(9)
	v_pk_fma_f32 v[112:113], v[72:73], v[12:13], v[112:113] neg_lo:[1,0,0] neg_hi:[1,0,0]
	v_pk_fma_f32 v[112:113], v[74:75], v[14:15], v[112:113] neg_lo:[1,0,0] neg_hi:[1,0,0]
	ds_read_b128 v[72:75], v64 offset:8432
	s_waitcnt lgkmcnt(9)
	v_pk_fma_f32 v[114:115], v[76:77], v[12:13], v[114:115] neg_lo:[1,0,0] neg_hi:[1,0,0]
	v_pk_fma_f32 v[114:115], v[78:79], v[14:15], v[114:115] neg_lo:[1,0,0] neg_hi:[1,0,0]
	ds_read_b128 v[76:79], v64 offset:8176
	s_waitcnt lgkmcnt(9)
	v_pk_fma_f32 v[112:113], v[80:81], v[16:17], v[112:113] neg_lo:[1,0,0] neg_hi:[1,0,0]
	v_pk_fma_f32 v[112:113], v[82:83], v[18:19], v[112:113] neg_lo:[1,0,0] neg_hi:[1,0,0]
	ds_read_b128 v[80:83], v64 offset:8448
	s_waitcnt lgkmcnt(9)
	v_pk_fma_f32 v[114:115], v[84:85], v[16:17], v[114:115] neg_lo:[1,0,0] neg_hi:[1,0,0]
	v_pk_fma_f32 v[114:115], v[86:87], v[18:19], v[114:115] neg_lo:[1,0,0] neg_hi:[1,0,0]
	ds_read_b128 v[84:87], v64 offset:8192
	s_waitcnt lgkmcnt(9)
	v_pk_fma_f32 v[112:113], v[88:89], v[20:21], v[112:113] neg_lo:[1,0,0] neg_hi:[1,0,0]
	v_pk_fma_f32 v[112:113], v[90:91], v[22:23], v[112:113] neg_lo:[1,0,0] neg_hi:[1,0,0]
	ds_read_b128 v[88:91], v64 offset:8464
	s_waitcnt lgkmcnt(9)
	v_pk_fma_f32 v[114:115], v[92:93], v[20:21], v[114:115] neg_lo:[1,0,0] neg_hi:[1,0,0]
	v_pk_fma_f32 v[114:115], v[94:95], v[22:23], v[114:115] neg_lo:[1,0,0] neg_hi:[1,0,0]
	ds_read_b128 v[92:95], v64 offset:8208
	s_waitcnt lgkmcnt(9)
	v_pk_fma_f32 v[112:113], v[96:97], v[24:25], v[112:113] neg_lo:[1,0,0] neg_hi:[1,0,0]
	v_pk_fma_f32 v[112:113], v[98:99], v[26:27], v[112:113] neg_lo:[1,0,0] neg_hi:[1,0,0]
	v_add_f32_e32 v112, v112, v113
	v_add_f32_e32 v28, v181, v112
	ds_read_b128 v[96:99], v64 offset:8480
	s_waitcnt lgkmcnt(9)
	v_pk_fma_f32 v[114:115], v[100:101], v[24:25], v[114:115] neg_lo:[1,0,0] neg_hi:[1,0,0]
	v_pk_fma_f32 v[114:115], v[102:103], v[26:27], v[114:115] neg_lo:[1,0,0] neg_hi:[1,0,0]
	ds_read_b128 v[100:103], v64 offset:8224
	s_waitcnt lgkmcnt(9)
	v_fma_f32 v114, -v104, v28, v114
	v_add_f32_e32 v114, v114, v115
	v_add_f32_e32 v29, v182, v114
	ds_read_b128 v[104:107], v64 offset:8496
	s_waitcnt lgkmcnt(9)
	v_pk_mul_f32 v[108:109], v[68:69], v[0:1] neg_lo:[1,0] neg_hi:[1,0]
	v_pk_fma_f32 v[108:109], v[70:71], v[2:3], v[108:109] neg_lo:[1,0,0] neg_hi:[1,0,0]
	ds_read_b128 v[68:71], v64 offset:8240
	s_waitcnt lgkmcnt(9)
	v_pk_mul_f32 v[110:111], v[72:73], v[0:1] neg_lo:[1,0] neg_hi:[1,0]
	v_pk_fma_f32 v[110:111], v[74:75], v[2:3], v[110:111] neg_lo:[1,0,0] neg_hi:[1,0,0]
	ds_read_b128 v[72:75], v64 offset:8512
	s_waitcnt lgkmcnt(9)
	v_pk_fma_f32 v[108:109], v[76:77], v[4:5], v[108:109] neg_lo:[1,0,0] neg_hi:[1,0,0]
	v_pk_fma_f32 v[108:109], v[78:79], v[6:7], v[108:109] neg_lo:[1,0,0] neg_hi:[1,0,0]
	ds_read_b128 v[76:79], v64 offset:8256
	s_waitcnt lgkmcnt(9)
	v_pk_fma_f32 v[110:111], v[80:81], v[4:5], v[110:111] neg_lo:[1,0,0] neg_hi:[1,0,0]
	v_pk_fma_f32 v[110:111], v[82:83], v[6:7], v[110:111] neg_lo:[1,0,0] neg_hi:[1,0,0]
	ds_read_b128 v[80:83], v64 offset:8528
	s_waitcnt lgkmcnt(9)
	v_pk_fma_f32 v[108:109], v[84:85], v[8:9], v[108:109] neg_lo:[1,0,0] neg_hi:[1,0,0]
	v_pk_fma_f32 v[108:109], v[86:87], v[10:11], v[108:109] neg_lo:[1,0,0] neg_hi:[1,0,0]
	ds_read_b128 v[84:87], v64 offset:8272
	s_waitcnt lgkmcnt(9)
	v_pk_fma_f32 v[110:111], v[88:89], v[8:9], v[110:111] neg_lo:[1,0,0] neg_hi:[1,0,0]
	v_pk_fma_f32 v[110:111], v[90:91], v[10:11], v[110:111] neg_lo:[1,0,0] neg_hi:[1,0,0]
	ds_read_b128 v[88:91], v64 offset:8544
	s_waitcnt lgkmcnt(9)
	v_pk_fma_f32 v[108:109], v[92:93], v[12:13], v[108:109] neg_lo:[1,0,0] neg_hi:[1,0,0]
	v_pk_fma_f32 v[108:109], v[94:95], v[14:15], v[108:109] neg_lo:[1,0,0] neg_hi:[1,0,0]
	ds_read_b128 v[92:95], v64 offset:8704
	s_waitcnt lgkmcnt(9)
	v_pk_fma_f32 v[110:111], v[96:97], v[12:13], v[110:111] neg_lo:[1,0,0] neg_hi:[1,0,0]
	v_pk_fma_f32 v[110:111], v[98:99], v[14:15], v[110:111] neg_lo:[1,0,0] neg_hi:[1,0,0]
	ds_read_b128 v[96:99], v64 offset:8976
	s_waitcnt lgkmcnt(9)
	v_pk_fma_f32 v[108:109], v[100:101], v[16:17], v[108:109] neg_lo:[1,0,0] neg_hi:[1,0,0]
	v_pk_fma_f32 v[108:109], v[102:103], v[18:19], v[108:109] neg_lo:[1,0,0] neg_hi:[1,0,0]
	ds_read_b128 v[100:103], v64 offset:8720
	s_waitcnt lgkmcnt(9)
	v_pk_fma_f32 v[110:111], v[104:105], v[16:17], v[110:111] neg_lo:[1,0,0] neg_hi:[1,0,0]
	v_pk_fma_f32 v[110:111], v[106:107], v[18:19], v[110:111] neg_lo:[1,0,0] neg_hi:[1,0,0]
	ds_read_b128 v[104:107], v64 offset:8992
	s_waitcnt lgkmcnt(9)
	v_pk_fma_f32 v[108:109], v[68:69], v[20:21], v[108:109] neg_lo:[1,0,0] neg_hi:[1,0,0]
	v_pk_fma_f32 v[108:109], v[70:71], v[22:23], v[108:109] neg_lo:[1,0,0] neg_hi:[1,0,0]
	ds_read_b128 v[68:71], v64 offset:8736
	s_waitcnt lgkmcnt(9)
	v_pk_fma_f32 v[110:111], v[72:73], v[20:21], v[110:111] neg_lo:[1,0,0] neg_hi:[1,0,0]
	v_pk_fma_f32 v[110:111], v[74:75], v[22:23], v[110:111] neg_lo:[1,0,0] neg_hi:[1,0,0]
	ds_read_b128 v[72:75], v64 offset:9008
	s_waitcnt lgkmcnt(9)
	v_pk_fma_f32 v[108:109], v[76:77], v[24:25], v[108:109] neg_lo:[1,0,0] neg_hi:[1,0,0]
	v_pk_fma_f32 v[108:109], v[78:79], v[26:27], v[108:109] neg_lo:[1,0,0] neg_hi:[1,0,0]
	ds_read_b128 v[76:79], v64 offset:8752
	s_waitcnt lgkmcnt(9)
	v_pk_fma_f32 v[110:111], v[80:81], v[24:25], v[110:111] neg_lo:[1,0,0] neg_hi:[1,0,0]
	v_pk_fma_f32 v[110:111], v[82:83], v[26:27], v[110:111] neg_lo:[1,0,0] neg_hi:[1,0,0]
	ds_read_b128 v[80:83], v64 offset:9024
	s_waitcnt lgkmcnt(9)
	v_pk_fma_f32 v[108:109], v[84:85], v[28:29], v[108:109] neg_lo:[1,0,0] neg_hi:[1,0,0]
	v_add_f32_e32 v108, v108, v109
	v_add_f32_e32 v30, v183, v108
	ds_read_b128 v[84:87], v64 offset:8768
	s_waitcnt lgkmcnt(9)
	v_pk_fma_f32 v[110:111], v[88:89], v[28:29], v[110:111] neg_lo:[1,0,0] neg_hi:[1,0,0]
	v_fma_f32 v110, -v90, v30, v110
	v_add_f32_e32 v110, v110, v111
	v_add_f32_e32 v31, v184, v110
	ds_read_b128 v[88:91], v64 offset:9040
	s_waitcnt lgkmcnt(9)
	v_pk_mul_f32 v[112:113], v[92:93], v[0:1] neg_lo:[1,0] neg_hi:[1,0]
	v_pk_fma_f32 v[112:113], v[94:95], v[2:3], v[112:113] neg_lo:[1,0,0] neg_hi:[1,0,0]
	ds_read_b128 v[92:95], v64 offset:8784
	s_waitcnt lgkmcnt(9)
	v_pk_mul_f32 v[114:115], v[96:97], v[0:1] neg_lo:[1,0] neg_hi:[1,0]
	v_pk_fma_f32 v[114:115], v[98:99], v[2:3], v[114:115] neg_lo:[1,0,0] neg_hi:[1,0,0]
	ds_read_b128 v[96:99], v64 offset:9056
	s_waitcnt lgkmcnt(9)
	v_pk_fma_f32 v[112:113], v[100:101], v[4:5], v[112:113] neg_lo:[1,0,0] neg_hi:[1,0,0]
	v_pk_fma_f32 v[112:113], v[102:103], v[6:7], v[112:113] neg_lo:[1,0,0] neg_hi:[1,0,0]
	ds_read_b128 v[100:103], v64 offset:8800
	s_waitcnt lgkmcnt(9)
	v_pk_fma_f32 v[114:115], v[104:105], v[4:5], v[114:115] neg_lo:[1,0,0] neg_hi:[1,0,0]
	v_pk_fma_f32 v[114:115], v[106:107], v[6:7], v[114:115] neg_lo:[1,0,0] neg_hi:[1,0,0]
	ds_read_b128 v[104:107], v64 offset:9072
	s_waitcnt lgkmcnt(9)
	v_pk_fma_f32 v[112:113], v[68:69], v[8:9], v[112:113] neg_lo:[1,0,0] neg_hi:[1,0,0]
	v_pk_fma_f32 v[112:113], v[70:71], v[10:11], v[112:113] neg_lo:[1,0,0] neg_hi:[1,0,0]
	ds_read_b128 v[68:71], v64 offset:8816
	s_waitcnt lgkmcnt(9)
	v_pk_fma_f32 v[114:115], v[72:73], v[8:9], v[114:115] neg_lo:[1,0,0] neg_hi:[1,0,0]
	v_pk_fma_f32 v[114:115], v[74:75], v[10:11], v[114:115] neg_lo:[1,0,0] neg_hi:[1,0,0]
	ds_read_b128 v[72:75], v64 offset:9088
	s_waitcnt lgkmcnt(9)
	v_pk_fma_f32 v[112:113], v[76:77], v[12:13], v[112:113] neg_lo:[1,0,0] neg_hi:[1,0,0]
	v_pk_fma_f32 v[112:113], v[78:79], v[14:15], v[112:113] neg_lo:[1,0,0] neg_hi:[1,0,0]
	ds_read_b128 v[76:79], v64 offset:9104
	s_waitcnt lgkmcnt(9)
	v_pk_fma_f32 v[114:115], v[80:81], v[12:13], v[114:115] neg_lo:[1,0,0] neg_hi:[1,0,0]
	v_pk_fma_f32 v[114:115], v[82:83], v[14:15], v[114:115] neg_lo:[1,0,0] neg_hi:[1,0,0]
	ds_read_b128 v[80:83], v64 offset:9248
	s_waitcnt lgkmcnt(9)
	v_pk_fma_f32 v[112:113], v[84:85], v[16:17], v[112:113] neg_lo:[1,0,0] neg_hi:[1,0,0]
	v_pk_fma_f32 v[112:113], v[86:87], v[18:19], v[112:113] neg_lo:[1,0,0] neg_hi:[1,0,0]
	ds_read_b128 v[84:87], v64 offset:9520
	s_waitcnt lgkmcnt(9)
	v_pk_fma_f32 v[114:115], v[88:89], v[16:17], v[114:115] neg_lo:[1,0,0] neg_hi:[1,0,0]
	v_pk_fma_f32 v[114:115], v[90:91], v[18:19], v[114:115] neg_lo:[1,0,0] neg_hi:[1,0,0]
	ds_read_b128 v[88:91], v64 offset:9264
	s_waitcnt lgkmcnt(9)
	v_pk_fma_f32 v[112:113], v[92:93], v[20:21], v[112:113] neg_lo:[1,0,0] neg_hi:[1,0,0]
	v_pk_fma_f32 v[112:113], v[94:95], v[22:23], v[112:113] neg_lo:[1,0,0] neg_hi:[1,0,0]
	ds_read_b128 v[92:95], v64 offset:9536
	s_waitcnt lgkmcnt(9)
	v_pk_fma_f32 v[114:115], v[96:97], v[20:21], v[114:115] neg_lo:[1,0,0] neg_hi:[1,0,0]
	v_pk_fma_f32 v[114:115], v[98:99], v[22:23], v[114:115] neg_lo:[1,0,0] neg_hi:[1,0,0]
	ds_read_b128 v[96:99], v64 offset:9280
	s_waitcnt lgkmcnt(9)
	v_pk_fma_f32 v[112:113], v[100:101], v[24:25], v[112:113] neg_lo:[1,0,0] neg_hi:[1,0,0]
	v_pk_fma_f32 v[112:113], v[102:103], v[26:27], v[112:113] neg_lo:[1,0,0] neg_hi:[1,0,0]
	ds_read_b128 v[100:103], v64 offset:9552
	s_waitcnt lgkmcnt(9)
	v_pk_fma_f32 v[114:115], v[104:105], v[24:25], v[114:115] neg_lo:[1,0,0] neg_hi:[1,0,0]
	v_pk_fma_f32 v[114:115], v[106:107], v[26:27], v[114:115] neg_lo:[1,0,0] neg_hi:[1,0,0]
	ds_read_b128 v[104:107], v64 offset:9296
	s_waitcnt lgkmcnt(9)
	v_pk_fma_f32 v[112:113], v[68:69], v[28:29], v[112:113] neg_lo:[1,0,0] neg_hi:[1,0,0]
	v_pk_fma_f32 v[112:113], v[70:71], v[30:31], v[112:113] neg_lo:[1,0,0] neg_hi:[1,0,0]
	v_add_f32_e32 v112, v112, v113
	v_add_f32_e32 v32, v185, v112
	ds_read_b128 v[68:71], v64 offset:9568
	s_waitcnt lgkmcnt(9)
	v_pk_fma_f32 v[114:115], v[72:73], v[28:29], v[114:115] neg_lo:[1,0,0] neg_hi:[1,0,0]
	v_pk_fma_f32 v[114:115], v[74:75], v[30:31], v[114:115] neg_lo:[1,0,0] neg_hi:[1,0,0]
	ds_read_b128 v[72:75], v64 offset:9312
	s_waitcnt lgkmcnt(9)
	v_fma_f32 v114, -v76, v32, v114
	v_add_f32_e32 v114, v114, v115
	v_add_f32_e32 v33, v186, v114
	ds_read_b128 v[76:79], v64 offset:9584
	s_waitcnt lgkmcnt(9)
	v_pk_mul_f32 v[108:109], v[80:81], v[0:1] neg_lo:[1,0] neg_hi:[1,0]
	v_pk_fma_f32 v[108:109], v[82:83], v[2:3], v[108:109] neg_lo:[1,0,0] neg_hi:[1,0,0]
	ds_read_b128 v[80:83], v64 offset:9328
	s_waitcnt lgkmcnt(9)
	v_pk_mul_f32 v[110:111], v[84:85], v[0:1] neg_lo:[1,0] neg_hi:[1,0]
	v_pk_fma_f32 v[110:111], v[86:87], v[2:3], v[110:111] neg_lo:[1,0,0] neg_hi:[1,0,0]
	ds_read_b128 v[84:87], v64 offset:9600
	s_waitcnt lgkmcnt(9)
	v_pk_fma_f32 v[108:109], v[88:89], v[4:5], v[108:109] neg_lo:[1,0,0] neg_hi:[1,0,0]
	v_pk_fma_f32 v[108:109], v[90:91], v[6:7], v[108:109] neg_lo:[1,0,0] neg_hi:[1,0,0]
	ds_read_b128 v[88:91], v64 offset:9344
	s_waitcnt lgkmcnt(9)
	v_pk_fma_f32 v[110:111], v[92:93], v[4:5], v[110:111] neg_lo:[1,0,0] neg_hi:[1,0,0]
	v_pk_fma_f32 v[110:111], v[94:95], v[6:7], v[110:111] neg_lo:[1,0,0] neg_hi:[1,0,0]
	ds_read_b128 v[92:95], v64 offset:9616
	s_waitcnt lgkmcnt(9)
	v_pk_fma_f32 v[108:109], v[96:97], v[8:9], v[108:109] neg_lo:[1,0,0] neg_hi:[1,0,0]
	v_pk_fma_f32 v[108:109], v[98:99], v[10:11], v[108:109] neg_lo:[1,0,0] neg_hi:[1,0,0]
	ds_read_b128 v[96:99], v64 offset:9360
	s_waitcnt lgkmcnt(9)
	v_pk_fma_f32 v[110:111], v[100:101], v[8:9], v[110:111] neg_lo:[1,0,0] neg_hi:[1,0,0]
	v_pk_fma_f32 v[110:111], v[102:103], v[10:11], v[110:111] neg_lo:[1,0,0] neg_hi:[1,0,0]
	ds_read_b128 v[100:103], v64 offset:9632
	s_waitcnt lgkmcnt(9)
	v_pk_fma_f32 v[108:109], v[104:105], v[12:13], v[108:109] neg_lo:[1,0,0] neg_hi:[1,0,0]
	v_pk_fma_f32 v[108:109], v[106:107], v[14:15], v[108:109] neg_lo:[1,0,0] neg_hi:[1,0,0]
	ds_read_b128 v[104:107], v64 offset:9376
	s_waitcnt lgkmcnt(9)
	v_pk_fma_f32 v[110:111], v[68:69], v[12:13], v[110:111] neg_lo:[1,0,0] neg_hi:[1,0,0]
	v_pk_fma_f32 v[110:111], v[70:71], v[14:15], v[110:111] neg_lo:[1,0,0] neg_hi:[1,0,0]
	ds_read_b128 v[68:71], v64 offset:9648
	s_waitcnt lgkmcnt(9)
	v_pk_fma_f32 v[108:109], v[72:73], v[16:17], v[108:109] neg_lo:[1,0,0] neg_hi:[1,0,0]
	v_pk_fma_f32 v[108:109], v[74:75], v[18:19], v[108:109] neg_lo:[1,0,0] neg_hi:[1,0,0]
	ds_read_b128 v[72:75], v64 offset:9792
	s_waitcnt lgkmcnt(9)
	v_pk_fma_f32 v[110:111], v[76:77], v[16:17], v[110:111] neg_lo:[1,0,0] neg_hi:[1,0,0]
	v_pk_fma_f32 v[110:111], v[78:79], v[18:19], v[110:111] neg_lo:[1,0,0] neg_hi:[1,0,0]
	ds_read_b128 v[76:79], v64 offset:10064
	s_waitcnt lgkmcnt(9)
	v_pk_fma_f32 v[108:109], v[80:81], v[20:21], v[108:109] neg_lo:[1,0,0] neg_hi:[1,0,0]
	v_pk_fma_f32 v[108:109], v[82:83], v[22:23], v[108:109] neg_lo:[1,0,0] neg_hi:[1,0,0]
	ds_read_b128 v[80:83], v64 offset:9808
	s_waitcnt lgkmcnt(9)
	v_pk_fma_f32 v[110:111], v[84:85], v[20:21], v[110:111] neg_lo:[1,0,0] neg_hi:[1,0,0]
	v_pk_fma_f32 v[110:111], v[86:87], v[22:23], v[110:111] neg_lo:[1,0,0] neg_hi:[1,0,0]
	ds_read_b128 v[84:87], v64 offset:10080
	s_waitcnt lgkmcnt(9)
	v_pk_fma_f32 v[108:109], v[88:89], v[24:25], v[108:109] neg_lo:[1,0,0] neg_hi:[1,0,0]
	v_pk_fma_f32 v[108:109], v[90:91], v[26:27], v[108:109] neg_lo:[1,0,0] neg_hi:[1,0,0]
	ds_read_b128 v[88:91], v64 offset:9824
	s_waitcnt lgkmcnt(9)
	v_pk_fma_f32 v[110:111], v[92:93], v[24:25], v[110:111] neg_lo:[1,0,0] neg_hi:[1,0,0]
	v_pk_fma_f32 v[110:111], v[94:95], v[26:27], v[110:111] neg_lo:[1,0,0] neg_hi:[1,0,0]
	ds_read_b128 v[92:95], v64 offset:10096
	s_waitcnt lgkmcnt(9)
	v_pk_fma_f32 v[108:109], v[96:97], v[28:29], v[108:109] neg_lo:[1,0,0] neg_hi:[1,0,0]
	v_pk_fma_f32 v[108:109], v[98:99], v[30:31], v[108:109] neg_lo:[1,0,0] neg_hi:[1,0,0]
	ds_read_b128 v[96:99], v64 offset:9840
	s_waitcnt lgkmcnt(9)
	v_pk_fma_f32 v[110:111], v[100:101], v[28:29], v[110:111] neg_lo:[1,0,0] neg_hi:[1,0,0]
	v_pk_fma_f32 v[110:111], v[102:103], v[30:31], v[110:111] neg_lo:[1,0,0] neg_hi:[1,0,0]
	ds_read_b128 v[100:103], v64 offset:10112
	s_waitcnt lgkmcnt(9)
	v_pk_fma_f32 v[108:109], v[104:105], v[32:33], v[108:109] neg_lo:[1,0,0] neg_hi:[1,0,0]
	v_add_f32_e32 v108, v108, v109
	v_add_f32_e32 v34, v187, v108
	ds_read_b128 v[104:107], v64 offset:9856
	s_waitcnt lgkmcnt(9)
	v_pk_fma_f32 v[110:111], v[68:69], v[32:33], v[110:111] neg_lo:[1,0,0] neg_hi:[1,0,0]
	v_fma_f32 v110, -v70, v34, v110
	v_add_f32_e32 v110, v110, v111
	v_add_f32_e32 v35, v188, v110
	ds_read_b128 v[68:71], v64 offset:10128
	s_waitcnt lgkmcnt(9)
	v_pk_mul_f32 v[112:113], v[72:73], v[0:1] neg_lo:[1,0] neg_hi:[1,0]
	v_pk_fma_f32 v[112:113], v[74:75], v[2:3], v[112:113] neg_lo:[1,0,0] neg_hi:[1,0,0]
	ds_read_b128 v[72:75], v64 offset:9872
	s_waitcnt lgkmcnt(9)
	v_pk_mul_f32 v[114:115], v[76:77], v[0:1] neg_lo:[1,0] neg_hi:[1,0]
	v_pk_fma_f32 v[114:115], v[78:79], v[2:3], v[114:115] neg_lo:[1,0,0] neg_hi:[1,0,0]
	ds_read_b128 v[76:79], v64 offset:10144
	s_waitcnt lgkmcnt(9)
	v_pk_fma_f32 v[112:113], v[80:81], v[4:5], v[112:113] neg_lo:[1,0,0] neg_hi:[1,0,0]
	v_pk_fma_f32 v[112:113], v[82:83], v[6:7], v[112:113] neg_lo:[1,0,0] neg_hi:[1,0,0]
	ds_read_b128 v[80:83], v64 offset:9888
	s_waitcnt lgkmcnt(9)
	v_pk_fma_f32 v[114:115], v[84:85], v[4:5], v[114:115] neg_lo:[1,0,0] neg_hi:[1,0,0]
	v_pk_fma_f32 v[114:115], v[86:87], v[6:7], v[114:115] neg_lo:[1,0,0] neg_hi:[1,0,0]
	ds_read_b128 v[84:87], v64 offset:10160
	s_waitcnt lgkmcnt(9)
	v_pk_fma_f32 v[112:113], v[88:89], v[8:9], v[112:113] neg_lo:[1,0,0] neg_hi:[1,0,0]
	v_pk_fma_f32 v[112:113], v[90:91], v[10:11], v[112:113] neg_lo:[1,0,0] neg_hi:[1,0,0]
	ds_read_b128 v[88:91], v64 offset:9904
	s_waitcnt lgkmcnt(9)
	v_pk_fma_f32 v[114:115], v[92:93], v[8:9], v[114:115] neg_lo:[1,0,0] neg_hi:[1,0,0]
	v_pk_fma_f32 v[114:115], v[94:95], v[10:11], v[114:115] neg_lo:[1,0,0] neg_hi:[1,0,0]
	ds_read_b128 v[92:95], v64 offset:10176
	s_waitcnt lgkmcnt(9)
	v_pk_fma_f32 v[112:113], v[96:97], v[12:13], v[112:113] neg_lo:[1,0,0] neg_hi:[1,0,0]
	v_pk_fma_f32 v[112:113], v[98:99], v[14:15], v[112:113] neg_lo:[1,0,0] neg_hi:[1,0,0]
	ds_read_b128 v[96:99], v64 offset:9920
	s_waitcnt lgkmcnt(9)
	v_pk_fma_f32 v[114:115], v[100:101], v[12:13], v[114:115] neg_lo:[1,0,0] neg_hi:[1,0,0]
	v_pk_fma_f32 v[114:115], v[102:103], v[14:15], v[114:115] neg_lo:[1,0,0] neg_hi:[1,0,0]
	ds_read_b128 v[100:103], v64 offset:10192
	s_waitcnt lgkmcnt(9)
	v_pk_fma_f32 v[112:113], v[104:105], v[16:17], v[112:113] neg_lo:[1,0,0] neg_hi:[1,0,0]
	v_pk_fma_f32 v[112:113], v[106:107], v[18:19], v[112:113] neg_lo:[1,0,0] neg_hi:[1,0,0]
	ds_read_b128 v[104:107], v64 offset:10208
	s_waitcnt lgkmcnt(9)
	v_pk_fma_f32 v[114:115], v[68:69], v[16:17], v[114:115] neg_lo:[1,0,0] neg_hi:[1,0,0]
	v_pk_fma_f32 v[114:115], v[70:71], v[18:19], v[114:115] neg_lo:[1,0,0] neg_hi:[1,0,0]
	ds_read_b128 v[68:71], v64 offset:10336
	s_waitcnt lgkmcnt(9)
	v_pk_fma_f32 v[112:113], v[72:73], v[20:21], v[112:113] neg_lo:[1,0,0] neg_hi:[1,0,0]
	v_pk_fma_f32 v[112:113], v[74:75], v[22:23], v[112:113] neg_lo:[1,0,0] neg_hi:[1,0,0]
	ds_read_b128 v[72:75], v64 offset:10608
	s_waitcnt lgkmcnt(9)
	v_pk_fma_f32 v[114:115], v[76:77], v[20:21], v[114:115] neg_lo:[1,0,0] neg_hi:[1,0,0]
	v_pk_fma_f32 v[114:115], v[78:79], v[22:23], v[114:115] neg_lo:[1,0,0] neg_hi:[1,0,0]
	ds_read_b128 v[76:79], v64 offset:10352
	s_waitcnt lgkmcnt(9)
	v_pk_fma_f32 v[112:113], v[80:81], v[24:25], v[112:113] neg_lo:[1,0,0] neg_hi:[1,0,0]
	v_pk_fma_f32 v[112:113], v[82:83], v[26:27], v[112:113] neg_lo:[1,0,0] neg_hi:[1,0,0]
	ds_read_b128 v[80:83], v64 offset:10624
	s_waitcnt lgkmcnt(9)
	v_pk_fma_f32 v[114:115], v[84:85], v[24:25], v[114:115] neg_lo:[1,0,0] neg_hi:[1,0,0]
	v_pk_fma_f32 v[114:115], v[86:87], v[26:27], v[114:115] neg_lo:[1,0,0] neg_hi:[1,0,0]
	ds_read_b128 v[84:87], v64 offset:10368
	s_waitcnt lgkmcnt(9)
	v_pk_fma_f32 v[112:113], v[88:89], v[28:29], v[112:113] neg_lo:[1,0,0] neg_hi:[1,0,0]
	v_pk_fma_f32 v[112:113], v[90:91], v[30:31], v[112:113] neg_lo:[1,0,0] neg_hi:[1,0,0]
	ds_read_b128 v[88:91], v64 offset:10640
	s_waitcnt lgkmcnt(9)
	v_pk_fma_f32 v[114:115], v[92:93], v[28:29], v[114:115] neg_lo:[1,0,0] neg_hi:[1,0,0]
	v_pk_fma_f32 v[114:115], v[94:95], v[30:31], v[114:115] neg_lo:[1,0,0] neg_hi:[1,0,0]
	ds_read_b128 v[92:95], v64 offset:10384
	s_waitcnt lgkmcnt(9)
	v_pk_fma_f32 v[112:113], v[96:97], v[32:33], v[112:113] neg_lo:[1,0,0] neg_hi:[1,0,0]
	v_pk_fma_f32 v[112:113], v[98:99], v[34:35], v[112:113] neg_lo:[1,0,0] neg_hi:[1,0,0]
	v_add_f32_e32 v112, v112, v113
	v_add_f32_e32 v36, v189, v112
	ds_read_b128 v[96:99], v64 offset:10656
	s_waitcnt lgkmcnt(9)
	v_pk_fma_f32 v[114:115], v[100:101], v[32:33], v[114:115] neg_lo:[1,0,0] neg_hi:[1,0,0]
	v_pk_fma_f32 v[114:115], v[102:103], v[34:35], v[114:115] neg_lo:[1,0,0] neg_hi:[1,0,0]
	ds_read_b128 v[100:103], v64 offset:10400
	s_waitcnt lgkmcnt(9)
	v_fma_f32 v114, -v104, v36, v114
	v_add_f32_e32 v114, v114, v115
	v_add_f32_e32 v37, v190, v114
	ds_read_b128 v[104:107], v64 offset:10672
	s_waitcnt lgkmcnt(9)
	v_pk_mul_f32 v[108:109], v[68:69], v[0:1] neg_lo:[1,0] neg_hi:[1,0]
	v_pk_fma_f32 v[108:109], v[70:71], v[2:3], v[108:109] neg_lo:[1,0,0] neg_hi:[1,0,0]
	ds_read_b128 v[68:71], v64 offset:10416
	s_waitcnt lgkmcnt(9)
	v_pk_mul_f32 v[110:111], v[72:73], v[0:1] neg_lo:[1,0] neg_hi:[1,0]
	v_pk_fma_f32 v[110:111], v[74:75], v[2:3], v[110:111] neg_lo:[1,0,0] neg_hi:[1,0,0]
	ds_read_b128 v[72:75], v64 offset:10688
	s_waitcnt lgkmcnt(9)
	v_pk_fma_f32 v[108:109], v[76:77], v[4:5], v[108:109] neg_lo:[1,0,0] neg_hi:[1,0,0]
	v_pk_fma_f32 v[108:109], v[78:79], v[6:7], v[108:109] neg_lo:[1,0,0] neg_hi:[1,0,0]
	ds_read_b128 v[76:79], v64 offset:10432
	s_waitcnt lgkmcnt(9)
	v_pk_fma_f32 v[110:111], v[80:81], v[4:5], v[110:111] neg_lo:[1,0,0] neg_hi:[1,0,0]
	v_pk_fma_f32 v[110:111], v[82:83], v[6:7], v[110:111] neg_lo:[1,0,0] neg_hi:[1,0,0]
	ds_read_b128 v[80:83], v64 offset:10704
	s_waitcnt lgkmcnt(9)
	v_pk_fma_f32 v[108:109], v[84:85], v[8:9], v[108:109] neg_lo:[1,0,0] neg_hi:[1,0,0]
	v_pk_fma_f32 v[108:109], v[86:87], v[10:11], v[108:109] neg_lo:[1,0,0] neg_hi:[1,0,0]
	ds_read_b128 v[84:87], v64 offset:10448
	s_waitcnt lgkmcnt(9)
	v_pk_fma_f32 v[110:111], v[88:89], v[8:9], v[110:111] neg_lo:[1,0,0] neg_hi:[1,0,0]
	v_pk_fma_f32 v[110:111], v[90:91], v[10:11], v[110:111] neg_lo:[1,0,0] neg_hi:[1,0,0]
	ds_read_b128 v[88:91], v64 offset:10720
	s_waitcnt lgkmcnt(9)
	v_pk_fma_f32 v[108:109], v[92:93], v[12:13], v[108:109] neg_lo:[1,0,0] neg_hi:[1,0,0]
	v_pk_fma_f32 v[108:109], v[94:95], v[14:15], v[108:109] neg_lo:[1,0,0] neg_hi:[1,0,0]
	ds_read_b128 v[92:95], v64 offset:10464
	s_waitcnt lgkmcnt(9)
	v_pk_fma_f32 v[110:111], v[96:97], v[12:13], v[110:111] neg_lo:[1,0,0] neg_hi:[1,0,0]
	v_pk_fma_f32 v[110:111], v[98:99], v[14:15], v[110:111] neg_lo:[1,0,0] neg_hi:[1,0,0]
	ds_read_b128 v[96:99], v64 offset:10736
	s_waitcnt lgkmcnt(9)
	v_pk_fma_f32 v[108:109], v[100:101], v[16:17], v[108:109] neg_lo:[1,0,0] neg_hi:[1,0,0]
	v_pk_fma_f32 v[108:109], v[102:103], v[18:19], v[108:109] neg_lo:[1,0,0] neg_hi:[1,0,0]
	ds_read_b128 v[100:103], v64 offset:10480
	s_waitcnt lgkmcnt(9)
	v_pk_fma_f32 v[110:111], v[104:105], v[16:17], v[110:111] neg_lo:[1,0,0] neg_hi:[1,0,0]
	v_pk_fma_f32 v[110:111], v[106:107], v[18:19], v[110:111] neg_lo:[1,0,0] neg_hi:[1,0,0]
	ds_read_b128 v[104:107], v64 offset:10752
	s_waitcnt lgkmcnt(9)
	v_pk_fma_f32 v[108:109], v[68:69], v[20:21], v[108:109] neg_lo:[1,0,0] neg_hi:[1,0,0]
	v_pk_fma_f32 v[108:109], v[70:71], v[22:23], v[108:109] neg_lo:[1,0,0] neg_hi:[1,0,0]
	ds_read_b128 v[68:71], v64 offset:10880
	s_waitcnt lgkmcnt(9)
	v_pk_fma_f32 v[110:111], v[72:73], v[20:21], v[110:111] neg_lo:[1,0,0] neg_hi:[1,0,0]
	v_pk_fma_f32 v[110:111], v[74:75], v[22:23], v[110:111] neg_lo:[1,0,0] neg_hi:[1,0,0]
	ds_read_b128 v[72:75], v64 offset:11152
	s_waitcnt lgkmcnt(9)
	v_pk_fma_f32 v[108:109], v[76:77], v[24:25], v[108:109] neg_lo:[1,0,0] neg_hi:[1,0,0]
	v_pk_fma_f32 v[108:109], v[78:79], v[26:27], v[108:109] neg_lo:[1,0,0] neg_hi:[1,0,0]
	ds_read_b128 v[76:79], v64 offset:10896
	s_waitcnt lgkmcnt(9)
	v_pk_fma_f32 v[110:111], v[80:81], v[24:25], v[110:111] neg_lo:[1,0,0] neg_hi:[1,0,0]
	v_pk_fma_f32 v[110:111], v[82:83], v[26:27], v[110:111] neg_lo:[1,0,0] neg_hi:[1,0,0]
	ds_read_b128 v[80:83], v64 offset:11168
	s_waitcnt lgkmcnt(9)
	v_pk_fma_f32 v[108:109], v[84:85], v[28:29], v[108:109] neg_lo:[1,0,0] neg_hi:[1,0,0]
	v_pk_fma_f32 v[108:109], v[86:87], v[30:31], v[108:109] neg_lo:[1,0,0] neg_hi:[1,0,0]
	ds_read_b128 v[84:87], v64 offset:10912
	s_waitcnt lgkmcnt(9)
	v_pk_fma_f32 v[110:111], v[88:89], v[28:29], v[110:111] neg_lo:[1,0,0] neg_hi:[1,0,0]
	v_pk_fma_f32 v[110:111], v[90:91], v[30:31], v[110:111] neg_lo:[1,0,0] neg_hi:[1,0,0]
	ds_read_b128 v[88:91], v64 offset:11184
	s_waitcnt lgkmcnt(9)
	v_pk_fma_f32 v[108:109], v[92:93], v[32:33], v[108:109] neg_lo:[1,0,0] neg_hi:[1,0,0]
	v_pk_fma_f32 v[108:109], v[94:95], v[34:35], v[108:109] neg_lo:[1,0,0] neg_hi:[1,0,0]
	ds_read_b128 v[92:95], v64 offset:10928
	s_waitcnt lgkmcnt(9)
	v_pk_fma_f32 v[110:111], v[96:97], v[32:33], v[110:111] neg_lo:[1,0,0] neg_hi:[1,0,0]
	v_pk_fma_f32 v[110:111], v[98:99], v[34:35], v[110:111] neg_lo:[1,0,0] neg_hi:[1,0,0]
	ds_read_b128 v[96:99], v64 offset:11200
	s_waitcnt lgkmcnt(9)
	v_pk_fma_f32 v[108:109], v[100:101], v[36:37], v[108:109] neg_lo:[1,0,0] neg_hi:[1,0,0]
	v_add_f32_e32 v108, v108, v109
	v_add_f32_e32 v38, v191, v108
	ds_read_b128 v[100:103], v64 offset:10944
	s_waitcnt lgkmcnt(9)
	v_pk_fma_f32 v[110:111], v[104:105], v[36:37], v[110:111] neg_lo:[1,0,0] neg_hi:[1,0,0]
	v_fma_f32 v110, -v106, v38, v110
	v_add_f32_e32 v110, v110, v111
	v_add_f32_e32 v39, v192, v110
	ds_read_b128 v[104:107], v64 offset:11216
	s_waitcnt lgkmcnt(9)
	v_pk_mul_f32 v[112:113], v[68:69], v[0:1] neg_lo:[1,0] neg_hi:[1,0]
	v_pk_fma_f32 v[112:113], v[70:71], v[2:3], v[112:113] neg_lo:[1,0,0] neg_hi:[1,0,0]
	ds_read_b128 v[68:71], v64 offset:10960
	s_waitcnt lgkmcnt(9)
	v_pk_mul_f32 v[114:115], v[72:73], v[0:1] neg_lo:[1,0] neg_hi:[1,0]
	v_pk_fma_f32 v[114:115], v[74:75], v[2:3], v[114:115] neg_lo:[1,0,0] neg_hi:[1,0,0]
	ds_read_b128 v[72:75], v64 offset:11232
	s_waitcnt lgkmcnt(9)
	v_pk_fma_f32 v[112:113], v[76:77], v[4:5], v[112:113] neg_lo:[1,0,0] neg_hi:[1,0,0]
	v_pk_fma_f32 v[112:113], v[78:79], v[6:7], v[112:113] neg_lo:[1,0,0] neg_hi:[1,0,0]
	ds_read_b128 v[76:79], v64 offset:10976
	s_waitcnt lgkmcnt(9)
	v_pk_fma_f32 v[114:115], v[80:81], v[4:5], v[114:115] neg_lo:[1,0,0] neg_hi:[1,0,0]
	v_pk_fma_f32 v[114:115], v[82:83], v[6:7], v[114:115] neg_lo:[1,0,0] neg_hi:[1,0,0]
	ds_read_b128 v[80:83], v64 offset:11248
	s_waitcnt lgkmcnt(9)
	v_pk_fma_f32 v[112:113], v[84:85], v[8:9], v[112:113] neg_lo:[1,0,0] neg_hi:[1,0,0]
	v_pk_fma_f32 v[112:113], v[86:87], v[10:11], v[112:113] neg_lo:[1,0,0] neg_hi:[1,0,0]
	ds_read_b128 v[84:87], v64 offset:10992
	s_waitcnt lgkmcnt(9)
	v_pk_fma_f32 v[114:115], v[88:89], v[8:9], v[114:115] neg_lo:[1,0,0] neg_hi:[1,0,0]
	v_pk_fma_f32 v[114:115], v[90:91], v[10:11], v[114:115] neg_lo:[1,0,0] neg_hi:[1,0,0]
	ds_read_b128 v[88:91], v64 offset:11264
	s_waitcnt lgkmcnt(9)
	v_pk_fma_f32 v[112:113], v[92:93], v[12:13], v[112:113] neg_lo:[1,0,0] neg_hi:[1,0,0]
	v_pk_fma_f32 v[112:113], v[94:95], v[14:15], v[112:113] neg_lo:[1,0,0] neg_hi:[1,0,0]
	ds_read_b128 v[92:95], v64 offset:11008
	s_waitcnt lgkmcnt(9)
	v_pk_fma_f32 v[114:115], v[96:97], v[12:13], v[114:115] neg_lo:[1,0,0] neg_hi:[1,0,0]
	v_pk_fma_f32 v[114:115], v[98:99], v[14:15], v[114:115] neg_lo:[1,0,0] neg_hi:[1,0,0]
	ds_read_b128 v[96:99], v64 offset:11280
	s_waitcnt lgkmcnt(9)
	v_pk_fma_f32 v[112:113], v[100:101], v[16:17], v[112:113] neg_lo:[1,0,0] neg_hi:[1,0,0]
	v_pk_fma_f32 v[112:113], v[102:103], v[18:19], v[112:113] neg_lo:[1,0,0] neg_hi:[1,0,0]
	ds_read_b128 v[100:103], v64 offset:11024
	s_waitcnt lgkmcnt(9)
	v_pk_fma_f32 v[114:115], v[104:105], v[16:17], v[114:115] neg_lo:[1,0,0] neg_hi:[1,0,0]
	v_pk_fma_f32 v[114:115], v[106:107], v[18:19], v[114:115] neg_lo:[1,0,0] neg_hi:[1,0,0]
	ds_read_b128 v[104:107], v64 offset:11296
	s_waitcnt lgkmcnt(9)
	v_pk_fma_f32 v[112:113], v[68:69], v[20:21], v[112:113] neg_lo:[1,0,0] neg_hi:[1,0,0]
	v_pk_fma_f32 v[112:113], v[70:71], v[22:23], v[112:113] neg_lo:[1,0,0] neg_hi:[1,0,0]
	ds_read_b128 v[68:71], v64 offset:11312
	s_waitcnt lgkmcnt(9)
	v_pk_fma_f32 v[114:115], v[72:73], v[20:21], v[114:115] neg_lo:[1,0,0] neg_hi:[1,0,0]
	v_pk_fma_f32 v[114:115], v[74:75], v[22:23], v[114:115] neg_lo:[1,0,0] neg_hi:[1,0,0]
	ds_read_b128 v[72:75], v64 offset:11424
	s_waitcnt lgkmcnt(9)
	v_pk_fma_f32 v[112:113], v[76:77], v[24:25], v[112:113] neg_lo:[1,0,0] neg_hi:[1,0,0]
	v_pk_fma_f32 v[112:113], v[78:79], v[26:27], v[112:113] neg_lo:[1,0,0] neg_hi:[1,0,0]
	ds_read_b128 v[76:79], v64 offset:11696
	s_waitcnt lgkmcnt(9)
	v_pk_fma_f32 v[114:115], v[80:81], v[24:25], v[114:115] neg_lo:[1,0,0] neg_hi:[1,0,0]
	v_pk_fma_f32 v[114:115], v[82:83], v[26:27], v[114:115] neg_lo:[1,0,0] neg_hi:[1,0,0]
	ds_read_b128 v[80:83], v64 offset:11440
	s_waitcnt lgkmcnt(9)
	v_pk_fma_f32 v[112:113], v[84:85], v[28:29], v[112:113] neg_lo:[1,0,0] neg_hi:[1,0,0]
	v_pk_fma_f32 v[112:113], v[86:87], v[30:31], v[112:113] neg_lo:[1,0,0] neg_hi:[1,0,0]
	ds_read_b128 v[84:87], v64 offset:11712
	s_waitcnt lgkmcnt(9)
	v_pk_fma_f32 v[114:115], v[88:89], v[28:29], v[114:115] neg_lo:[1,0,0] neg_hi:[1,0,0]
	v_pk_fma_f32 v[114:115], v[90:91], v[30:31], v[114:115] neg_lo:[1,0,0] neg_hi:[1,0,0]
	ds_read_b128 v[88:91], v64 offset:11456
	s_waitcnt lgkmcnt(9)
	v_pk_fma_f32 v[112:113], v[92:93], v[32:33], v[112:113] neg_lo:[1,0,0] neg_hi:[1,0,0]
	v_pk_fma_f32 v[112:113], v[94:95], v[34:35], v[112:113] neg_lo:[1,0,0] neg_hi:[1,0,0]
	ds_read_b128 v[92:95], v64 offset:11728
	s_waitcnt lgkmcnt(9)
	v_pk_fma_f32 v[114:115], v[96:97], v[32:33], v[114:115] neg_lo:[1,0,0] neg_hi:[1,0,0]
	v_pk_fma_f32 v[114:115], v[98:99], v[34:35], v[114:115] neg_lo:[1,0,0] neg_hi:[1,0,0]
	ds_read_b128 v[96:99], v64 offset:11472
	s_waitcnt lgkmcnt(9)
	v_pk_fma_f32 v[112:113], v[100:101], v[36:37], v[112:113] neg_lo:[1,0,0] neg_hi:[1,0,0]
	v_pk_fma_f32 v[112:113], v[102:103], v[38:39], v[112:113] neg_lo:[1,0,0] neg_hi:[1,0,0]
	v_add_f32_e32 v112, v112, v113
	v_add_f32_e32 v40, v193, v112
	ds_read_b128 v[100:103], v64 offset:11744
	s_waitcnt lgkmcnt(9)
	v_pk_fma_f32 v[114:115], v[104:105], v[36:37], v[114:115] neg_lo:[1,0,0] neg_hi:[1,0,0]
	v_pk_fma_f32 v[114:115], v[106:107], v[38:39], v[114:115] neg_lo:[1,0,0] neg_hi:[1,0,0]
	ds_read_b128 v[104:107], v64 offset:11488
	s_waitcnt lgkmcnt(9)
	v_fma_f32 v114, -v68, v40, v114
	v_add_f32_e32 v114, v114, v115
	v_add_f32_e32 v41, v194, v114
	ds_read_b128 v[68:71], v64 offset:11760
	s_waitcnt lgkmcnt(9)
	v_pk_mul_f32 v[108:109], v[72:73], v[0:1] neg_lo:[1,0] neg_hi:[1,0]
	v_pk_fma_f32 v[108:109], v[74:75], v[2:3], v[108:109] neg_lo:[1,0,0] neg_hi:[1,0,0]
	ds_read_b128 v[72:75], v64 offset:11504
	s_waitcnt lgkmcnt(9)
	v_pk_mul_f32 v[110:111], v[76:77], v[0:1] neg_lo:[1,0] neg_hi:[1,0]
	v_pk_fma_f32 v[110:111], v[78:79], v[2:3], v[110:111] neg_lo:[1,0,0] neg_hi:[1,0,0]
	ds_read_b128 v[76:79], v64 offset:11776
	s_waitcnt lgkmcnt(9)
	v_pk_fma_f32 v[108:109], v[80:81], v[4:5], v[108:109] neg_lo:[1,0,0] neg_hi:[1,0,0]
	v_pk_fma_f32 v[108:109], v[82:83], v[6:7], v[108:109] neg_lo:[1,0,0] neg_hi:[1,0,0]
	ds_read_b128 v[80:83], v64 offset:11520
	s_waitcnt lgkmcnt(9)
	v_pk_fma_f32 v[110:111], v[84:85], v[4:5], v[110:111] neg_lo:[1,0,0] neg_hi:[1,0,0]
	v_pk_fma_f32 v[110:111], v[86:87], v[6:7], v[110:111] neg_lo:[1,0,0] neg_hi:[1,0,0]
	ds_read_b128 v[84:87], v64 offset:11792
	s_waitcnt lgkmcnt(9)
	v_pk_fma_f32 v[108:109], v[88:89], v[8:9], v[108:109] neg_lo:[1,0,0] neg_hi:[1,0,0]
	v_pk_fma_f32 v[108:109], v[90:91], v[10:11], v[108:109] neg_lo:[1,0,0] neg_hi:[1,0,0]
	ds_read_b128 v[88:91], v64 offset:11536
	s_waitcnt lgkmcnt(9)
	v_pk_fma_f32 v[110:111], v[92:93], v[8:9], v[110:111] neg_lo:[1,0,0] neg_hi:[1,0,0]
	v_pk_fma_f32 v[110:111], v[94:95], v[10:11], v[110:111] neg_lo:[1,0,0] neg_hi:[1,0,0]
	ds_read_b128 v[92:95], v64 offset:11808
	s_waitcnt lgkmcnt(9)
	v_pk_fma_f32 v[108:109], v[96:97], v[12:13], v[108:109] neg_lo:[1,0,0] neg_hi:[1,0,0]
	v_pk_fma_f32 v[108:109], v[98:99], v[14:15], v[108:109] neg_lo:[1,0,0] neg_hi:[1,0,0]
	ds_read_b128 v[96:99], v64 offset:11552
	s_waitcnt lgkmcnt(9)
	v_pk_fma_f32 v[110:111], v[100:101], v[12:13], v[110:111] neg_lo:[1,0,0] neg_hi:[1,0,0]
	v_pk_fma_f32 v[110:111], v[102:103], v[14:15], v[110:111] neg_lo:[1,0,0] neg_hi:[1,0,0]
	ds_read_b128 v[100:103], v64 offset:11824
	s_waitcnt lgkmcnt(9)
	v_pk_fma_f32 v[108:109], v[104:105], v[16:17], v[108:109] neg_lo:[1,0,0] neg_hi:[1,0,0]
	v_pk_fma_f32 v[108:109], v[106:107], v[18:19], v[108:109] neg_lo:[1,0,0] neg_hi:[1,0,0]
	ds_read_b128 v[104:107], v64 offset:11568
	s_waitcnt lgkmcnt(9)
	v_pk_fma_f32 v[110:111], v[68:69], v[16:17], v[110:111] neg_lo:[1,0,0] neg_hi:[1,0,0]
	v_pk_fma_f32 v[110:111], v[70:71], v[18:19], v[110:111] neg_lo:[1,0,0] neg_hi:[1,0,0]
	ds_read_b128 v[68:71], v64 offset:11840
	s_waitcnt lgkmcnt(9)
	v_pk_fma_f32 v[108:109], v[72:73], v[20:21], v[108:109] neg_lo:[1,0,0] neg_hi:[1,0,0]
	v_pk_fma_f32 v[108:109], v[74:75], v[22:23], v[108:109] neg_lo:[1,0,0] neg_hi:[1,0,0]
	ds_read_b128 v[72:75], v64 offset:11584
	s_waitcnt lgkmcnt(9)
	v_pk_fma_f32 v[110:111], v[76:77], v[20:21], v[110:111] neg_lo:[1,0,0] neg_hi:[1,0,0]
	v_pk_fma_f32 v[110:111], v[78:79], v[22:23], v[110:111] neg_lo:[1,0,0] neg_hi:[1,0,0]
	ds_read_b128 v[76:79], v64 offset:11856
	s_waitcnt lgkmcnt(9)
	v_pk_fma_f32 v[108:109], v[80:81], v[24:25], v[108:109] neg_lo:[1,0,0] neg_hi:[1,0,0]
	v_pk_fma_f32 v[108:109], v[82:83], v[26:27], v[108:109] neg_lo:[1,0,0] neg_hi:[1,0,0]
	ds_read_b128 v[80:83], v64 offset:11968
	s_waitcnt lgkmcnt(9)
	v_pk_fma_f32 v[110:111], v[84:85], v[24:25], v[110:111] neg_lo:[1,0,0] neg_hi:[1,0,0]
	v_pk_fma_f32 v[110:111], v[86:87], v[26:27], v[110:111] neg_lo:[1,0,0] neg_hi:[1,0,0]
	ds_read_b128 v[84:87], v64 offset:12240
	s_waitcnt lgkmcnt(9)
	v_pk_fma_f32 v[108:109], v[88:89], v[28:29], v[108:109] neg_lo:[1,0,0] neg_hi:[1,0,0]
	v_pk_fma_f32 v[108:109], v[90:91], v[30:31], v[108:109] neg_lo:[1,0,0] neg_hi:[1,0,0]
	ds_read_b128 v[88:91], v64 offset:11984
	s_waitcnt lgkmcnt(9)
	v_pk_fma_f32 v[110:111], v[92:93], v[28:29], v[110:111] neg_lo:[1,0,0] neg_hi:[1,0,0]
	v_pk_fma_f32 v[110:111], v[94:95], v[30:31], v[110:111] neg_lo:[1,0,0] neg_hi:[1,0,0]
	ds_read_b128 v[92:95], v64 offset:12256
	s_waitcnt lgkmcnt(9)
	v_pk_fma_f32 v[108:109], v[96:97], v[32:33], v[108:109] neg_lo:[1,0,0] neg_hi:[1,0,0]
	v_pk_fma_f32 v[108:109], v[98:99], v[34:35], v[108:109] neg_lo:[1,0,0] neg_hi:[1,0,0]
	ds_read_b128 v[96:99], v64 offset:12000
	s_waitcnt lgkmcnt(9)
	v_pk_fma_f32 v[110:111], v[100:101], v[32:33], v[110:111] neg_lo:[1,0,0] neg_hi:[1,0,0]
	v_pk_fma_f32 v[110:111], v[102:103], v[34:35], v[110:111] neg_lo:[1,0,0] neg_hi:[1,0,0]
	ds_read_b128 v[100:103], v64 offset:12272
	s_waitcnt lgkmcnt(9)
	v_pk_fma_f32 v[108:109], v[104:105], v[36:37], v[108:109] neg_lo:[1,0,0] neg_hi:[1,0,0]
	v_pk_fma_f32 v[108:109], v[106:107], v[38:39], v[108:109] neg_lo:[1,0,0] neg_hi:[1,0,0]
	ds_read_b128 v[104:107], v64 offset:12016
	s_waitcnt lgkmcnt(9)
	v_pk_fma_f32 v[110:111], v[68:69], v[36:37], v[110:111] neg_lo:[1,0,0] neg_hi:[1,0,0]
	v_pk_fma_f32 v[110:111], v[70:71], v[38:39], v[110:111] neg_lo:[1,0,0] neg_hi:[1,0,0]
	ds_read_b128 v[68:71], v64 offset:12288
	s_waitcnt lgkmcnt(9)
	v_pk_fma_f32 v[108:109], v[72:73], v[40:41], v[108:109] neg_lo:[1,0,0] neg_hi:[1,0,0]
	v_add_f32_e32 v108, v108, v109
	v_add_f32_e32 v42, v195, v108
	ds_read_b128 v[72:75], v64 offset:12032
	s_waitcnt lgkmcnt(9)
	v_pk_fma_f32 v[110:111], v[76:77], v[40:41], v[110:111] neg_lo:[1,0,0] neg_hi:[1,0,0]
	v_fma_f32 v110, -v78, v42, v110
	v_add_f32_e32 v110, v110, v111
	v_add_f32_e32 v43, v196, v110
	ds_read_b128 v[76:79], v64 offset:12304
	s_waitcnt lgkmcnt(9)
	v_pk_mul_f32 v[112:113], v[80:81], v[0:1] neg_lo:[1,0] neg_hi:[1,0]
	v_pk_fma_f32 v[112:113], v[82:83], v[2:3], v[112:113] neg_lo:[1,0,0] neg_hi:[1,0,0]
	ds_read_b128 v[80:83], v64 offset:12048
	s_waitcnt lgkmcnt(9)
	v_pk_mul_f32 v[114:115], v[84:85], v[0:1] neg_lo:[1,0] neg_hi:[1,0]
	v_pk_fma_f32 v[114:115], v[86:87], v[2:3], v[114:115] neg_lo:[1,0,0] neg_hi:[1,0,0]
	ds_read_b128 v[84:87], v64 offset:12320
	s_waitcnt lgkmcnt(9)
	v_pk_fma_f32 v[112:113], v[88:89], v[4:5], v[112:113] neg_lo:[1,0,0] neg_hi:[1,0,0]
	v_pk_fma_f32 v[112:113], v[90:91], v[6:7], v[112:113] neg_lo:[1,0,0] neg_hi:[1,0,0]
	ds_read_b128 v[88:91], v64 offset:12064
	s_waitcnt lgkmcnt(9)
	v_pk_fma_f32 v[114:115], v[92:93], v[4:5], v[114:115] neg_lo:[1,0,0] neg_hi:[1,0,0]
	v_pk_fma_f32 v[114:115], v[94:95], v[6:7], v[114:115] neg_lo:[1,0,0] neg_hi:[1,0,0]
	ds_read_b128 v[92:95], v64 offset:12336
	s_waitcnt lgkmcnt(9)
	v_pk_fma_f32 v[112:113], v[96:97], v[8:9], v[112:113] neg_lo:[1,0,0] neg_hi:[1,0,0]
	v_pk_fma_f32 v[112:113], v[98:99], v[10:11], v[112:113] neg_lo:[1,0,0] neg_hi:[1,0,0]
	ds_read_b128 v[96:99], v64 offset:12080
	s_waitcnt lgkmcnt(9)
	v_pk_fma_f32 v[114:115], v[100:101], v[8:9], v[114:115] neg_lo:[1,0,0] neg_hi:[1,0,0]
	v_pk_fma_f32 v[114:115], v[102:103], v[10:11], v[114:115] neg_lo:[1,0,0] neg_hi:[1,0,0]
	ds_read_b128 v[100:103], v64 offset:12352
	s_waitcnt lgkmcnt(9)
	v_pk_fma_f32 v[112:113], v[104:105], v[12:13], v[112:113] neg_lo:[1,0,0] neg_hi:[1,0,0]
	v_pk_fma_f32 v[112:113], v[106:107], v[14:15], v[112:113] neg_lo:[1,0,0] neg_hi:[1,0,0]
	ds_read_b128 v[104:107], v64 offset:12096
	s_waitcnt lgkmcnt(9)
	v_pk_fma_f32 v[114:115], v[68:69], v[12:13], v[114:115] neg_lo:[1,0,0] neg_hi:[1,0,0]
	v_pk_fma_f32 v[114:115], v[70:71], v[14:15], v[114:115] neg_lo:[1,0,0] neg_hi:[1,0,0]
	ds_read_b128 v[68:71], v64 offset:12368
	s_waitcnt lgkmcnt(9)
	v_pk_fma_f32 v[112:113], v[72:73], v[16:17], v[112:113] neg_lo:[1,0,0] neg_hi:[1,0,0]
	v_pk_fma_f32 v[112:113], v[74:75], v[18:19], v[112:113] neg_lo:[1,0,0] neg_hi:[1,0,0]
	ds_read_b128 v[72:75], v64 offset:12112
	s_waitcnt lgkmcnt(9)
	v_pk_fma_f32 v[114:115], v[76:77], v[16:17], v[114:115] neg_lo:[1,0,0] neg_hi:[1,0,0]
	v_pk_fma_f32 v[114:115], v[78:79], v[18:19], v[114:115] neg_lo:[1,0,0] neg_hi:[1,0,0]
	ds_read_b128 v[76:79], v64 offset:12384
	s_waitcnt lgkmcnt(9)
	v_pk_fma_f32 v[112:113], v[80:81], v[20:21], v[112:113] neg_lo:[1,0,0] neg_hi:[1,0,0]
	v_pk_fma_f32 v[112:113], v[82:83], v[22:23], v[112:113] neg_lo:[1,0,0] neg_hi:[1,0,0]
	ds_read_b128 v[80:83], v64 offset:12128
	s_waitcnt lgkmcnt(9)
	v_pk_fma_f32 v[114:115], v[84:85], v[20:21], v[114:115] neg_lo:[1,0,0] neg_hi:[1,0,0]
	v_pk_fma_f32 v[114:115], v[86:87], v[22:23], v[114:115] neg_lo:[1,0,0] neg_hi:[1,0,0]
	ds_read_b128 v[84:87], v64 offset:12400
	s_waitcnt lgkmcnt(9)
	v_pk_fma_f32 v[112:113], v[88:89], v[24:25], v[112:113] neg_lo:[1,0,0] neg_hi:[1,0,0]
	v_pk_fma_f32 v[112:113], v[90:91], v[26:27], v[112:113] neg_lo:[1,0,0] neg_hi:[1,0,0]
	ds_read_b128 v[88:91], v64 offset:12416
	s_waitcnt lgkmcnt(9)
	v_pk_fma_f32 v[114:115], v[92:93], v[24:25], v[114:115] neg_lo:[1,0,0] neg_hi:[1,0,0]
	v_pk_fma_f32 v[114:115], v[94:95], v[26:27], v[114:115] neg_lo:[1,0,0] neg_hi:[1,0,0]
	ds_read_b128 v[92:95], v64 offset:12512
	s_waitcnt lgkmcnt(9)
	v_pk_fma_f32 v[112:113], v[96:97], v[28:29], v[112:113] neg_lo:[1,0,0] neg_hi:[1,0,0]
	v_pk_fma_f32 v[112:113], v[98:99], v[30:31], v[112:113] neg_lo:[1,0,0] neg_hi:[1,0,0]
	ds_read_b128 v[96:99], v64 offset:12784
	s_waitcnt lgkmcnt(9)
	v_pk_fma_f32 v[114:115], v[100:101], v[28:29], v[114:115] neg_lo:[1,0,0] neg_hi:[1,0,0]
	v_pk_fma_f32 v[114:115], v[102:103], v[30:31], v[114:115] neg_lo:[1,0,0] neg_hi:[1,0,0]
	ds_read_b128 v[100:103], v64 offset:12528
	s_waitcnt lgkmcnt(9)
	v_pk_fma_f32 v[112:113], v[104:105], v[32:33], v[112:113] neg_lo:[1,0,0] neg_hi:[1,0,0]
	v_pk_fma_f32 v[112:113], v[106:107], v[34:35], v[112:113] neg_lo:[1,0,0] neg_hi:[1,0,0]
	ds_read_b128 v[104:107], v64 offset:12800
	s_waitcnt lgkmcnt(9)
	v_pk_fma_f32 v[114:115], v[68:69], v[32:33], v[114:115] neg_lo:[1,0,0] neg_hi:[1,0,0]
	v_pk_fma_f32 v[114:115], v[70:71], v[34:35], v[114:115] neg_lo:[1,0,0] neg_hi:[1,0,0]
	ds_read_b128 v[68:71], v64 offset:12544
	s_waitcnt lgkmcnt(9)
	v_pk_fma_f32 v[112:113], v[72:73], v[36:37], v[112:113] neg_lo:[1,0,0] neg_hi:[1,0,0]
	v_pk_fma_f32 v[112:113], v[74:75], v[38:39], v[112:113] neg_lo:[1,0,0] neg_hi:[1,0,0]
	ds_read_b128 v[72:75], v64 offset:12816
	s_waitcnt lgkmcnt(9)
	v_pk_fma_f32 v[114:115], v[76:77], v[36:37], v[114:115] neg_lo:[1,0,0] neg_hi:[1,0,0]
	v_pk_fma_f32 v[114:115], v[78:79], v[38:39], v[114:115] neg_lo:[1,0,0] neg_hi:[1,0,0]
	ds_read_b128 v[76:79], v64 offset:12560
	s_waitcnt lgkmcnt(9)
	v_pk_fma_f32 v[112:113], v[80:81], v[40:41], v[112:113] neg_lo:[1,0,0] neg_hi:[1,0,0]
	v_pk_fma_f32 v[112:113], v[82:83], v[42:43], v[112:113] neg_lo:[1,0,0] neg_hi:[1,0,0]
	v_add_f32_e32 v112, v112, v113
	v_add_f32_e32 v44, v197, v112
	ds_read_b128 v[80:83], v64 offset:12832
	s_waitcnt lgkmcnt(9)
	v_pk_fma_f32 v[114:115], v[84:85], v[40:41], v[114:115] neg_lo:[1,0,0] neg_hi:[1,0,0]
	v_pk_fma_f32 v[114:115], v[86:87], v[42:43], v[114:115] neg_lo:[1,0,0] neg_hi:[1,0,0]
	ds_read_b128 v[84:87], v64 offset:12576
	s_waitcnt lgkmcnt(9)
	v_fma_f32 v114, -v88, v44, v114
	v_add_f32_e32 v114, v114, v115
	v_add_f32_e32 v45, v198, v114
	ds_read_b128 v[88:91], v64 offset:12848
	s_waitcnt lgkmcnt(9)
	v_pk_mul_f32 v[108:109], v[92:93], v[0:1] neg_lo:[1,0] neg_hi:[1,0]
	v_pk_fma_f32 v[108:109], v[94:95], v[2:3], v[108:109] neg_lo:[1,0,0] neg_hi:[1,0,0]
	ds_read_b128 v[92:95], v64 offset:12592
	s_waitcnt lgkmcnt(9)
	v_pk_mul_f32 v[110:111], v[96:97], v[0:1] neg_lo:[1,0] neg_hi:[1,0]
	v_pk_fma_f32 v[110:111], v[98:99], v[2:3], v[110:111] neg_lo:[1,0,0] neg_hi:[1,0,0]
	ds_read_b128 v[96:99], v64 offset:12864
	s_waitcnt lgkmcnt(9)
	v_pk_fma_f32 v[108:109], v[100:101], v[4:5], v[108:109] neg_lo:[1,0,0] neg_hi:[1,0,0]
	v_pk_fma_f32 v[108:109], v[102:103], v[6:7], v[108:109] neg_lo:[1,0,0] neg_hi:[1,0,0]
	ds_read_b128 v[100:103], v64 offset:12608
	s_waitcnt lgkmcnt(9)
	v_pk_fma_f32 v[110:111], v[104:105], v[4:5], v[110:111] neg_lo:[1,0,0] neg_hi:[1,0,0]
	v_pk_fma_f32 v[110:111], v[106:107], v[6:7], v[110:111] neg_lo:[1,0,0] neg_hi:[1,0,0]
	ds_read_b128 v[104:107], v64 offset:12880
	s_waitcnt lgkmcnt(9)
	v_pk_fma_f32 v[108:109], v[68:69], v[8:9], v[108:109] neg_lo:[1,0,0] neg_hi:[1,0,0]
	v_pk_fma_f32 v[108:109], v[70:71], v[10:11], v[108:109] neg_lo:[1,0,0] neg_hi:[1,0,0]
	ds_read_b128 v[68:71], v64 offset:12624
	s_waitcnt lgkmcnt(9)
	v_pk_fma_f32 v[110:111], v[72:73], v[8:9], v[110:111] neg_lo:[1,0,0] neg_hi:[1,0,0]
	v_pk_fma_f32 v[110:111], v[74:75], v[10:11], v[110:111] neg_lo:[1,0,0] neg_hi:[1,0,0]
	ds_read_b128 v[72:75], v64 offset:12896
	s_waitcnt lgkmcnt(9)
	v_pk_fma_f32 v[108:109], v[76:77], v[12:13], v[108:109] neg_lo:[1,0,0] neg_hi:[1,0,0]
	v_pk_fma_f32 v[108:109], v[78:79], v[14:15], v[108:109] neg_lo:[1,0,0] neg_hi:[1,0,0]
	ds_read_b128 v[76:79], v64 offset:12640
	s_waitcnt lgkmcnt(9)
	v_pk_fma_f32 v[110:111], v[80:81], v[12:13], v[110:111] neg_lo:[1,0,0] neg_hi:[1,0,0]
	v_pk_fma_f32 v[110:111], v[82:83], v[14:15], v[110:111] neg_lo:[1,0,0] neg_hi:[1,0,0]
	ds_read_b128 v[80:83], v64 offset:12912
	s_waitcnt lgkmcnt(9)
	v_pk_fma_f32 v[108:109], v[84:85], v[16:17], v[108:109] neg_lo:[1,0,0] neg_hi:[1,0,0]
	v_pk_fma_f32 v[108:109], v[86:87], v[18:19], v[108:109] neg_lo:[1,0,0] neg_hi:[1,0,0]
	ds_read_b128 v[84:87], v64 offset:12656
	s_waitcnt lgkmcnt(9)
	v_pk_fma_f32 v[110:111], v[88:89], v[16:17], v[110:111] neg_lo:[1,0,0] neg_hi:[1,0,0]
	v_pk_fma_f32 v[110:111], v[90:91], v[18:19], v[110:111] neg_lo:[1,0,0] neg_hi:[1,0,0]
	ds_read_b128 v[88:91], v64 offset:12928
	s_waitcnt lgkmcnt(9)
	v_pk_fma_f32 v[108:109], v[92:93], v[20:21], v[108:109] neg_lo:[1,0,0] neg_hi:[1,0,0]
	v_pk_fma_f32 v[108:109], v[94:95], v[22:23], v[108:109] neg_lo:[1,0,0] neg_hi:[1,0,0]
	ds_read_b128 v[92:95], v64 offset:12672
	s_waitcnt lgkmcnt(9)
	v_pk_fma_f32 v[110:111], v[96:97], v[20:21], v[110:111] neg_lo:[1,0,0] neg_hi:[1,0,0]
	v_pk_fma_f32 v[110:111], v[98:99], v[22:23], v[110:111] neg_lo:[1,0,0] neg_hi:[1,0,0]
	ds_read_b128 v[96:99], v64 offset:12944
	s_waitcnt lgkmcnt(9)
	v_pk_fma_f32 v[108:109], v[100:101], v[24:25], v[108:109] neg_lo:[1,0,0] neg_hi:[1,0,0]
	v_pk_fma_f32 v[108:109], v[102:103], v[26:27], v[108:109] neg_lo:[1,0,0] neg_hi:[1,0,0]
	ds_read_b128 v[100:103], v64 offset:12688
	s_waitcnt lgkmcnt(9)
	v_pk_fma_f32 v[110:111], v[104:105], v[24:25], v[110:111] neg_lo:[1,0,0] neg_hi:[1,0,0]
	v_pk_fma_f32 v[110:111], v[106:107], v[26:27], v[110:111] neg_lo:[1,0,0] neg_hi:[1,0,0]
	ds_read_b128 v[104:107], v64 offset:12960
	s_waitcnt lgkmcnt(9)
	v_pk_fma_f32 v[108:109], v[68:69], v[28:29], v[108:109] neg_lo:[1,0,0] neg_hi:[1,0,0]
	v_pk_fma_f32 v[108:109], v[70:71], v[30:31], v[108:109] neg_lo:[1,0,0] neg_hi:[1,0,0]
	ds_read_b128 v[68:71], v64 offset:13056
	s_waitcnt lgkmcnt(9)
	v_pk_fma_f32 v[110:111], v[72:73], v[28:29], v[110:111] neg_lo:[1,0,0] neg_hi:[1,0,0]
	v_pk_fma_f32 v[110:111], v[74:75], v[30:31], v[110:111] neg_lo:[1,0,0] neg_hi:[1,0,0]
	ds_read_b128 v[72:75], v64 offset:13328
	s_waitcnt lgkmcnt(9)
	v_pk_fma_f32 v[108:109], v[76:77], v[32:33], v[108:109] neg_lo:[1,0,0] neg_hi:[1,0,0]
	v_pk_fma_f32 v[108:109], v[78:79], v[34:35], v[108:109] neg_lo:[1,0,0] neg_hi:[1,0,0]
	ds_read_b128 v[76:79], v64 offset:13072
	s_waitcnt lgkmcnt(9)
	v_pk_fma_f32 v[110:111], v[80:81], v[32:33], v[110:111] neg_lo:[1,0,0] neg_hi:[1,0,0]
	v_pk_fma_f32 v[110:111], v[82:83], v[34:35], v[110:111] neg_lo:[1,0,0] neg_hi:[1,0,0]
	ds_read_b128 v[80:83], v64 offset:13344
	s_waitcnt lgkmcnt(9)
	v_pk_fma_f32 v[108:109], v[84:85], v[36:37], v[108:109] neg_lo:[1,0,0] neg_hi:[1,0,0]
	v_pk_fma_f32 v[108:109], v[86:87], v[38:39], v[108:109] neg_lo:[1,0,0] neg_hi:[1,0,0]
	ds_read_b128 v[84:87], v64 offset:13088
	s_waitcnt lgkmcnt(9)
	v_pk_fma_f32 v[110:111], v[88:89], v[36:37], v[110:111] neg_lo:[1,0,0] neg_hi:[1,0,0]
	v_pk_fma_f32 v[110:111], v[90:91], v[38:39], v[110:111] neg_lo:[1,0,0] neg_hi:[1,0,0]
	ds_read_b128 v[88:91], v64 offset:13360
	s_waitcnt lgkmcnt(9)
	v_pk_fma_f32 v[108:109], v[92:93], v[40:41], v[108:109] neg_lo:[1,0,0] neg_hi:[1,0,0]
	v_pk_fma_f32 v[108:109], v[94:95], v[42:43], v[108:109] neg_lo:[1,0,0] neg_hi:[1,0,0]
	ds_read_b128 v[92:95], v64 offset:13104
	s_waitcnt lgkmcnt(9)
	v_pk_fma_f32 v[110:111], v[96:97], v[40:41], v[110:111] neg_lo:[1,0,0] neg_hi:[1,0,0]
	v_pk_fma_f32 v[110:111], v[98:99], v[42:43], v[110:111] neg_lo:[1,0,0] neg_hi:[1,0,0]
	ds_read_b128 v[96:99], v64 offset:13376
	s_waitcnt lgkmcnt(9)
	v_pk_fma_f32 v[108:109], v[100:101], v[44:45], v[108:109] neg_lo:[1,0,0] neg_hi:[1,0,0]
	v_add_f32_e32 v108, v108, v109
	v_add_f32_e32 v46, v199, v108
	ds_read_b128 v[100:103], v64 offset:13120
	s_waitcnt lgkmcnt(9)
	v_pk_fma_f32 v[110:111], v[104:105], v[44:45], v[110:111] neg_lo:[1,0,0] neg_hi:[1,0,0]
	v_fma_f32 v110, -v106, v46, v110
	v_add_f32_e32 v110, v110, v111
	v_add_f32_e32 v47, v202, v110
	ds_read_b128 v[104:107], v64 offset:13392
	s_waitcnt lgkmcnt(9)
	v_pk_mul_f32 v[112:113], v[68:69], v[0:1] neg_lo:[1,0] neg_hi:[1,0]
	v_pk_fma_f32 v[112:113], v[70:71], v[2:3], v[112:113] neg_lo:[1,0,0] neg_hi:[1,0,0]
	ds_read_b128 v[68:71], v64 offset:13136
	s_waitcnt lgkmcnt(9)
	v_pk_mul_f32 v[114:115], v[72:73], v[0:1] neg_lo:[1,0] neg_hi:[1,0]
	v_pk_fma_f32 v[114:115], v[74:75], v[2:3], v[114:115] neg_lo:[1,0,0] neg_hi:[1,0,0]
	ds_read_b128 v[72:75], v64 offset:13408
	s_waitcnt lgkmcnt(9)
	v_pk_fma_f32 v[112:113], v[76:77], v[4:5], v[112:113] neg_lo:[1,0,0] neg_hi:[1,0,0]
	v_pk_fma_f32 v[112:113], v[78:79], v[6:7], v[112:113] neg_lo:[1,0,0] neg_hi:[1,0,0]
	ds_read_b128 v[76:79], v64 offset:13152
	s_waitcnt lgkmcnt(9)
	v_pk_fma_f32 v[114:115], v[80:81], v[4:5], v[114:115] neg_lo:[1,0,0] neg_hi:[1,0,0]
	v_pk_fma_f32 v[114:115], v[82:83], v[6:7], v[114:115] neg_lo:[1,0,0] neg_hi:[1,0,0]
	ds_read_b128 v[80:83], v64 offset:13424
	s_waitcnt lgkmcnt(9)
	v_pk_fma_f32 v[112:113], v[84:85], v[8:9], v[112:113] neg_lo:[1,0,0] neg_hi:[1,0,0]
	v_pk_fma_f32 v[112:113], v[86:87], v[10:11], v[112:113] neg_lo:[1,0,0] neg_hi:[1,0,0]
	ds_read_b128 v[84:87], v64 offset:13168
	s_waitcnt lgkmcnt(9)
	v_pk_fma_f32 v[114:115], v[88:89], v[8:9], v[114:115] neg_lo:[1,0,0] neg_hi:[1,0,0]
	v_pk_fma_f32 v[114:115], v[90:91], v[10:11], v[114:115] neg_lo:[1,0,0] neg_hi:[1,0,0]
	ds_read_b128 v[88:91], v64 offset:13440
	s_waitcnt lgkmcnt(9)
	v_pk_fma_f32 v[112:113], v[92:93], v[12:13], v[112:113] neg_lo:[1,0,0] neg_hi:[1,0,0]
	v_pk_fma_f32 v[112:113], v[94:95], v[14:15], v[112:113] neg_lo:[1,0,0] neg_hi:[1,0,0]
	ds_read_b128 v[92:95], v64 offset:13184
	s_waitcnt lgkmcnt(9)
	v_pk_fma_f32 v[114:115], v[96:97], v[12:13], v[114:115] neg_lo:[1,0,0] neg_hi:[1,0,0]
	v_pk_fma_f32 v[114:115], v[98:99], v[14:15], v[114:115] neg_lo:[1,0,0] neg_hi:[1,0,0]
	ds_read_b128 v[96:99], v64 offset:13456
	s_waitcnt lgkmcnt(9)
	v_pk_fma_f32 v[112:113], v[100:101], v[16:17], v[112:113] neg_lo:[1,0,0] neg_hi:[1,0,0]
	v_pk_fma_f32 v[112:113], v[102:103], v[18:19], v[112:113] neg_lo:[1,0,0] neg_hi:[1,0,0]
	ds_read_b128 v[100:103], v64 offset:13200
	s_waitcnt lgkmcnt(9)
	v_pk_fma_f32 v[114:115], v[104:105], v[16:17], v[114:115] neg_lo:[1,0,0] neg_hi:[1,0,0]
	v_pk_fma_f32 v[114:115], v[106:107], v[18:19], v[114:115] neg_lo:[1,0,0] neg_hi:[1,0,0]
	ds_read_b128 v[104:107], v64 offset:13472
	s_waitcnt lgkmcnt(9)
	v_pk_fma_f32 v[112:113], v[68:69], v[20:21], v[112:113] neg_lo:[1,0,0] neg_hi:[1,0,0]
	v_pk_fma_f32 v[112:113], v[70:71], v[22:23], v[112:113] neg_lo:[1,0,0] neg_hi:[1,0,0]
	ds_read_b128 v[68:71], v64 offset:13216
	s_waitcnt lgkmcnt(9)
	v_pk_fma_f32 v[114:115], v[72:73], v[20:21], v[114:115] neg_lo:[1,0,0] neg_hi:[1,0,0]
	v_pk_fma_f32 v[114:115], v[74:75], v[22:23], v[114:115] neg_lo:[1,0,0] neg_hi:[1,0,0]
	ds_read_b128 v[72:75], v64 offset:13488
	s_waitcnt lgkmcnt(9)
	v_pk_fma_f32 v[112:113], v[76:77], v[24:25], v[112:113] neg_lo:[1,0,0] neg_hi:[1,0,0]
	v_pk_fma_f32 v[112:113], v[78:79], v[26:27], v[112:113] neg_lo:[1,0,0] neg_hi:[1,0,0]
	ds_read_b128 v[76:79], v64 offset:13232
	s_waitcnt lgkmcnt(9)
	v_pk_fma_f32 v[114:115], v[80:81], v[24:25], v[114:115] neg_lo:[1,0,0] neg_hi:[1,0,0]
	v_pk_fma_f32 v[114:115], v[82:83], v[26:27], v[114:115] neg_lo:[1,0,0] neg_hi:[1,0,0]
	ds_read_b128 v[80:83], v64 offset:13504
	s_waitcnt lgkmcnt(9)
	v_pk_fma_f32 v[112:113], v[84:85], v[28:29], v[112:113] neg_lo:[1,0,0] neg_hi:[1,0,0]
	v_pk_fma_f32 v[112:113], v[86:87], v[30:31], v[112:113] neg_lo:[1,0,0] neg_hi:[1,0,0]
	ds_read_b128 v[84:87], v64 offset:13520
	s_waitcnt lgkmcnt(9)
	v_pk_fma_f32 v[114:115], v[88:89], v[28:29], v[114:115] neg_lo:[1,0,0] neg_hi:[1,0,0]
	v_pk_fma_f32 v[114:115], v[90:91], v[30:31], v[114:115] neg_lo:[1,0,0] neg_hi:[1,0,0]
	ds_read_b128 v[88:91], v64 offset:13600
	s_waitcnt lgkmcnt(9)
	v_pk_fma_f32 v[112:113], v[92:93], v[32:33], v[112:113] neg_lo:[1,0,0] neg_hi:[1,0,0]
	v_pk_fma_f32 v[112:113], v[94:95], v[34:35], v[112:113] neg_lo:[1,0,0] neg_hi:[1,0,0]
	ds_read_b128 v[92:95], v64 offset:13872
	s_waitcnt lgkmcnt(9)
	v_pk_fma_f32 v[114:115], v[96:97], v[32:33], v[114:115] neg_lo:[1,0,0] neg_hi:[1,0,0]
	v_pk_fma_f32 v[114:115], v[98:99], v[34:35], v[114:115] neg_lo:[1,0,0] neg_hi:[1,0,0]
	ds_read_b128 v[96:99], v64 offset:13616
	s_waitcnt lgkmcnt(9)
	v_pk_fma_f32 v[112:113], v[100:101], v[36:37], v[112:113] neg_lo:[1,0,0] neg_hi:[1,0,0]
	v_pk_fma_f32 v[112:113], v[102:103], v[38:39], v[112:113] neg_lo:[1,0,0] neg_hi:[1,0,0]
	ds_read_b128 v[100:103], v64 offset:13888
	s_waitcnt lgkmcnt(9)
	v_pk_fma_f32 v[114:115], v[104:105], v[36:37], v[114:115] neg_lo:[1,0,0] neg_hi:[1,0,0]
	v_pk_fma_f32 v[114:115], v[106:107], v[38:39], v[114:115] neg_lo:[1,0,0] neg_hi:[1,0,0]
	ds_read_b128 v[104:107], v64 offset:13632
	s_waitcnt lgkmcnt(9)
	v_pk_fma_f32 v[112:113], v[68:69], v[40:41], v[112:113] neg_lo:[1,0,0] neg_hi:[1,0,0]
	v_pk_fma_f32 v[112:113], v[70:71], v[42:43], v[112:113] neg_lo:[1,0,0] neg_hi:[1,0,0]
	ds_read_b128 v[68:71], v64 offset:13904
	s_waitcnt lgkmcnt(9)
	v_pk_fma_f32 v[114:115], v[72:73], v[40:41], v[114:115] neg_lo:[1,0,0] neg_hi:[1,0,0]
	v_pk_fma_f32 v[114:115], v[74:75], v[42:43], v[114:115] neg_lo:[1,0,0] neg_hi:[1,0,0]
	ds_read_b128 v[72:75], v64 offset:13648
	s_waitcnt lgkmcnt(9)
	v_pk_fma_f32 v[112:113], v[76:77], v[44:45], v[112:113] neg_lo:[1,0,0] neg_hi:[1,0,0]
	v_pk_fma_f32 v[112:113], v[78:79], v[46:47], v[112:113] neg_lo:[1,0,0] neg_hi:[1,0,0]
	v_add_f32_e32 v112, v112, v113
	v_add_f32_e32 v48, v203, v112
	ds_read_b128 v[76:79], v64 offset:13920
	s_waitcnt lgkmcnt(9)
	v_pk_fma_f32 v[114:115], v[80:81], v[44:45], v[114:115] neg_lo:[1,0,0] neg_hi:[1,0,0]
	v_pk_fma_f32 v[114:115], v[82:83], v[46:47], v[114:115] neg_lo:[1,0,0] neg_hi:[1,0,0]
	ds_read_b128 v[80:83], v64 offset:13664
	s_waitcnt lgkmcnt(9)
	v_fma_f32 v114, -v84, v48, v114
	v_add_f32_e32 v114, v114, v115
	v_add_f32_e32 v49, v204, v114
	ds_read_b128 v[84:87], v64 offset:13936
	s_waitcnt lgkmcnt(9)
	v_pk_mul_f32 v[108:109], v[88:89], v[0:1] neg_lo:[1,0] neg_hi:[1,0]
	v_pk_fma_f32 v[108:109], v[90:91], v[2:3], v[108:109] neg_lo:[1,0,0] neg_hi:[1,0,0]
	ds_read_b128 v[88:91], v64 offset:13680
	s_waitcnt lgkmcnt(9)
	v_pk_mul_f32 v[110:111], v[92:93], v[0:1] neg_lo:[1,0] neg_hi:[1,0]
	v_pk_fma_f32 v[110:111], v[94:95], v[2:3], v[110:111] neg_lo:[1,0,0] neg_hi:[1,0,0]
	ds_read_b128 v[92:95], v64 offset:13952
	s_waitcnt lgkmcnt(9)
	v_pk_fma_f32 v[108:109], v[96:97], v[4:5], v[108:109] neg_lo:[1,0,0] neg_hi:[1,0,0]
	v_pk_fma_f32 v[108:109], v[98:99], v[6:7], v[108:109] neg_lo:[1,0,0] neg_hi:[1,0,0]
	ds_read_b128 v[96:99], v64 offset:13696
	s_waitcnt lgkmcnt(9)
	v_pk_fma_f32 v[110:111], v[100:101], v[4:5], v[110:111] neg_lo:[1,0,0] neg_hi:[1,0,0]
	v_pk_fma_f32 v[110:111], v[102:103], v[6:7], v[110:111] neg_lo:[1,0,0] neg_hi:[1,0,0]
	ds_read_b128 v[100:103], v64 offset:13968
	s_waitcnt lgkmcnt(9)
	v_pk_fma_f32 v[108:109], v[104:105], v[8:9], v[108:109] neg_lo:[1,0,0] neg_hi:[1,0,0]
	v_pk_fma_f32 v[108:109], v[106:107], v[10:11], v[108:109] neg_lo:[1,0,0] neg_hi:[1,0,0]
	ds_read_b128 v[104:107], v64 offset:13712
	s_waitcnt lgkmcnt(9)
	v_pk_fma_f32 v[110:111], v[68:69], v[8:9], v[110:111] neg_lo:[1,0,0] neg_hi:[1,0,0]
	v_pk_fma_f32 v[110:111], v[70:71], v[10:11], v[110:111] neg_lo:[1,0,0] neg_hi:[1,0,0]
	ds_read_b128 v[68:71], v64 offset:13984
	s_waitcnt lgkmcnt(9)
	v_pk_fma_f32 v[108:109], v[72:73], v[12:13], v[108:109] neg_lo:[1,0,0] neg_hi:[1,0,0]
	v_pk_fma_f32 v[108:109], v[74:75], v[14:15], v[108:109] neg_lo:[1,0,0] neg_hi:[1,0,0]
	ds_read_b128 v[72:75], v64 offset:13728
	s_waitcnt lgkmcnt(9)
	v_pk_fma_f32 v[110:111], v[76:77], v[12:13], v[110:111] neg_lo:[1,0,0] neg_hi:[1,0,0]
	v_pk_fma_f32 v[110:111], v[78:79], v[14:15], v[110:111] neg_lo:[1,0,0] neg_hi:[1,0,0]
	ds_read_b128 v[76:79], v64 offset:14000
	s_waitcnt lgkmcnt(9)
	v_pk_fma_f32 v[108:109], v[80:81], v[16:17], v[108:109] neg_lo:[1,0,0] neg_hi:[1,0,0]
	v_pk_fma_f32 v[108:109], v[82:83], v[18:19], v[108:109] neg_lo:[1,0,0] neg_hi:[1,0,0]
	ds_read_b128 v[80:83], v64 offset:13744
	s_waitcnt lgkmcnt(9)
	v_pk_fma_f32 v[110:111], v[84:85], v[16:17], v[110:111] neg_lo:[1,0,0] neg_hi:[1,0,0]
	v_pk_fma_f32 v[110:111], v[86:87], v[18:19], v[110:111] neg_lo:[1,0,0] neg_hi:[1,0,0]
	ds_read_b128 v[84:87], v64 offset:14016
	s_waitcnt lgkmcnt(9)
	v_pk_fma_f32 v[108:109], v[88:89], v[20:21], v[108:109] neg_lo:[1,0,0] neg_hi:[1,0,0]
	v_pk_fma_f32 v[108:109], v[90:91], v[22:23], v[108:109] neg_lo:[1,0,0] neg_hi:[1,0,0]
	ds_read_b128 v[88:91], v64 offset:13760
	s_waitcnt lgkmcnt(9)
	v_pk_fma_f32 v[110:111], v[92:93], v[20:21], v[110:111] neg_lo:[1,0,0] neg_hi:[1,0,0]
	v_pk_fma_f32 v[110:111], v[94:95], v[22:23], v[110:111] neg_lo:[1,0,0] neg_hi:[1,0,0]
	ds_read_b128 v[92:95], v64 offset:14032
	s_waitcnt lgkmcnt(9)
	v_pk_fma_f32 v[108:109], v[96:97], v[24:25], v[108:109] neg_lo:[1,0,0] neg_hi:[1,0,0]
	v_pk_fma_f32 v[108:109], v[98:99], v[26:27], v[108:109] neg_lo:[1,0,0] neg_hi:[1,0,0]
	ds_read_b128 v[96:99], v64 offset:13776
	s_waitcnt lgkmcnt(9)
	v_pk_fma_f32 v[110:111], v[100:101], v[24:25], v[110:111] neg_lo:[1,0,0] neg_hi:[1,0,0]
	v_pk_fma_f32 v[110:111], v[102:103], v[26:27], v[110:111] neg_lo:[1,0,0] neg_hi:[1,0,0]
	ds_read_b128 v[100:103], v64 offset:14048
	s_waitcnt lgkmcnt(9)
	v_pk_fma_f32 v[108:109], v[104:105], v[28:29], v[108:109] neg_lo:[1,0,0] neg_hi:[1,0,0]
	v_pk_fma_f32 v[108:109], v[106:107], v[30:31], v[108:109] neg_lo:[1,0,0] neg_hi:[1,0,0]
	ds_read_b128 v[104:107], v64 offset:13792
	s_waitcnt lgkmcnt(9)
	v_pk_fma_f32 v[110:111], v[68:69], v[28:29], v[110:111] neg_lo:[1,0,0] neg_hi:[1,0,0]
	v_pk_fma_f32 v[110:111], v[70:71], v[30:31], v[110:111] neg_lo:[1,0,0] neg_hi:[1,0,0]
	ds_read_b128 v[68:71], v64 offset:14064
	s_waitcnt lgkmcnt(9)
	v_pk_fma_f32 v[108:109], v[72:73], v[32:33], v[108:109] neg_lo:[1,0,0] neg_hi:[1,0,0]
	v_pk_fma_f32 v[108:109], v[74:75], v[34:35], v[108:109] neg_lo:[1,0,0] neg_hi:[1,0,0]
	ds_read_b128 v[72:75], v64 offset:14144
	s_waitcnt lgkmcnt(9)
	v_pk_fma_f32 v[110:111], v[76:77], v[32:33], v[110:111] neg_lo:[1,0,0] neg_hi:[1,0,0]
	v_pk_fma_f32 v[110:111], v[78:79], v[34:35], v[110:111] neg_lo:[1,0,0] neg_hi:[1,0,0]
	ds_read_b128 v[76:79], v64 offset:14416
	s_waitcnt lgkmcnt(9)
	v_pk_fma_f32 v[108:109], v[80:81], v[36:37], v[108:109] neg_lo:[1,0,0] neg_hi:[1,0,0]
	v_pk_fma_f32 v[108:109], v[82:83], v[38:39], v[108:109] neg_lo:[1,0,0] neg_hi:[1,0,0]
	ds_read_b128 v[80:83], v64 offset:14160
	s_waitcnt lgkmcnt(9)
	v_pk_fma_f32 v[110:111], v[84:85], v[36:37], v[110:111] neg_lo:[1,0,0] neg_hi:[1,0,0]
	v_pk_fma_f32 v[110:111], v[86:87], v[38:39], v[110:111] neg_lo:[1,0,0] neg_hi:[1,0,0]
	ds_read_b128 v[84:87], v64 offset:14432
	s_waitcnt lgkmcnt(9)
	v_pk_fma_f32 v[108:109], v[88:89], v[40:41], v[108:109] neg_lo:[1,0,0] neg_hi:[1,0,0]
	v_pk_fma_f32 v[108:109], v[90:91], v[42:43], v[108:109] neg_lo:[1,0,0] neg_hi:[1,0,0]
	ds_read_b128 v[88:91], v64 offset:14176
	s_waitcnt lgkmcnt(9)
	v_pk_fma_f32 v[110:111], v[92:93], v[40:41], v[110:111] neg_lo:[1,0,0] neg_hi:[1,0,0]
	v_pk_fma_f32 v[110:111], v[94:95], v[42:43], v[110:111] neg_lo:[1,0,0] neg_hi:[1,0,0]
	ds_read_b128 v[92:95], v64 offset:14448
	s_waitcnt lgkmcnt(9)
	v_pk_fma_f32 v[108:109], v[96:97], v[44:45], v[108:109] neg_lo:[1,0,0] neg_hi:[1,0,0]
	v_pk_fma_f32 v[108:109], v[98:99], v[46:47], v[108:109] neg_lo:[1,0,0] neg_hi:[1,0,0]
	ds_read_b128 v[96:99], v64 offset:14192
	s_waitcnt lgkmcnt(9)
	v_pk_fma_f32 v[110:111], v[100:101], v[44:45], v[110:111] neg_lo:[1,0,0] neg_hi:[1,0,0]
	v_pk_fma_f32 v[110:111], v[102:103], v[46:47], v[110:111] neg_lo:[1,0,0] neg_hi:[1,0,0]
	ds_read_b128 v[100:103], v64 offset:14464
	s_waitcnt lgkmcnt(9)
	v_pk_fma_f32 v[108:109], v[104:105], v[48:49], v[108:109] neg_lo:[1,0,0] neg_hi:[1,0,0]
	v_add_f32_e32 v108, v108, v109
	v_add_f32_e32 v50, v205, v108
	ds_read_b128 v[104:107], v64 offset:14208
	s_waitcnt lgkmcnt(9)
	v_pk_fma_f32 v[110:111], v[68:69], v[48:49], v[110:111] neg_lo:[1,0,0] neg_hi:[1,0,0]
	v_fma_f32 v110, -v70, v50, v110
	v_add_f32_e32 v110, v110, v111
	v_add_f32_e32 v51, v206, v110
	ds_read_b128 v[68:71], v64 offset:14480
	s_waitcnt lgkmcnt(9)
	v_pk_mul_f32 v[112:113], v[72:73], v[0:1] neg_lo:[1,0] neg_hi:[1,0]
	v_pk_fma_f32 v[112:113], v[74:75], v[2:3], v[112:113] neg_lo:[1,0,0] neg_hi:[1,0,0]
	ds_read_b128 v[72:75], v64 offset:14224
	s_waitcnt lgkmcnt(9)
	v_pk_mul_f32 v[114:115], v[76:77], v[0:1] neg_lo:[1,0] neg_hi:[1,0]
	v_pk_fma_f32 v[114:115], v[78:79], v[2:3], v[114:115] neg_lo:[1,0,0] neg_hi:[1,0,0]
	ds_read_b128 v[76:79], v64 offset:14496
	s_waitcnt lgkmcnt(9)
	v_pk_fma_f32 v[112:113], v[80:81], v[4:5], v[112:113] neg_lo:[1,0,0] neg_hi:[1,0,0]
	v_pk_fma_f32 v[112:113], v[82:83], v[6:7], v[112:113] neg_lo:[1,0,0] neg_hi:[1,0,0]
	ds_read_b128 v[80:83], v64 offset:14240
	s_waitcnt lgkmcnt(9)
	v_pk_fma_f32 v[114:115], v[84:85], v[4:5], v[114:115] neg_lo:[1,0,0] neg_hi:[1,0,0]
	v_pk_fma_f32 v[114:115], v[86:87], v[6:7], v[114:115] neg_lo:[1,0,0] neg_hi:[1,0,0]
	ds_read_b128 v[84:87], v64 offset:14512
	s_waitcnt lgkmcnt(9)
	v_pk_fma_f32 v[112:113], v[88:89], v[8:9], v[112:113] neg_lo:[1,0,0] neg_hi:[1,0,0]
	v_pk_fma_f32 v[112:113], v[90:91], v[10:11], v[112:113] neg_lo:[1,0,0] neg_hi:[1,0,0]
	ds_read_b128 v[88:91], v64 offset:14256
	s_waitcnt lgkmcnt(9)
	v_pk_fma_f32 v[114:115], v[92:93], v[8:9], v[114:115] neg_lo:[1,0,0] neg_hi:[1,0,0]
	v_pk_fma_f32 v[114:115], v[94:95], v[10:11], v[114:115] neg_lo:[1,0,0] neg_hi:[1,0,0]
	ds_read_b128 v[92:95], v64 offset:14528
	s_waitcnt lgkmcnt(9)
	v_pk_fma_f32 v[112:113], v[96:97], v[12:13], v[112:113] neg_lo:[1,0,0] neg_hi:[1,0,0]
	v_pk_fma_f32 v[112:113], v[98:99], v[14:15], v[112:113] neg_lo:[1,0,0] neg_hi:[1,0,0]
	ds_read_b128 v[96:99], v64 offset:14272
	s_waitcnt lgkmcnt(9)
	v_pk_fma_f32 v[114:115], v[100:101], v[12:13], v[114:115] neg_lo:[1,0,0] neg_hi:[1,0,0]
	v_pk_fma_f32 v[114:115], v[102:103], v[14:15], v[114:115] neg_lo:[1,0,0] neg_hi:[1,0,0]
	ds_read_b128 v[100:103], v64 offset:14544
	s_waitcnt lgkmcnt(9)
	v_pk_fma_f32 v[112:113], v[104:105], v[16:17], v[112:113] neg_lo:[1,0,0] neg_hi:[1,0,0]
	v_pk_fma_f32 v[112:113], v[106:107], v[18:19], v[112:113] neg_lo:[1,0,0] neg_hi:[1,0,0]
	ds_read_b128 v[104:107], v64 offset:14288
	s_waitcnt lgkmcnt(9)
	v_pk_fma_f32 v[114:115], v[68:69], v[16:17], v[114:115] neg_lo:[1,0,0] neg_hi:[1,0,0]
	v_pk_fma_f32 v[114:115], v[70:71], v[18:19], v[114:115] neg_lo:[1,0,0] neg_hi:[1,0,0]
	ds_read_b128 v[68:71], v64 offset:14560
	s_waitcnt lgkmcnt(9)
	v_pk_fma_f32 v[112:113], v[72:73], v[20:21], v[112:113] neg_lo:[1,0,0] neg_hi:[1,0,0]
	v_pk_fma_f32 v[112:113], v[74:75], v[22:23], v[112:113] neg_lo:[1,0,0] neg_hi:[1,0,0]
	ds_read_b128 v[72:75], v64 offset:14304
	s_waitcnt lgkmcnt(9)
	v_pk_fma_f32 v[114:115], v[76:77], v[20:21], v[114:115] neg_lo:[1,0,0] neg_hi:[1,0,0]
	v_pk_fma_f32 v[114:115], v[78:79], v[22:23], v[114:115] neg_lo:[1,0,0] neg_hi:[1,0,0]
	ds_read_b128 v[76:79], v64 offset:14576
	s_waitcnt lgkmcnt(9)
	v_pk_fma_f32 v[112:113], v[80:81], v[24:25], v[112:113] neg_lo:[1,0,0] neg_hi:[1,0,0]
	v_pk_fma_f32 v[112:113], v[82:83], v[26:27], v[112:113] neg_lo:[1,0,0] neg_hi:[1,0,0]
	ds_read_b128 v[80:83], v64 offset:14320
	s_waitcnt lgkmcnt(9)
	v_pk_fma_f32 v[114:115], v[84:85], v[24:25], v[114:115] neg_lo:[1,0,0] neg_hi:[1,0,0]
	v_pk_fma_f32 v[114:115], v[86:87], v[26:27], v[114:115] neg_lo:[1,0,0] neg_hi:[1,0,0]
	ds_read_b128 v[84:87], v64 offset:14592
	s_waitcnt lgkmcnt(9)
	v_pk_fma_f32 v[112:113], v[88:89], v[28:29], v[112:113] neg_lo:[1,0,0] neg_hi:[1,0,0]
	v_pk_fma_f32 v[112:113], v[90:91], v[30:31], v[112:113] neg_lo:[1,0,0] neg_hi:[1,0,0]
	ds_read_b128 v[88:91], v64 offset:14336
	s_waitcnt lgkmcnt(9)
	v_pk_fma_f32 v[114:115], v[92:93], v[28:29], v[114:115] neg_lo:[1,0,0] neg_hi:[1,0,0]
	v_pk_fma_f32 v[114:115], v[94:95], v[30:31], v[114:115] neg_lo:[1,0,0] neg_hi:[1,0,0]
	ds_read_b128 v[92:95], v64 offset:14608
	s_waitcnt lgkmcnt(9)
	v_pk_fma_f32 v[112:113], v[96:97], v[32:33], v[112:113] neg_lo:[1,0,0] neg_hi:[1,0,0]
	v_pk_fma_f32 v[112:113], v[98:99], v[34:35], v[112:113] neg_lo:[1,0,0] neg_hi:[1,0,0]
	ds_read_b128 v[96:99], v64 offset:14624
	s_waitcnt lgkmcnt(9)
	v_pk_fma_f32 v[114:115], v[100:101], v[32:33], v[114:115] neg_lo:[1,0,0] neg_hi:[1,0,0]
	v_pk_fma_f32 v[114:115], v[102:103], v[34:35], v[114:115] neg_lo:[1,0,0] neg_hi:[1,0,0]
	ds_read_b128 v[100:103], v64 offset:14688
	s_waitcnt lgkmcnt(9)
	v_pk_fma_f32 v[112:113], v[104:105], v[36:37], v[112:113] neg_lo:[1,0,0] neg_hi:[1,0,0]
	v_pk_fma_f32 v[112:113], v[106:107], v[38:39], v[112:113] neg_lo:[1,0,0] neg_hi:[1,0,0]
	ds_read_b128 v[104:107], v64 offset:14960
	s_waitcnt lgkmcnt(9)
	v_pk_fma_f32 v[114:115], v[68:69], v[36:37], v[114:115] neg_lo:[1,0,0] neg_hi:[1,0,0]
	v_pk_fma_f32 v[114:115], v[70:71], v[38:39], v[114:115] neg_lo:[1,0,0] neg_hi:[1,0,0]
	ds_read_b128 v[68:71], v64 offset:14704
	s_waitcnt lgkmcnt(9)
	v_pk_fma_f32 v[112:113], v[72:73], v[40:41], v[112:113] neg_lo:[1,0,0] neg_hi:[1,0,0]
	v_pk_fma_f32 v[112:113], v[74:75], v[42:43], v[112:113] neg_lo:[1,0,0] neg_hi:[1,0,0]
	ds_read_b128 v[72:75], v64 offset:14976
	s_waitcnt lgkmcnt(9)
	v_pk_fma_f32 v[114:115], v[76:77], v[40:41], v[114:115] neg_lo:[1,0,0] neg_hi:[1,0,0]
	v_pk_fma_f32 v[114:115], v[78:79], v[42:43], v[114:115] neg_lo:[1,0,0] neg_hi:[1,0,0]
	ds_read_b128 v[76:79], v64 offset:14720
	s_waitcnt lgkmcnt(9)
	v_pk_fma_f32 v[112:113], v[80:81], v[44:45], v[112:113] neg_lo:[1,0,0] neg_hi:[1,0,0]
	v_pk_fma_f32 v[112:113], v[82:83], v[46:47], v[112:113] neg_lo:[1,0,0] neg_hi:[1,0,0]
	ds_read_b128 v[80:83], v64 offset:14992
	s_waitcnt lgkmcnt(9)
	v_pk_fma_f32 v[114:115], v[84:85], v[44:45], v[114:115] neg_lo:[1,0,0] neg_hi:[1,0,0]
	v_pk_fma_f32 v[114:115], v[86:87], v[46:47], v[114:115] neg_lo:[1,0,0] neg_hi:[1,0,0]
	ds_read_b128 v[84:87], v64 offset:14736
	s_waitcnt lgkmcnt(9)
	v_pk_fma_f32 v[112:113], v[88:89], v[48:49], v[112:113] neg_lo:[1,0,0] neg_hi:[1,0,0]
	v_pk_fma_f32 v[112:113], v[90:91], v[50:51], v[112:113] neg_lo:[1,0,0] neg_hi:[1,0,0]
	v_add_f32_e32 v112, v112, v113
	v_add_f32_e32 v52, v207, v112
	ds_read_b128 v[88:91], v64 offset:15008
	s_waitcnt lgkmcnt(9)
	v_pk_fma_f32 v[114:115], v[92:93], v[48:49], v[114:115] neg_lo:[1,0,0] neg_hi:[1,0,0]
	v_pk_fma_f32 v[114:115], v[94:95], v[50:51], v[114:115] neg_lo:[1,0,0] neg_hi:[1,0,0]
	ds_read_b128 v[92:95], v64 offset:14752
	s_waitcnt lgkmcnt(9)
	v_fma_f32 v114, -v96, v52, v114
	v_add_f32_e32 v114, v114, v115
	v_add_f32_e32 v53, v208, v114
	ds_read_b128 v[96:99], v64 offset:15024
	s_waitcnt lgkmcnt(9)
	v_pk_mul_f32 v[108:109], v[100:101], v[0:1] neg_lo:[1,0] neg_hi:[1,0]
	v_pk_fma_f32 v[108:109], v[102:103], v[2:3], v[108:109] neg_lo:[1,0,0] neg_hi:[1,0,0]
	ds_read_b128 v[100:103], v64 offset:14768
	s_waitcnt lgkmcnt(9)
	v_pk_mul_f32 v[110:111], v[104:105], v[0:1] neg_lo:[1,0] neg_hi:[1,0]
	v_pk_fma_f32 v[110:111], v[106:107], v[2:3], v[110:111] neg_lo:[1,0,0] neg_hi:[1,0,0]
	ds_read_b128 v[104:107], v64 offset:15040
	s_waitcnt lgkmcnt(9)
	v_pk_fma_f32 v[108:109], v[68:69], v[4:5], v[108:109] neg_lo:[1,0,0] neg_hi:[1,0,0]
	v_pk_fma_f32 v[108:109], v[70:71], v[6:7], v[108:109] neg_lo:[1,0,0] neg_hi:[1,0,0]
	ds_read_b128 v[68:71], v64 offset:14784
	s_waitcnt lgkmcnt(9)
	v_pk_fma_f32 v[110:111], v[72:73], v[4:5], v[110:111] neg_lo:[1,0,0] neg_hi:[1,0,0]
	v_pk_fma_f32 v[110:111], v[74:75], v[6:7], v[110:111] neg_lo:[1,0,0] neg_hi:[1,0,0]
	ds_read_b128 v[72:75], v64 offset:15056
	s_waitcnt lgkmcnt(9)
	v_pk_fma_f32 v[108:109], v[76:77], v[8:9], v[108:109] neg_lo:[1,0,0] neg_hi:[1,0,0]
	v_pk_fma_f32 v[108:109], v[78:79], v[10:11], v[108:109] neg_lo:[1,0,0] neg_hi:[1,0,0]
	ds_read_b128 v[76:79], v64 offset:14800
	s_waitcnt lgkmcnt(9)
	v_pk_fma_f32 v[110:111], v[80:81], v[8:9], v[110:111] neg_lo:[1,0,0] neg_hi:[1,0,0]
	v_pk_fma_f32 v[110:111], v[82:83], v[10:11], v[110:111] neg_lo:[1,0,0] neg_hi:[1,0,0]
	ds_read_b128 v[80:83], v64 offset:15072
	s_waitcnt lgkmcnt(9)
	v_pk_fma_f32 v[108:109], v[84:85], v[12:13], v[108:109] neg_lo:[1,0,0] neg_hi:[1,0,0]
	v_pk_fma_f32 v[108:109], v[86:87], v[14:15], v[108:109] neg_lo:[1,0,0] neg_hi:[1,0,0]
	ds_read_b128 v[84:87], v64 offset:14816
	s_waitcnt lgkmcnt(9)
	v_pk_fma_f32 v[110:111], v[88:89], v[12:13], v[110:111] neg_lo:[1,0,0] neg_hi:[1,0,0]
	v_pk_fma_f32 v[110:111], v[90:91], v[14:15], v[110:111] neg_lo:[1,0,0] neg_hi:[1,0,0]
	ds_read_b128 v[88:91], v64 offset:15088
	s_waitcnt lgkmcnt(9)
	v_pk_fma_f32 v[108:109], v[92:93], v[16:17], v[108:109] neg_lo:[1,0,0] neg_hi:[1,0,0]
	v_pk_fma_f32 v[108:109], v[94:95], v[18:19], v[108:109] neg_lo:[1,0,0] neg_hi:[1,0,0]
	ds_read_b128 v[92:95], v64 offset:14832
	s_waitcnt lgkmcnt(9)
	v_pk_fma_f32 v[110:111], v[96:97], v[16:17], v[110:111] neg_lo:[1,0,0] neg_hi:[1,0,0]
	v_pk_fma_f32 v[110:111], v[98:99], v[18:19], v[110:111] neg_lo:[1,0,0] neg_hi:[1,0,0]
	ds_read_b128 v[96:99], v64 offset:15104
	s_waitcnt lgkmcnt(9)
	v_pk_fma_f32 v[108:109], v[100:101], v[20:21], v[108:109] neg_lo:[1,0,0] neg_hi:[1,0,0]
	v_pk_fma_f32 v[108:109], v[102:103], v[22:23], v[108:109] neg_lo:[1,0,0] neg_hi:[1,0,0]
	ds_read_b128 v[100:103], v64 offset:14848
	s_waitcnt lgkmcnt(9)
	v_pk_fma_f32 v[110:111], v[104:105], v[20:21], v[110:111] neg_lo:[1,0,0] neg_hi:[1,0,0]
	v_pk_fma_f32 v[110:111], v[106:107], v[22:23], v[110:111] neg_lo:[1,0,0] neg_hi:[1,0,0]
	ds_read_b128 v[104:107], v64 offset:15120
	s_waitcnt lgkmcnt(9)
	v_pk_fma_f32 v[108:109], v[68:69], v[24:25], v[108:109] neg_lo:[1,0,0] neg_hi:[1,0,0]
	v_pk_fma_f32 v[108:109], v[70:71], v[26:27], v[108:109] neg_lo:[1,0,0] neg_hi:[1,0,0]
	ds_read_b128 v[68:71], v64 offset:14864
	s_waitcnt lgkmcnt(9)
	v_pk_fma_f32 v[110:111], v[72:73], v[24:25], v[110:111] neg_lo:[1,0,0] neg_hi:[1,0,0]
	v_pk_fma_f32 v[110:111], v[74:75], v[26:27], v[110:111] neg_lo:[1,0,0] neg_hi:[1,0,0]
	ds_read_b128 v[72:75], v64 offset:15136
	s_waitcnt lgkmcnt(9)
	v_pk_fma_f32 v[108:109], v[76:77], v[28:29], v[108:109] neg_lo:[1,0,0] neg_hi:[1,0,0]
	v_pk_fma_f32 v[108:109], v[78:79], v[30:31], v[108:109] neg_lo:[1,0,0] neg_hi:[1,0,0]
	ds_read_b128 v[76:79], v64 offset:14880
	s_waitcnt lgkmcnt(9)
	v_pk_fma_f32 v[110:111], v[80:81], v[28:29], v[110:111] neg_lo:[1,0,0] neg_hi:[1,0,0]
	v_pk_fma_f32 v[110:111], v[82:83], v[30:31], v[110:111] neg_lo:[1,0,0] neg_hi:[1,0,0]
	ds_read_b128 v[80:83], v64 offset:15152
	s_waitcnt lgkmcnt(9)
	v_pk_fma_f32 v[108:109], v[84:85], v[32:33], v[108:109] neg_lo:[1,0,0] neg_hi:[1,0,0]
	v_pk_fma_f32 v[108:109], v[86:87], v[34:35], v[108:109] neg_lo:[1,0,0] neg_hi:[1,0,0]
	ds_read_b128 v[84:87], v64 offset:14896
	s_waitcnt lgkmcnt(9)
	v_pk_fma_f32 v[110:111], v[88:89], v[32:33], v[110:111] neg_lo:[1,0,0] neg_hi:[1,0,0]
	v_pk_fma_f32 v[110:111], v[90:91], v[34:35], v[110:111] neg_lo:[1,0,0] neg_hi:[1,0,0]
	ds_read_b128 v[88:91], v64 offset:15168
	s_waitcnt lgkmcnt(9)
	v_pk_fma_f32 v[108:109], v[92:93], v[36:37], v[108:109] neg_lo:[1,0,0] neg_hi:[1,0,0]
	v_pk_fma_f32 v[108:109], v[94:95], v[38:39], v[108:109] neg_lo:[1,0,0] neg_hi:[1,0,0]
	ds_read_b128 v[92:95], v64 offset:15232
	s_waitcnt lgkmcnt(9)
	v_pk_fma_f32 v[110:111], v[96:97], v[36:37], v[110:111] neg_lo:[1,0,0] neg_hi:[1,0,0]
	v_pk_fma_f32 v[110:111], v[98:99], v[38:39], v[110:111] neg_lo:[1,0,0] neg_hi:[1,0,0]
	ds_read_b128 v[96:99], v64 offset:15504
	s_waitcnt lgkmcnt(9)
	v_pk_fma_f32 v[108:109], v[100:101], v[40:41], v[108:109] neg_lo:[1,0,0] neg_hi:[1,0,0]
	v_pk_fma_f32 v[108:109], v[102:103], v[42:43], v[108:109] neg_lo:[1,0,0] neg_hi:[1,0,0]
	ds_read_b128 v[100:103], v64 offset:15248
	s_waitcnt lgkmcnt(9)
	v_pk_fma_f32 v[110:111], v[104:105], v[40:41], v[110:111] neg_lo:[1,0,0] neg_hi:[1,0,0]
	v_pk_fma_f32 v[110:111], v[106:107], v[42:43], v[110:111] neg_lo:[1,0,0] neg_hi:[1,0,0]
	ds_read_b128 v[104:107], v64 offset:15520
	s_waitcnt lgkmcnt(9)
	v_pk_fma_f32 v[108:109], v[68:69], v[44:45], v[108:109] neg_lo:[1,0,0] neg_hi:[1,0,0]
	v_pk_fma_f32 v[108:109], v[70:71], v[46:47], v[108:109] neg_lo:[1,0,0] neg_hi:[1,0,0]
	ds_read_b128 v[68:71], v64 offset:15264
	s_waitcnt lgkmcnt(9)
	v_pk_fma_f32 v[110:111], v[72:73], v[44:45], v[110:111] neg_lo:[1,0,0] neg_hi:[1,0,0]
	v_pk_fma_f32 v[110:111], v[74:75], v[46:47], v[110:111] neg_lo:[1,0,0] neg_hi:[1,0,0]
	ds_read_b128 v[72:75], v64 offset:15536
	s_waitcnt lgkmcnt(9)
	v_pk_fma_f32 v[108:109], v[76:77], v[48:49], v[108:109] neg_lo:[1,0,0] neg_hi:[1,0,0]
	v_pk_fma_f32 v[108:109], v[78:79], v[50:51], v[108:109] neg_lo:[1,0,0] neg_hi:[1,0,0]
	ds_read_b128 v[76:79], v64 offset:15280
	s_waitcnt lgkmcnt(9)
	v_pk_fma_f32 v[110:111], v[80:81], v[48:49], v[110:111] neg_lo:[1,0,0] neg_hi:[1,0,0]
	v_pk_fma_f32 v[110:111], v[82:83], v[50:51], v[110:111] neg_lo:[1,0,0] neg_hi:[1,0,0]
	ds_read_b128 v[80:83], v64 offset:15552
	s_waitcnt lgkmcnt(9)
	v_pk_fma_f32 v[108:109], v[84:85], v[52:53], v[108:109] neg_lo:[1,0,0] neg_hi:[1,0,0]
	v_add_f32_e32 v108, v108, v109
	v_add_f32_e32 v54, v209, v108
	ds_read_b128 v[84:87], v64 offset:15296
	s_waitcnt lgkmcnt(9)
	v_pk_fma_f32 v[110:111], v[88:89], v[52:53], v[110:111] neg_lo:[1,0,0] neg_hi:[1,0,0]
	v_fma_f32 v110, -v90, v54, v110
	v_add_f32_e32 v110, v110, v111
	v_add_f32_e32 v55, v210, v110
	ds_read_b128 v[88:91], v64 offset:15568
	s_waitcnt lgkmcnt(9)
	v_pk_mul_f32 v[112:113], v[92:93], v[0:1] neg_lo:[1,0] neg_hi:[1,0]
	v_pk_fma_f32 v[112:113], v[94:95], v[2:3], v[112:113] neg_lo:[1,0,0] neg_hi:[1,0,0]
	ds_read_b128 v[92:95], v64 offset:15312
	s_waitcnt lgkmcnt(9)
	v_pk_mul_f32 v[114:115], v[96:97], v[0:1] neg_lo:[1,0] neg_hi:[1,0]
	v_pk_fma_f32 v[114:115], v[98:99], v[2:3], v[114:115] neg_lo:[1,0,0] neg_hi:[1,0,0]
	ds_read_b128 v[96:99], v64 offset:15584
	s_waitcnt lgkmcnt(9)
	v_pk_fma_f32 v[112:113], v[100:101], v[4:5], v[112:113] neg_lo:[1,0,0] neg_hi:[1,0,0]
	v_pk_fma_f32 v[112:113], v[102:103], v[6:7], v[112:113] neg_lo:[1,0,0] neg_hi:[1,0,0]
	ds_read_b128 v[100:103], v64 offset:15328
	s_waitcnt lgkmcnt(9)
	v_pk_fma_f32 v[114:115], v[104:105], v[4:5], v[114:115] neg_lo:[1,0,0] neg_hi:[1,0,0]
	v_pk_fma_f32 v[114:115], v[106:107], v[6:7], v[114:115] neg_lo:[1,0,0] neg_hi:[1,0,0]
	ds_read_b128 v[104:107], v64 offset:15600
	s_waitcnt lgkmcnt(9)
	v_pk_fma_f32 v[112:113], v[68:69], v[8:9], v[112:113] neg_lo:[1,0,0] neg_hi:[1,0,0]
	v_pk_fma_f32 v[112:113], v[70:71], v[10:11], v[112:113] neg_lo:[1,0,0] neg_hi:[1,0,0]
	ds_read_b128 v[68:71], v64 offset:15344
	s_waitcnt lgkmcnt(9)
	v_pk_fma_f32 v[114:115], v[72:73], v[8:9], v[114:115] neg_lo:[1,0,0] neg_hi:[1,0,0]
	v_pk_fma_f32 v[114:115], v[74:75], v[10:11], v[114:115] neg_lo:[1,0,0] neg_hi:[1,0,0]
	ds_read_b128 v[72:75], v64 offset:15616
	s_waitcnt lgkmcnt(9)
	v_pk_fma_f32 v[112:113], v[76:77], v[12:13], v[112:113] neg_lo:[1,0,0] neg_hi:[1,0,0]
	v_pk_fma_f32 v[112:113], v[78:79], v[14:15], v[112:113] neg_lo:[1,0,0] neg_hi:[1,0,0]
	ds_read_b128 v[76:79], v64 offset:15360
	s_waitcnt lgkmcnt(9)
	v_pk_fma_f32 v[114:115], v[80:81], v[12:13], v[114:115] neg_lo:[1,0,0] neg_hi:[1,0,0]
	v_pk_fma_f32 v[114:115], v[82:83], v[14:15], v[114:115] neg_lo:[1,0,0] neg_hi:[1,0,0]
	ds_read_b128 v[80:83], v64 offset:15632
	s_waitcnt lgkmcnt(9)
	v_pk_fma_f32 v[112:113], v[84:85], v[16:17], v[112:113] neg_lo:[1,0,0] neg_hi:[1,0,0]
	v_pk_fma_f32 v[112:113], v[86:87], v[18:19], v[112:113] neg_lo:[1,0,0] neg_hi:[1,0,0]
	ds_read_b128 v[84:87], v64 offset:15376
	s_waitcnt lgkmcnt(9)
	v_pk_fma_f32 v[114:115], v[88:89], v[16:17], v[114:115] neg_lo:[1,0,0] neg_hi:[1,0,0]
	v_pk_fma_f32 v[114:115], v[90:91], v[18:19], v[114:115] neg_lo:[1,0,0] neg_hi:[1,0,0]
	ds_read_b128 v[88:91], v64 offset:15648
	s_waitcnt lgkmcnt(9)
	v_pk_fma_f32 v[112:113], v[92:93], v[20:21], v[112:113] neg_lo:[1,0,0] neg_hi:[1,0,0]
	v_pk_fma_f32 v[112:113], v[94:95], v[22:23], v[112:113] neg_lo:[1,0,0] neg_hi:[1,0,0]
	ds_read_b128 v[92:95], v64 offset:15392
	s_waitcnt lgkmcnt(9)
	v_pk_fma_f32 v[114:115], v[96:97], v[20:21], v[114:115] neg_lo:[1,0,0] neg_hi:[1,0,0]
	v_pk_fma_f32 v[114:115], v[98:99], v[22:23], v[114:115] neg_lo:[1,0,0] neg_hi:[1,0,0]
	ds_read_b128 v[96:99], v64 offset:15664
	s_waitcnt lgkmcnt(9)
	v_pk_fma_f32 v[112:113], v[100:101], v[24:25], v[112:113] neg_lo:[1,0,0] neg_hi:[1,0,0]
	v_pk_fma_f32 v[112:113], v[102:103], v[26:27], v[112:113] neg_lo:[1,0,0] neg_hi:[1,0,0]
	ds_read_b128 v[100:103], v64 offset:15408
	s_waitcnt lgkmcnt(9)
	v_pk_fma_f32 v[114:115], v[104:105], v[24:25], v[114:115] neg_lo:[1,0,0] neg_hi:[1,0,0]
	v_pk_fma_f32 v[114:115], v[106:107], v[26:27], v[114:115] neg_lo:[1,0,0] neg_hi:[1,0,0]
	ds_read_b128 v[104:107], v64 offset:15680
	s_waitcnt lgkmcnt(9)
	v_pk_fma_f32 v[112:113], v[68:69], v[28:29], v[112:113] neg_lo:[1,0,0] neg_hi:[1,0,0]
	v_pk_fma_f32 v[112:113], v[70:71], v[30:31], v[112:113] neg_lo:[1,0,0] neg_hi:[1,0,0]
	ds_read_b128 v[68:71], v64 offset:15424
	s_waitcnt lgkmcnt(9)
	v_pk_fma_f32 v[114:115], v[72:73], v[28:29], v[114:115] neg_lo:[1,0,0] neg_hi:[1,0,0]
	v_pk_fma_f32 v[114:115], v[74:75], v[30:31], v[114:115] neg_lo:[1,0,0] neg_hi:[1,0,0]
	ds_read_b128 v[72:75], v64 offset:15696
	s_waitcnt lgkmcnt(9)
	v_pk_fma_f32 v[112:113], v[76:77], v[32:33], v[112:113] neg_lo:[1,0,0] neg_hi:[1,0,0]
	v_pk_fma_f32 v[112:113], v[78:79], v[34:35], v[112:113] neg_lo:[1,0,0] neg_hi:[1,0,0]
	ds_read_b128 v[76:79], v64 offset:15440
	s_waitcnt lgkmcnt(9)
	v_pk_fma_f32 v[114:115], v[80:81], v[32:33], v[114:115] neg_lo:[1,0,0] neg_hi:[1,0,0]
	v_pk_fma_f32 v[114:115], v[82:83], v[34:35], v[114:115] neg_lo:[1,0,0] neg_hi:[1,0,0]
	ds_read_b128 v[80:83], v64 offset:15712
	s_waitcnt lgkmcnt(9)
	v_pk_fma_f32 v[112:113], v[84:85], v[36:37], v[112:113] neg_lo:[1,0,0] neg_hi:[1,0,0]
	v_pk_fma_f32 v[112:113], v[86:87], v[38:39], v[112:113] neg_lo:[1,0,0] neg_hi:[1,0,0]
	ds_read_b128 v[84:87], v64 offset:15728
	s_waitcnt lgkmcnt(9)
	v_pk_fma_f32 v[114:115], v[88:89], v[36:37], v[114:115] neg_lo:[1,0,0] neg_hi:[1,0,0]
	v_pk_fma_f32 v[114:115], v[90:91], v[38:39], v[114:115] neg_lo:[1,0,0] neg_hi:[1,0,0]
	ds_read_b128 v[88:91], v64 offset:15776
	s_waitcnt lgkmcnt(9)
	v_pk_fma_f32 v[112:113], v[92:93], v[40:41], v[112:113] neg_lo:[1,0,0] neg_hi:[1,0,0]
	v_pk_fma_f32 v[112:113], v[94:95], v[42:43], v[112:113] neg_lo:[1,0,0] neg_hi:[1,0,0]
	ds_read_b128 v[92:95], v64 offset:16048
	s_waitcnt lgkmcnt(9)
	v_pk_fma_f32 v[114:115], v[96:97], v[40:41], v[114:115] neg_lo:[1,0,0] neg_hi:[1,0,0]
	v_pk_fma_f32 v[114:115], v[98:99], v[42:43], v[114:115] neg_lo:[1,0,0] neg_hi:[1,0,0]
	ds_read_b128 v[96:99], v64 offset:15792
	s_waitcnt lgkmcnt(9)
	v_pk_fma_f32 v[112:113], v[100:101], v[44:45], v[112:113] neg_lo:[1,0,0] neg_hi:[1,0,0]
	v_pk_fma_f32 v[112:113], v[102:103], v[46:47], v[112:113] neg_lo:[1,0,0] neg_hi:[1,0,0]
	ds_read_b128 v[100:103], v64 offset:16064
	s_waitcnt lgkmcnt(9)
	v_pk_fma_f32 v[114:115], v[104:105], v[44:45], v[114:115] neg_lo:[1,0,0] neg_hi:[1,0,0]
	v_pk_fma_f32 v[114:115], v[106:107], v[46:47], v[114:115] neg_lo:[1,0,0] neg_hi:[1,0,0]
	ds_read_b128 v[104:107], v64 offset:15808
	s_waitcnt lgkmcnt(9)
	v_pk_fma_f32 v[112:113], v[68:69], v[48:49], v[112:113] neg_lo:[1,0,0] neg_hi:[1,0,0]
	v_pk_fma_f32 v[112:113], v[70:71], v[50:51], v[112:113] neg_lo:[1,0,0] neg_hi:[1,0,0]
	ds_read_b128 v[68:71], v64 offset:16080
	s_waitcnt lgkmcnt(9)
	v_pk_fma_f32 v[114:115], v[72:73], v[48:49], v[114:115] neg_lo:[1,0,0] neg_hi:[1,0,0]
	v_pk_fma_f32 v[114:115], v[74:75], v[50:51], v[114:115] neg_lo:[1,0,0] neg_hi:[1,0,0]
	ds_read_b128 v[72:75], v64 offset:15824
	s_waitcnt lgkmcnt(9)
	v_pk_fma_f32 v[112:113], v[76:77], v[52:53], v[112:113] neg_lo:[1,0,0] neg_hi:[1,0,0]
	v_pk_fma_f32 v[112:113], v[78:79], v[54:55], v[112:113] neg_lo:[1,0,0] neg_hi:[1,0,0]
	v_add_f32_e32 v112, v112, v113
	v_add_f32_e32 v56, v211, v112
	ds_read_b128 v[76:79], v64 offset:16096
	s_waitcnt lgkmcnt(9)
	v_pk_fma_f32 v[114:115], v[80:81], v[52:53], v[114:115] neg_lo:[1,0,0] neg_hi:[1,0,0]
	v_pk_fma_f32 v[114:115], v[82:83], v[54:55], v[114:115] neg_lo:[1,0,0] neg_hi:[1,0,0]
	ds_read_b128 v[80:83], v64 offset:15840
	s_waitcnt lgkmcnt(9)
	v_fma_f32 v114, -v84, v56, v114
	v_add_f32_e32 v114, v114, v115
	v_add_f32_e32 v57, v212, v114
	ds_read_b128 v[84:87], v64 offset:16112
	s_waitcnt lgkmcnt(9)
	v_pk_mul_f32 v[108:109], v[88:89], v[0:1] neg_lo:[1,0] neg_hi:[1,0]
	v_pk_fma_f32 v[108:109], v[90:91], v[2:3], v[108:109] neg_lo:[1,0,0] neg_hi:[1,0,0]
	ds_read_b128 v[88:91], v64 offset:15856
	s_waitcnt lgkmcnt(9)
	v_pk_mul_f32 v[110:111], v[92:93], v[0:1] neg_lo:[1,0] neg_hi:[1,0]
	v_pk_fma_f32 v[110:111], v[94:95], v[2:3], v[110:111] neg_lo:[1,0,0] neg_hi:[1,0,0]
	ds_read_b128 v[92:95], v64 offset:16128
	s_waitcnt lgkmcnt(9)
	v_pk_fma_f32 v[108:109], v[96:97], v[4:5], v[108:109] neg_lo:[1,0,0] neg_hi:[1,0,0]
	v_pk_fma_f32 v[108:109], v[98:99], v[6:7], v[108:109] neg_lo:[1,0,0] neg_hi:[1,0,0]
	ds_read_b128 v[96:99], v64 offset:15872
	s_waitcnt lgkmcnt(9)
	v_pk_fma_f32 v[110:111], v[100:101], v[4:5], v[110:111] neg_lo:[1,0,0] neg_hi:[1,0,0]
	v_pk_fma_f32 v[110:111], v[102:103], v[6:7], v[110:111] neg_lo:[1,0,0] neg_hi:[1,0,0]
	ds_read_b128 v[100:103], v64 offset:16144
	s_waitcnt lgkmcnt(9)
	v_pk_fma_f32 v[108:109], v[104:105], v[8:9], v[108:109] neg_lo:[1,0,0] neg_hi:[1,0,0]
	v_pk_fma_f32 v[108:109], v[106:107], v[10:11], v[108:109] neg_lo:[1,0,0] neg_hi:[1,0,0]
	ds_read_b128 v[104:107], v64 offset:15888
	s_waitcnt lgkmcnt(9)
	v_pk_fma_f32 v[110:111], v[68:69], v[8:9], v[110:111] neg_lo:[1,0,0] neg_hi:[1,0,0]
	v_pk_fma_f32 v[110:111], v[70:71], v[10:11], v[110:111] neg_lo:[1,0,0] neg_hi:[1,0,0]
	ds_read_b128 v[68:71], v64 offset:16160
	s_waitcnt lgkmcnt(9)
	v_pk_fma_f32 v[108:109], v[72:73], v[12:13], v[108:109] neg_lo:[1,0,0] neg_hi:[1,0,0]
	v_pk_fma_f32 v[108:109], v[74:75], v[14:15], v[108:109] neg_lo:[1,0,0] neg_hi:[1,0,0]
	ds_read_b128 v[72:75], v64 offset:15904
	s_waitcnt lgkmcnt(9)
	v_pk_fma_f32 v[110:111], v[76:77], v[12:13], v[110:111] neg_lo:[1,0,0] neg_hi:[1,0,0]
	v_pk_fma_f32 v[110:111], v[78:79], v[14:15], v[110:111] neg_lo:[1,0,0] neg_hi:[1,0,0]
	ds_read_b128 v[76:79], v64 offset:16176
	s_waitcnt lgkmcnt(9)
	v_pk_fma_f32 v[108:109], v[80:81], v[16:17], v[108:109] neg_lo:[1,0,0] neg_hi:[1,0,0]
	v_pk_fma_f32 v[108:109], v[82:83], v[18:19], v[108:109] neg_lo:[1,0,0] neg_hi:[1,0,0]
	ds_read_b128 v[80:83], v64 offset:15920
	s_waitcnt lgkmcnt(9)
	v_pk_fma_f32 v[110:111], v[84:85], v[16:17], v[110:111] neg_lo:[1,0,0] neg_hi:[1,0,0]
	v_pk_fma_f32 v[110:111], v[86:87], v[18:19], v[110:111] neg_lo:[1,0,0] neg_hi:[1,0,0]
	ds_read_b128 v[84:87], v64 offset:16192
	s_waitcnt lgkmcnt(9)
	v_pk_fma_f32 v[108:109], v[88:89], v[20:21], v[108:109] neg_lo:[1,0,0] neg_hi:[1,0,0]
	v_pk_fma_f32 v[108:109], v[90:91], v[22:23], v[108:109] neg_lo:[1,0,0] neg_hi:[1,0,0]
	ds_read_b128 v[88:91], v64 offset:15936
	s_waitcnt lgkmcnt(9)
	v_pk_fma_f32 v[110:111], v[92:93], v[20:21], v[110:111] neg_lo:[1,0,0] neg_hi:[1,0,0]
	v_pk_fma_f32 v[110:111], v[94:95], v[22:23], v[110:111] neg_lo:[1,0,0] neg_hi:[1,0,0]
	ds_read_b128 v[92:95], v64 offset:16208
	s_waitcnt lgkmcnt(9)
	v_pk_fma_f32 v[108:109], v[96:97], v[24:25], v[108:109] neg_lo:[1,0,0] neg_hi:[1,0,0]
	v_pk_fma_f32 v[108:109], v[98:99], v[26:27], v[108:109] neg_lo:[1,0,0] neg_hi:[1,0,0]
	ds_read_b128 v[96:99], v64 offset:15952
	s_waitcnt lgkmcnt(9)
	v_pk_fma_f32 v[110:111], v[100:101], v[24:25], v[110:111] neg_lo:[1,0,0] neg_hi:[1,0,0]
	v_pk_fma_f32 v[110:111], v[102:103], v[26:27], v[110:111] neg_lo:[1,0,0] neg_hi:[1,0,0]
	ds_read_b128 v[100:103], v64 offset:16224
	s_waitcnt lgkmcnt(9)
	v_pk_fma_f32 v[108:109], v[104:105], v[28:29], v[108:109] neg_lo:[1,0,0] neg_hi:[1,0,0]
	v_pk_fma_f32 v[108:109], v[106:107], v[30:31], v[108:109] neg_lo:[1,0,0] neg_hi:[1,0,0]
	ds_read_b128 v[104:107], v64 offset:15968
	s_waitcnt lgkmcnt(9)
	v_pk_fma_f32 v[110:111], v[68:69], v[28:29], v[110:111] neg_lo:[1,0,0] neg_hi:[1,0,0]
	v_pk_fma_f32 v[110:111], v[70:71], v[30:31], v[110:111] neg_lo:[1,0,0] neg_hi:[1,0,0]
	ds_read_b128 v[68:71], v64 offset:16240
	s_waitcnt lgkmcnt(9)
	v_pk_fma_f32 v[108:109], v[72:73], v[32:33], v[108:109] neg_lo:[1,0,0] neg_hi:[1,0,0]
	v_pk_fma_f32 v[108:109], v[74:75], v[34:35], v[108:109] neg_lo:[1,0,0] neg_hi:[1,0,0]
	ds_read_b128 v[72:75], v64 offset:15984
	s_waitcnt lgkmcnt(9)
	v_pk_fma_f32 v[110:111], v[76:77], v[32:33], v[110:111] neg_lo:[1,0,0] neg_hi:[1,0,0]
	v_pk_fma_f32 v[110:111], v[78:79], v[34:35], v[110:111] neg_lo:[1,0,0] neg_hi:[1,0,0]
	ds_read_b128 v[76:79], v64 offset:16256
	s_waitcnt lgkmcnt(9)
	v_pk_fma_f32 v[108:109], v[80:81], v[36:37], v[108:109] neg_lo:[1,0,0] neg_hi:[1,0,0]
	v_pk_fma_f32 v[108:109], v[82:83], v[38:39], v[108:109] neg_lo:[1,0,0] neg_hi:[1,0,0]
	ds_read_b128 v[80:83], v64 offset:16000
	s_waitcnt lgkmcnt(9)
	v_pk_fma_f32 v[110:111], v[84:85], v[36:37], v[110:111] neg_lo:[1,0,0] neg_hi:[1,0,0]
	v_pk_fma_f32 v[110:111], v[86:87], v[38:39], v[110:111] neg_lo:[1,0,0] neg_hi:[1,0,0]
	ds_read_b128 v[84:87], v64 offset:16272
	s_waitcnt lgkmcnt(9)
	v_pk_fma_f32 v[108:109], v[88:89], v[40:41], v[108:109] neg_lo:[1,0,0] neg_hi:[1,0,0]
	v_pk_fma_f32 v[108:109], v[90:91], v[42:43], v[108:109] neg_lo:[1,0,0] neg_hi:[1,0,0]
	ds_read_b128 v[88:91], v64 offset:16320
	s_waitcnt lgkmcnt(9)
	v_pk_fma_f32 v[110:111], v[92:93], v[40:41], v[110:111] neg_lo:[1,0,0] neg_hi:[1,0,0]
	v_pk_fma_f32 v[110:111], v[94:95], v[42:43], v[110:111] neg_lo:[1,0,0] neg_hi:[1,0,0]
	ds_read_b128 v[92:95], v64 offset:16592
	s_waitcnt lgkmcnt(9)
	v_pk_fma_f32 v[108:109], v[96:97], v[44:45], v[108:109] neg_lo:[1,0,0] neg_hi:[1,0,0]
	v_pk_fma_f32 v[108:109], v[98:99], v[46:47], v[108:109] neg_lo:[1,0,0] neg_hi:[1,0,0]
	ds_read_b128 v[96:99], v64 offset:16336
	s_waitcnt lgkmcnt(9)
	v_pk_fma_f32 v[110:111], v[100:101], v[44:45], v[110:111] neg_lo:[1,0,0] neg_hi:[1,0,0]
	v_pk_fma_f32 v[110:111], v[102:103], v[46:47], v[110:111] neg_lo:[1,0,0] neg_hi:[1,0,0]
	ds_read_b128 v[100:103], v64 offset:16608
	s_waitcnt lgkmcnt(9)
	v_pk_fma_f32 v[108:109], v[104:105], v[48:49], v[108:109] neg_lo:[1,0,0] neg_hi:[1,0,0]
	v_pk_fma_f32 v[108:109], v[106:107], v[50:51], v[108:109] neg_lo:[1,0,0] neg_hi:[1,0,0]
	ds_read_b128 v[104:107], v64 offset:16352
	s_waitcnt lgkmcnt(9)
	v_pk_fma_f32 v[110:111], v[68:69], v[48:49], v[110:111] neg_lo:[1,0,0] neg_hi:[1,0,0]
	v_pk_fma_f32 v[110:111], v[70:71], v[50:51], v[110:111] neg_lo:[1,0,0] neg_hi:[1,0,0]
	ds_read_b128 v[68:71], v64 offset:16624
	s_waitcnt lgkmcnt(9)
	v_pk_fma_f32 v[108:109], v[72:73], v[52:53], v[108:109] neg_lo:[1,0,0] neg_hi:[1,0,0]
	v_pk_fma_f32 v[108:109], v[74:75], v[54:55], v[108:109] neg_lo:[1,0,0] neg_hi:[1,0,0]
	ds_read_b128 v[72:75], v64 offset:16368
	s_waitcnt lgkmcnt(9)
	v_pk_fma_f32 v[110:111], v[76:77], v[52:53], v[110:111] neg_lo:[1,0,0] neg_hi:[1,0,0]
	v_pk_fma_f32 v[110:111], v[78:79], v[54:55], v[110:111] neg_lo:[1,0,0] neg_hi:[1,0,0]
	ds_read_b128 v[76:79], v64 offset:16640
	s_waitcnt lgkmcnt(9)
	v_pk_fma_f32 v[108:109], v[80:81], v[56:57], v[108:109] neg_lo:[1,0,0] neg_hi:[1,0,0]
	v_add_f32_e32 v108, v108, v109
	v_add_f32_e32 v58, v213, v108
	ds_read_b128 v[80:83], v64 offset:16384
	s_waitcnt lgkmcnt(9)
	v_pk_fma_f32 v[110:111], v[84:85], v[56:57], v[110:111] neg_lo:[1,0,0] neg_hi:[1,0,0]
	v_fma_f32 v110, -v86, v58, v110
	v_add_f32_e32 v110, v110, v111
	v_add_f32_e32 v59, v214, v110
	ds_read_b128 v[84:87], v64 offset:16656
	s_waitcnt lgkmcnt(9)
	v_pk_mul_f32 v[112:113], v[88:89], v[0:1] neg_lo:[1,0] neg_hi:[1,0]
	v_pk_fma_f32 v[112:113], v[90:91], v[2:3], v[112:113] neg_lo:[1,0,0] neg_hi:[1,0,0]
	ds_read_b128 v[88:91], v64 offset:16400
	s_waitcnt lgkmcnt(9)
	v_pk_mul_f32 v[114:115], v[92:93], v[0:1] neg_lo:[1,0] neg_hi:[1,0]
	v_pk_fma_f32 v[114:115], v[94:95], v[2:3], v[114:115] neg_lo:[1,0,0] neg_hi:[1,0,0]
	ds_read_b128 v[92:95], v64 offset:16672
	s_waitcnt lgkmcnt(9)
	v_pk_fma_f32 v[112:113], v[96:97], v[4:5], v[112:113] neg_lo:[1,0,0] neg_hi:[1,0,0]
	v_pk_fma_f32 v[112:113], v[98:99], v[6:7], v[112:113] neg_lo:[1,0,0] neg_hi:[1,0,0]
	ds_read_b128 v[96:99], v64 offset:16416
	s_waitcnt lgkmcnt(9)
	v_pk_fma_f32 v[114:115], v[100:101], v[4:5], v[114:115] neg_lo:[1,0,0] neg_hi:[1,0,0]
	v_pk_fma_f32 v[114:115], v[102:103], v[6:7], v[114:115] neg_lo:[1,0,0] neg_hi:[1,0,0]
	ds_read_b128 v[100:103], v64 offset:16688
	s_waitcnt lgkmcnt(9)
	v_pk_fma_f32 v[112:113], v[104:105], v[8:9], v[112:113] neg_lo:[1,0,0] neg_hi:[1,0,0]
	v_pk_fma_f32 v[112:113], v[106:107], v[10:11], v[112:113] neg_lo:[1,0,0] neg_hi:[1,0,0]
	ds_read_b128 v[104:107], v64 offset:16432
	s_waitcnt lgkmcnt(9)
	v_pk_fma_f32 v[114:115], v[68:69], v[8:9], v[114:115] neg_lo:[1,0,0] neg_hi:[1,0,0]
	v_pk_fma_f32 v[114:115], v[70:71], v[10:11], v[114:115] neg_lo:[1,0,0] neg_hi:[1,0,0]
	ds_read_b128 v[68:71], v64 offset:16704
	s_waitcnt lgkmcnt(9)
	v_pk_fma_f32 v[112:113], v[72:73], v[12:13], v[112:113] neg_lo:[1,0,0] neg_hi:[1,0,0]
	v_pk_fma_f32 v[112:113], v[74:75], v[14:15], v[112:113] neg_lo:[1,0,0] neg_hi:[1,0,0]
	ds_read_b128 v[72:75], v64 offset:16448
	s_waitcnt lgkmcnt(9)
	v_pk_fma_f32 v[114:115], v[76:77], v[12:13], v[114:115] neg_lo:[1,0,0] neg_hi:[1,0,0]
	v_pk_fma_f32 v[114:115], v[78:79], v[14:15], v[114:115] neg_lo:[1,0,0] neg_hi:[1,0,0]
	ds_read_b128 v[76:79], v64 offset:16720
	s_waitcnt lgkmcnt(9)
	v_pk_fma_f32 v[112:113], v[80:81], v[16:17], v[112:113] neg_lo:[1,0,0] neg_hi:[1,0,0]
	v_pk_fma_f32 v[112:113], v[82:83], v[18:19], v[112:113] neg_lo:[1,0,0] neg_hi:[1,0,0]
	ds_read_b128 v[80:83], v64 offset:16464
	s_waitcnt lgkmcnt(9)
	v_pk_fma_f32 v[114:115], v[84:85], v[16:17], v[114:115] neg_lo:[1,0,0] neg_hi:[1,0,0]
	v_pk_fma_f32 v[114:115], v[86:87], v[18:19], v[114:115] neg_lo:[1,0,0] neg_hi:[1,0,0]
	ds_read_b128 v[84:87], v64 offset:16736
	s_waitcnt lgkmcnt(9)
	v_pk_fma_f32 v[112:113], v[88:89], v[20:21], v[112:113] neg_lo:[1,0,0] neg_hi:[1,0,0]
	v_pk_fma_f32 v[112:113], v[90:91], v[22:23], v[112:113] neg_lo:[1,0,0] neg_hi:[1,0,0]
	ds_read_b128 v[88:91], v64 offset:16480
	s_waitcnt lgkmcnt(9)
	v_pk_fma_f32 v[114:115], v[92:93], v[20:21], v[114:115] neg_lo:[1,0,0] neg_hi:[1,0,0]
	v_pk_fma_f32 v[114:115], v[94:95], v[22:23], v[114:115] neg_lo:[1,0,0] neg_hi:[1,0,0]
	ds_read_b128 v[92:95], v64 offset:16752
	s_waitcnt lgkmcnt(9)
	v_pk_fma_f32 v[112:113], v[96:97], v[24:25], v[112:113] neg_lo:[1,0,0] neg_hi:[1,0,0]
	v_pk_fma_f32 v[112:113], v[98:99], v[26:27], v[112:113] neg_lo:[1,0,0] neg_hi:[1,0,0]
	ds_read_b128 v[96:99], v64 offset:16496
	s_waitcnt lgkmcnt(9)
	v_pk_fma_f32 v[114:115], v[100:101], v[24:25], v[114:115] neg_lo:[1,0,0] neg_hi:[1,0,0]
	v_pk_fma_f32 v[114:115], v[102:103], v[26:27], v[114:115] neg_lo:[1,0,0] neg_hi:[1,0,0]
	ds_read_b128 v[100:103], v64 offset:16768
	s_waitcnt lgkmcnt(9)
	v_pk_fma_f32 v[112:113], v[104:105], v[28:29], v[112:113] neg_lo:[1,0,0] neg_hi:[1,0,0]
	v_pk_fma_f32 v[112:113], v[106:107], v[30:31], v[112:113] neg_lo:[1,0,0] neg_hi:[1,0,0]
	ds_read_b128 v[104:107], v64 offset:16512
	s_waitcnt lgkmcnt(9)
	v_pk_fma_f32 v[114:115], v[68:69], v[28:29], v[114:115] neg_lo:[1,0,0] neg_hi:[1,0,0]
	v_pk_fma_f32 v[114:115], v[70:71], v[30:31], v[114:115] neg_lo:[1,0,0] neg_hi:[1,0,0]
	ds_read_b128 v[68:71], v64 offset:16784
	s_waitcnt lgkmcnt(9)
	v_pk_fma_f32 v[112:113], v[72:73], v[32:33], v[112:113] neg_lo:[1,0,0] neg_hi:[1,0,0]
	v_pk_fma_f32 v[112:113], v[74:75], v[34:35], v[112:113] neg_lo:[1,0,0] neg_hi:[1,0,0]
	ds_read_b128 v[72:75], v64 offset:16528
	s_waitcnt lgkmcnt(9)
	v_pk_fma_f32 v[114:115], v[76:77], v[32:33], v[114:115] neg_lo:[1,0,0] neg_hi:[1,0,0]
	v_pk_fma_f32 v[114:115], v[78:79], v[34:35], v[114:115] neg_lo:[1,0,0] neg_hi:[1,0,0]
	ds_read_b128 v[76:79], v64 offset:16800
	s_waitcnt lgkmcnt(9)
	v_pk_fma_f32 v[112:113], v[80:81], v[36:37], v[112:113] neg_lo:[1,0,0] neg_hi:[1,0,0]
	v_pk_fma_f32 v[112:113], v[82:83], v[38:39], v[112:113] neg_lo:[1,0,0] neg_hi:[1,0,0]
	ds_read_b128 v[80:83], v64 offset:16544
	s_waitcnt lgkmcnt(9)
	v_pk_fma_f32 v[114:115], v[84:85], v[36:37], v[114:115] neg_lo:[1,0,0] neg_hi:[1,0,0]
	v_pk_fma_f32 v[114:115], v[86:87], v[38:39], v[114:115] neg_lo:[1,0,0] neg_hi:[1,0,0]
	ds_read_b128 v[84:87], v64 offset:16816
	s_waitcnt lgkmcnt(9)
	v_pk_fma_f32 v[112:113], v[88:89], v[40:41], v[112:113] neg_lo:[1,0,0] neg_hi:[1,0,0]
	v_pk_fma_f32 v[112:113], v[90:91], v[42:43], v[112:113] neg_lo:[1,0,0] neg_hi:[1,0,0]
	ds_read_b128 v[88:91], v64 offset:16832
	s_waitcnt lgkmcnt(9)
	v_pk_fma_f32 v[114:115], v[92:93], v[40:41], v[114:115] neg_lo:[1,0,0] neg_hi:[1,0,0]
	v_pk_fma_f32 v[114:115], v[94:95], v[42:43], v[114:115] neg_lo:[1,0,0] neg_hi:[1,0,0]
	ds_read_b128 v[92:95], v64 offset:16864
	s_waitcnt lgkmcnt(9)
	v_pk_fma_f32 v[112:113], v[96:97], v[44:45], v[112:113] neg_lo:[1,0,0] neg_hi:[1,0,0]
	v_pk_fma_f32 v[112:113], v[98:99], v[46:47], v[112:113] neg_lo:[1,0,0] neg_hi:[1,0,0]
	ds_read_b128 v[96:99], v64 offset:17136
	s_waitcnt lgkmcnt(9)
	v_pk_fma_f32 v[114:115], v[100:101], v[44:45], v[114:115] neg_lo:[1,0,0] neg_hi:[1,0,0]
	v_pk_fma_f32 v[114:115], v[102:103], v[46:47], v[114:115] neg_lo:[1,0,0] neg_hi:[1,0,0]
	ds_read_b128 v[100:103], v64 offset:16880
	s_waitcnt lgkmcnt(9)
	v_pk_fma_f32 v[112:113], v[104:105], v[48:49], v[112:113] neg_lo:[1,0,0] neg_hi:[1,0,0]
	v_pk_fma_f32 v[112:113], v[106:107], v[50:51], v[112:113] neg_lo:[1,0,0] neg_hi:[1,0,0]
	ds_read_b128 v[104:107], v64 offset:17152
	s_waitcnt lgkmcnt(9)
	v_pk_fma_f32 v[114:115], v[68:69], v[48:49], v[114:115] neg_lo:[1,0,0] neg_hi:[1,0,0]
	v_pk_fma_f32 v[114:115], v[70:71], v[50:51], v[114:115] neg_lo:[1,0,0] neg_hi:[1,0,0]
	ds_read_b128 v[68:71], v64 offset:16896
	s_waitcnt lgkmcnt(9)
	v_pk_fma_f32 v[112:113], v[72:73], v[52:53], v[112:113] neg_lo:[1,0,0] neg_hi:[1,0,0]
	v_pk_fma_f32 v[112:113], v[74:75], v[54:55], v[112:113] neg_lo:[1,0,0] neg_hi:[1,0,0]
	ds_read_b128 v[72:75], v64 offset:17168
	s_waitcnt lgkmcnt(9)
	v_pk_fma_f32 v[114:115], v[76:77], v[52:53], v[114:115] neg_lo:[1,0,0] neg_hi:[1,0,0]
	v_pk_fma_f32 v[114:115], v[78:79], v[54:55], v[114:115] neg_lo:[1,0,0] neg_hi:[1,0,0]
	ds_read_b128 v[76:79], v64 offset:16912
	s_waitcnt lgkmcnt(9)
	v_pk_fma_f32 v[112:113], v[80:81], v[56:57], v[112:113] neg_lo:[1,0,0] neg_hi:[1,0,0]
	v_pk_fma_f32 v[112:113], v[82:83], v[58:59], v[112:113] neg_lo:[1,0,0] neg_hi:[1,0,0]
	v_add_f32_e32 v112, v112, v113
	v_add_f32_e32 v60, v215, v112
	ds_read_b128 v[80:83], v64 offset:17184
	s_waitcnt lgkmcnt(9)
	v_pk_fma_f32 v[114:115], v[84:85], v[56:57], v[114:115] neg_lo:[1,0,0] neg_hi:[1,0,0]
	v_pk_fma_f32 v[114:115], v[86:87], v[58:59], v[114:115] neg_lo:[1,0,0] neg_hi:[1,0,0]
	ds_read_b128 v[84:87], v64 offset:16928
	s_waitcnt lgkmcnt(9)
	v_fma_f32 v114, -v88, v60, v114
	v_add_f32_e32 v114, v114, v115
	v_add_f32_e32 v61, v216, v114
	ds_read_b128 v[88:91], v64 offset:17200
	s_waitcnt lgkmcnt(9)
	v_pk_mul_f32 v[108:109], v[92:93], v[0:1] neg_lo:[1,0] neg_hi:[1,0]
	v_pk_fma_f32 v[108:109], v[94:95], v[2:3], v[108:109] neg_lo:[1,0,0] neg_hi:[1,0,0]
	ds_read_b128 v[92:95], v64 offset:16944
	s_waitcnt lgkmcnt(9)
	v_pk_mul_f32 v[110:111], v[96:97], v[0:1] neg_lo:[1,0] neg_hi:[1,0]
	v_pk_fma_f32 v[110:111], v[98:99], v[2:3], v[110:111] neg_lo:[1,0,0] neg_hi:[1,0,0]
	ds_read_b128 v[96:99], v64 offset:17216
	s_waitcnt lgkmcnt(9)
	v_pk_fma_f32 v[108:109], v[100:101], v[4:5], v[108:109] neg_lo:[1,0,0] neg_hi:[1,0,0]
	v_pk_fma_f32 v[108:109], v[102:103], v[6:7], v[108:109] neg_lo:[1,0,0] neg_hi:[1,0,0]
	ds_read_b128 v[100:103], v64 offset:16960
	s_waitcnt lgkmcnt(9)
	v_pk_fma_f32 v[110:111], v[104:105], v[4:5], v[110:111] neg_lo:[1,0,0] neg_hi:[1,0,0]
	v_pk_fma_f32 v[110:111], v[106:107], v[6:7], v[110:111] neg_lo:[1,0,0] neg_hi:[1,0,0]
	ds_read_b128 v[104:107], v64 offset:17232
	s_waitcnt lgkmcnt(9)
	v_pk_fma_f32 v[108:109], v[68:69], v[8:9], v[108:109] neg_lo:[1,0,0] neg_hi:[1,0,0]
	v_pk_fma_f32 v[108:109], v[70:71], v[10:11], v[108:109] neg_lo:[1,0,0] neg_hi:[1,0,0]
	ds_read_b128 v[68:71], v64 offset:16976
	s_waitcnt lgkmcnt(9)
	v_pk_fma_f32 v[110:111], v[72:73], v[8:9], v[110:111] neg_lo:[1,0,0] neg_hi:[1,0,0]
	v_pk_fma_f32 v[110:111], v[74:75], v[10:11], v[110:111] neg_lo:[1,0,0] neg_hi:[1,0,0]
	ds_read_b128 v[72:75], v64 offset:17248
	s_waitcnt lgkmcnt(9)
	v_pk_fma_f32 v[108:109], v[76:77], v[12:13], v[108:109] neg_lo:[1,0,0] neg_hi:[1,0,0]
	v_pk_fma_f32 v[108:109], v[78:79], v[14:15], v[108:109] neg_lo:[1,0,0] neg_hi:[1,0,0]
	ds_read_b128 v[76:79], v64 offset:16992
	s_waitcnt lgkmcnt(9)
	v_pk_fma_f32 v[110:111], v[80:81], v[12:13], v[110:111] neg_lo:[1,0,0] neg_hi:[1,0,0]
	v_pk_fma_f32 v[110:111], v[82:83], v[14:15], v[110:111] neg_lo:[1,0,0] neg_hi:[1,0,0]
	ds_read_b128 v[80:83], v64 offset:17264
	s_waitcnt lgkmcnt(9)
	v_pk_fma_f32 v[108:109], v[84:85], v[16:17], v[108:109] neg_lo:[1,0,0] neg_hi:[1,0,0]
	v_pk_fma_f32 v[108:109], v[86:87], v[18:19], v[108:109] neg_lo:[1,0,0] neg_hi:[1,0,0]
	ds_read_b128 v[84:87], v64 offset:17008
	s_waitcnt lgkmcnt(9)
	v_pk_fma_f32 v[110:111], v[88:89], v[16:17], v[110:111] neg_lo:[1,0,0] neg_hi:[1,0,0]
	v_pk_fma_f32 v[110:111], v[90:91], v[18:19], v[110:111] neg_lo:[1,0,0] neg_hi:[1,0,0]
	ds_read_b128 v[88:91], v64 offset:17280
	s_waitcnt lgkmcnt(9)
	v_pk_fma_f32 v[108:109], v[92:93], v[20:21], v[108:109] neg_lo:[1,0,0] neg_hi:[1,0,0]
	v_pk_fma_f32 v[108:109], v[94:95], v[22:23], v[108:109] neg_lo:[1,0,0] neg_hi:[1,0,0]
	ds_read_b128 v[92:95], v64 offset:17024
	s_waitcnt lgkmcnt(9)
	v_pk_fma_f32 v[110:111], v[96:97], v[20:21], v[110:111] neg_lo:[1,0,0] neg_hi:[1,0,0]
	v_pk_fma_f32 v[110:111], v[98:99], v[22:23], v[110:111] neg_lo:[1,0,0] neg_hi:[1,0,0]
	ds_read_b128 v[96:99], v64 offset:17296
	s_waitcnt lgkmcnt(9)
	v_pk_fma_f32 v[108:109], v[100:101], v[24:25], v[108:109] neg_lo:[1,0,0] neg_hi:[1,0,0]
	v_pk_fma_f32 v[108:109], v[102:103], v[26:27], v[108:109] neg_lo:[1,0,0] neg_hi:[1,0,0]
	ds_read_b128 v[100:103], v64 offset:17040
	s_waitcnt lgkmcnt(9)
	v_pk_fma_f32 v[110:111], v[104:105], v[24:25], v[110:111] neg_lo:[1,0,0] neg_hi:[1,0,0]
	v_pk_fma_f32 v[110:111], v[106:107], v[26:27], v[110:111] neg_lo:[1,0,0] neg_hi:[1,0,0]
	ds_read_b128 v[104:107], v64 offset:17312
	s_waitcnt lgkmcnt(9)
	v_pk_fma_f32 v[108:109], v[68:69], v[28:29], v[108:109] neg_lo:[1,0,0] neg_hi:[1,0,0]
	v_pk_fma_f32 v[108:109], v[70:71], v[30:31], v[108:109] neg_lo:[1,0,0] neg_hi:[1,0,0]
	ds_read_b128 v[68:71], v64 offset:17056
	s_waitcnt lgkmcnt(9)
	v_pk_fma_f32 v[110:111], v[72:73], v[28:29], v[110:111] neg_lo:[1,0,0] neg_hi:[1,0,0]
	v_pk_fma_f32 v[110:111], v[74:75], v[30:31], v[110:111] neg_lo:[1,0,0] neg_hi:[1,0,0]
	ds_read_b128 v[72:75], v64 offset:17328
	s_waitcnt lgkmcnt(9)
	v_pk_fma_f32 v[108:109], v[76:77], v[32:33], v[108:109] neg_lo:[1,0,0] neg_hi:[1,0,0]
	v_pk_fma_f32 v[108:109], v[78:79], v[34:35], v[108:109] neg_lo:[1,0,0] neg_hi:[1,0,0]
	ds_read_b128 v[76:79], v64 offset:17072
	s_waitcnt lgkmcnt(9)
	v_pk_fma_f32 v[110:111], v[80:81], v[32:33], v[110:111] neg_lo:[1,0,0] neg_hi:[1,0,0]
	v_pk_fma_f32 v[110:111], v[82:83], v[34:35], v[110:111] neg_lo:[1,0,0] neg_hi:[1,0,0]
	ds_read_b128 v[80:83], v64 offset:17344
	s_waitcnt lgkmcnt(9)
	v_pk_fma_f32 v[108:109], v[84:85], v[36:37], v[108:109] neg_lo:[1,0,0] neg_hi:[1,0,0]
	v_pk_fma_f32 v[108:109], v[86:87], v[38:39], v[108:109] neg_lo:[1,0,0] neg_hi:[1,0,0]
	ds_read_b128 v[84:87], v64 offset:17088
	s_waitcnt lgkmcnt(9)
	v_pk_fma_f32 v[110:111], v[88:89], v[36:37], v[110:111] neg_lo:[1,0,0] neg_hi:[1,0,0]
	v_pk_fma_f32 v[110:111], v[90:91], v[38:39], v[110:111] neg_lo:[1,0,0] neg_hi:[1,0,0]
	ds_read_b128 v[88:91], v64 offset:17360
	s_waitcnt lgkmcnt(9)
	v_pk_fma_f32 v[108:109], v[92:93], v[40:41], v[108:109] neg_lo:[1,0,0] neg_hi:[1,0,0]
	v_pk_fma_f32 v[108:109], v[94:95], v[42:43], v[108:109] neg_lo:[1,0,0] neg_hi:[1,0,0]
	ds_read_b128 v[92:95], v64 offset:17104
	s_waitcnt lgkmcnt(9)
	v_pk_fma_f32 v[110:111], v[96:97], v[40:41], v[110:111] neg_lo:[1,0,0] neg_hi:[1,0,0]
	v_pk_fma_f32 v[110:111], v[98:99], v[42:43], v[110:111] neg_lo:[1,0,0] neg_hi:[1,0,0]
	ds_read_b128 v[96:99], v64 offset:17376
	s_waitcnt lgkmcnt(9)
	v_pk_fma_f32 v[108:109], v[100:101], v[44:45], v[108:109] neg_lo:[1,0,0] neg_hi:[1,0,0]
	v_pk_fma_f32 v[108:109], v[102:103], v[46:47], v[108:109] neg_lo:[1,0,0] neg_hi:[1,0,0]
	s_waitcnt lgkmcnt(8)
	v_pk_fma_f32 v[110:111], v[104:105], v[44:45], v[110:111] neg_lo:[1,0,0] neg_hi:[1,0,0]
	v_pk_fma_f32 v[110:111], v[106:107], v[46:47], v[110:111] neg_lo:[1,0,0] neg_hi:[1,0,0]
	s_waitcnt lgkmcnt(7)
	v_pk_fma_f32 v[108:109], v[68:69], v[48:49], v[108:109] neg_lo:[1,0,0] neg_hi:[1,0,0]
	v_pk_fma_f32 v[108:109], v[70:71], v[50:51], v[108:109] neg_lo:[1,0,0] neg_hi:[1,0,0]
	s_waitcnt lgkmcnt(6)
	v_pk_fma_f32 v[110:111], v[72:73], v[48:49], v[110:111] neg_lo:[1,0,0] neg_hi:[1,0,0]
	v_pk_fma_f32 v[110:111], v[74:75], v[50:51], v[110:111] neg_lo:[1,0,0] neg_hi:[1,0,0]
	s_waitcnt lgkmcnt(5)
	v_pk_fma_f32 v[108:109], v[76:77], v[52:53], v[108:109] neg_lo:[1,0,0] neg_hi:[1,0,0]
	v_pk_fma_f32 v[108:109], v[78:79], v[54:55], v[108:109] neg_lo:[1,0,0] neg_hi:[1,0,0]
	s_waitcnt lgkmcnt(4)
	v_pk_fma_f32 v[110:111], v[80:81], v[52:53], v[110:111] neg_lo:[1,0,0] neg_hi:[1,0,0]
	v_pk_fma_f32 v[110:111], v[82:83], v[54:55], v[110:111] neg_lo:[1,0,0] neg_hi:[1,0,0]
	s_waitcnt lgkmcnt(3)
	v_pk_fma_f32 v[108:109], v[84:85], v[56:57], v[108:109] neg_lo:[1,0,0] neg_hi:[1,0,0]
	v_pk_fma_f32 v[108:109], v[86:87], v[58:59], v[108:109] neg_lo:[1,0,0] neg_hi:[1,0,0]
	s_waitcnt lgkmcnt(2)
	v_pk_fma_f32 v[110:111], v[88:89], v[56:57], v[110:111] neg_lo:[1,0,0] neg_hi:[1,0,0]
	v_pk_fma_f32 v[110:111], v[90:91], v[58:59], v[110:111] neg_lo:[1,0,0] neg_hi:[1,0,0]
	s_waitcnt lgkmcnt(1)
	v_pk_fma_f32 v[108:109], v[92:93], v[60:61], v[108:109] neg_lo:[1,0,0] neg_hi:[1,0,0]
	v_add_f32_e32 v108, v108, v109
	v_add_f32_e32 v62, v217, v108
	s_waitcnt lgkmcnt(0)
	v_pk_fma_f32 v[110:111], v[96:97], v[60:61], v[110:111] neg_lo:[1,0,0] neg_hi:[1,0,0]
	v_fma_f32 v110, -v98, v62, v110
	v_add_f32_e32 v110, v110, v111
	v_add_f32_e32 v63, v218, v110
	ds_write_b16 v150, v219
	v_cvt_pk_bf16_f32 v0, v1, s0
	ds_write_b16 v150, v0 offset:128
	v_cvt_pk_bf16_f32 v0, v2, s0
	ds_write_b16 v150, v0 offset:256
	v_cvt_pk_bf16_f32 v0, v3, s0
	ds_write_b16 v150, v0 offset:384
	v_cvt_pk_bf16_f32 v0, v4, s0
	ds_write_b16 v150, v0 offset:512
	v_cvt_pk_bf16_f32 v0, v5, s0
	ds_write_b16 v150, v0 offset:640
	v_cvt_pk_bf16_f32 v0, v6, s0
	ds_write_b16 v150, v0 offset:768
	v_cvt_pk_bf16_f32 v0, v7, s0
	ds_write_b16 v150, v0 offset:896
	v_cvt_pk_bf16_f32 v0, v8, s0
	ds_write_b16 v150, v0 offset:1024
	v_cvt_pk_bf16_f32 v0, v9, s0
	ds_write_b16 v150, v0 offset:1152
	v_cvt_pk_bf16_f32 v0, v10, s0
	ds_write_b16 v150, v0 offset:1280
	v_cvt_pk_bf16_f32 v0, v11, s0
	ds_write_b16 v150, v0 offset:1408
	v_cvt_pk_bf16_f32 v0, v12, s0
	ds_write_b16 v150, v0 offset:1536
	v_cvt_pk_bf16_f32 v0, v13, s0
	ds_write_b16 v150, v0 offset:1664
	v_cvt_pk_bf16_f32 v0, v14, s0
	ds_write_b16 v150, v0 offset:1792
	v_cvt_pk_bf16_f32 v0, v15, s0
	ds_write_b16 v150, v0 offset:1920
	v_cvt_pk_bf16_f32 v0, v16, s0
	ds_write_b16 v150, v0 offset:2048
	v_cvt_pk_bf16_f32 v0, v17, s0
	ds_write_b16 v150, v0 offset:2176
	v_cvt_pk_bf16_f32 v0, v18, s0
	ds_write_b16 v150, v0 offset:2304
	v_cvt_pk_bf16_f32 v0, v19, s0
	ds_write_b16 v150, v0 offset:2432
	v_cvt_pk_bf16_f32 v0, v20, s0
	ds_write_b16 v150, v0 offset:2560
	v_cvt_pk_bf16_f32 v0, v21, s0
	ds_write_b16 v150, v0 offset:2688
	v_cvt_pk_bf16_f32 v0, v22, s0
	ds_write_b16 v150, v0 offset:2816
	v_cvt_pk_bf16_f32 v0, v23, s0
	ds_write_b16 v150, v0 offset:2944
	v_cvt_pk_bf16_f32 v0, v24, s0
	ds_write_b16 v150, v0 offset:3072
	v_cvt_pk_bf16_f32 v0, v25, s0
	ds_write_b16 v150, v0 offset:3200
	v_cvt_pk_bf16_f32 v0, v26, s0
	ds_write_b16 v150, v0 offset:3328
	v_cvt_pk_bf16_f32 v0, v27, s0
	ds_write_b16 v150, v0 offset:3456
	v_cvt_pk_bf16_f32 v0, v28, s0
	ds_write_b16 v150, v0 offset:3584
	v_cvt_pk_bf16_f32 v0, v29, s0
	ds_write_b16 v150, v0 offset:3712
	v_cvt_pk_bf16_f32 v0, v30, s0
	ds_write_b16 v150, v0 offset:3840
	v_cvt_pk_bf16_f32 v0, v31, s0
	ds_write_b16 v150, v0 offset:3968
	v_cvt_pk_bf16_f32 v0, v32, s0
	ds_write_b16 v150, v0 offset:4096
	v_cvt_pk_bf16_f32 v0, v33, s0
	ds_write_b16 v150, v0 offset:4224
	v_cvt_pk_bf16_f32 v0, v34, s0
	ds_write_b16 v150, v0 offset:4352
	v_cvt_pk_bf16_f32 v0, v35, s0
	ds_write_b16 v150, v0 offset:4480
	v_cvt_pk_bf16_f32 v0, v36, s0
	ds_write_b16 v150, v0 offset:4608
	v_cvt_pk_bf16_f32 v0, v37, s0
	ds_write_b16 v150, v0 offset:4736
	v_cvt_pk_bf16_f32 v0, v38, s0
	ds_write_b16 v150, v0 offset:4864
	v_cvt_pk_bf16_f32 v0, v39, s0
	ds_write_b16 v150, v0 offset:4992
	v_cvt_pk_bf16_f32 v0, v40, s0
	ds_write_b16 v150, v0 offset:5120
	v_cvt_pk_bf16_f32 v0, v41, s0
	ds_write_b16 v150, v0 offset:5248
	v_cvt_pk_bf16_f32 v0, v42, s0
	ds_write_b16 v150, v0 offset:5376
	v_cvt_pk_bf16_f32 v0, v43, s0
	ds_write_b16 v150, v0 offset:5504
	v_cvt_pk_bf16_f32 v0, v44, s0
	ds_write_b16 v150, v0 offset:5632
	v_cvt_pk_bf16_f32 v0, v45, s0
	ds_write_b16 v150, v0 offset:5760
	v_cvt_pk_bf16_f32 v0, v46, s0
	ds_write_b16 v150, v0 offset:5888
	v_cvt_pk_bf16_f32 v0, v47, s0
	ds_write_b16 v150, v0 offset:6016
	v_cvt_pk_bf16_f32 v0, v48, s0
	ds_write_b16 v150, v0 offset:6144
	v_cvt_pk_bf16_f32 v0, v49, s0
	ds_write_b16 v150, v0 offset:6272
	v_cvt_pk_bf16_f32 v0, v50, s0
	ds_write_b16 v150, v0 offset:6400
	v_cvt_pk_bf16_f32 v0, v51, s0
	ds_write_b16 v150, v0 offset:6528
	v_cvt_pk_bf16_f32 v0, v52, s0
	ds_write_b16 v150, v0 offset:6656
	v_cvt_pk_bf16_f32 v0, v53, s0
	ds_write_b16 v150, v0 offset:6784
	v_cvt_pk_bf16_f32 v0, v54, s0
	ds_write_b16 v150, v0 offset:6912
	v_cvt_pk_bf16_f32 v0, v55, s0
	ds_write_b16 v150, v0 offset:7040
	v_cvt_pk_bf16_f32 v0, v56, s0
	ds_write_b16 v150, v0 offset:7168
	v_cvt_pk_bf16_f32 v0, v57, s0
	ds_write_b16 v150, v0 offset:7296
	v_cvt_pk_bf16_f32 v0, v58, s0
	ds_write_b16 v150, v0 offset:7424
	v_cvt_pk_bf16_f32 v0, v59, s0
	ds_write_b16 v150, v0 offset:7552
	v_cvt_pk_bf16_f32 v0, v60, s0
	ds_write_b16 v150, v0 offset:7680
	v_cvt_pk_bf16_f32 v0, v61, s0
	ds_write_b16 v150, v0 offset:7808
	v_cvt_pk_bf16_f32 v0, v62, s0
	ds_write_b16 v150, v0 offset:7936
	v_cvt_pk_bf16_f32 v0, v63, s0
	ds_write_b16 v150, v0 offset:8064
	v_lshl_add_u64 v[0:1], v[126:127], 0, s[0:1]
